# GEMM K-loops: B-fragment ds_reads use one loop-invariant base VGPR + immediate offsets (removes all non-MFMA VALU from the K-loops)
# baseline (speedup 1.0000x reference)
; #define PG8_STAGE(bufoff, gbase, voff) do { _Pragma("unroll") for (int _i = 0; _i < 2; ++_i) \
;         __builtin_amdgcn_global_load_lds((const unsigned*)((const char*)(gbase) + (voff)[_i]), (LAS unsigned*)(lds + (bufoff) + ldsw + _i * 8192), 16, 0, 0); } while (0)
; #define PG8_LDA(dst, b, h) do { _Pragma("unroll") for (int m = 0; m < 4; ++m) _Pragma("unroll") for (int k = 0; k < 2; ++k) dst[m][k] = *(const LAS bf16x8*)(lds + PG8_SA(b, h) + aoff + m * 2048 + k * 1024); } while (0)
; #define PG8_LDB(dst, b, h) do { _Pragma("unroll") for (int n = 0; n < 2; ++n) _Pragma("unroll") for (int k = 0; k < 2; ++k) dst[n][k] = *(const LAS bf16x8*)(lds + PG8_SB(b, h) + boff + n * 2048 + k * 1024); } while (0)
; #define PG8_MMA(ai, bj, At, Bt) do { __builtin_amdgcn_s_setprio(1); _Pragma("unroll") for (int m = 0; m < 4; ++m) _Pragma("unroll") for (int n = 0; n < 2; ++n) _Pragma("unroll") for (int k = 0; k < 2; ++k) \
;         acc[ai][bj][m][n] = __builtin_amdgcn_mfma_f32_16x16x32_bf16(Bt[n][k], At[m][k], acc[ai][bj][m][n], 0, 0, 0); __builtin_amdgcn_s_setprio(0); } while (0)
; #define PG8_WAIT_L(n) asm volatile("s_waitcnt lgkmcnt(" #n ")" ::: "memory")
; #define PG8_BAR __builtin_amdgcn_s_barrier()
; #define PG8_SCHED __builtin_amdgcn_sched_barrier(0)
; template <class Epi>
; __device__ __forceinline__ void gemm_phase(LAS unsigned char* lds, const Gemm g, const StaticOrder& S, const Epi& E) {
;     ...
;         for (int t = 0; t < nt; t += 2) {
;             const bool last = (t == nt - 2);
;             const char* a1 = cA + (size_t)(t + 1) * kstep;
;             const char* a2 = last ? nA : cA + (size_t)(t + 2) * kstep; const char* b2 = last ? nB : cB + (size_t)(t + 2) * kstep;
;             const char* a3 = a2 + kstep; const char* b3 = b2 + kstep;
;             PG8_LDB(B0, 0, 0); PG8_SCHED; PG8_LDA(At, 0, 0); PG8_STAGE(PG8_SA(1, 1), a1 + hstep, voffA);
;             PG8_WAIT_L(8); PG8_BAR; PG8_WAIT_L(0); PG8_MMA(0, 0, At, B0); PG8_BAR; PG8_SCHED;
;     ...
; #pragma unroll
;         for (int a = 0; a < 2; ++a)
; #pragma unroll
;             for (int b = 0; b < 2; ++b)
; #pragma unroll
;                 for (int m = 0; m < 4; ++m)
; #pragma unroll
;                     for (int n = 0; n < 2; ++n) acc[a][b][m][n] = (f32x4){0.f, 0.f, 0.f, 0.f};
;         cur = nxt; cA = nA; cB = nB; ++ui;
.LBB0_63:
	v_mov_b64_e32 v[2:3], s[42:43]
	s_ashr_i32 s49, s48, 31
	v_cmp_lt_i64_e32 vcc, s[50:51], v[2:3]
	s_lshl_b64 s[50:51], s[48:49], 20
	v_readlane_b32 s52, v254, 8
	v_readlane_b32 s53, v254, 9
	s_add_u32 s50, s52, s50
	s_addc_u32 s51, s53, s51
	s_and_b64 s[52:53], vcc, exec
	s_cselect_b32 s49, s51, s57
	s_cselect_b32 s81, s50, s56
	s_ashr_i32 s47, s46, 31
	s_lshl_b64 s[52:53], s[46:47], 20
	s_add_u32 s52, s65, s52
	s_addc_u32 s53, s68, s53
	s_and_b64 s[60:61], vcc, exec
	s_cselect_b32 s47, s53, s59
	s_cselect_b32 s82, s52, s58
	s_add_u32 s56, s56, 0x80080
	s_addc_u32 s57, s57, 0
	s_add_u32 s83, s58, 0x100
	v_mov_b32_e32 v2, 0
	s_addc_u32 s84, s59, 0
	s_mov_b32 s85, -2
	v_mov_b32_e32 v3, v2
	v_mov_b32_e32 v4, v2
	v_mov_b32_e32 v5, v2
	v_mov_b32_e32 v6, v2
	v_mov_b32_e32 v7, v2
	v_mov_b32_e32 v8, v2
	v_mov_b32_e32 v9, v2
	v_mov_b32_e32 v10, v2
	v_mov_b32_e32 v11, v2
	v_mov_b32_e32 v12, v2
	v_mov_b32_e32 v13, v2
	v_mov_b32_e32 v18, v2
	v_mov_b32_e32 v19, v2
	v_mov_b32_e32 v20, v2
	v_mov_b32_e32 v21, v2
	s_waitcnt vmcnt(0)
	v_mov_b32_e32 v26, v2
	v_mov_b32_e32 v27, v2
	v_mov_b32_e32 v28, v2
	v_mov_b32_e32 v29, v2
	v_mov_b32_e32 v34, v2
	v_mov_b32_e32 v35, v2
	v_mov_b32_e32 v36, v2
	v_mov_b32_e32 v37, v2
	v_mov_b32_e32 v42, v2
	v_mov_b32_e32 v43, v2
	v_mov_b32_e32 v44, v2
	v_mov_b32_e32 v45, v2
	v_mov_b32_e32 v50, v2
	v_mov_b32_e32 v51, v2
	v_mov_b32_e32 v52, v2
	v_mov_b32_e32 v53, v2
	v_mov_b32_e32 v14, v2
	v_mov_b32_e32 v15, v2
	v_mov_b32_e32 v16, v2
	v_mov_b32_e32 v17, v2
	v_mov_b32_e32 v22, v2
	v_mov_b32_e32 v23, v2
	v_mov_b32_e32 v24, v2
	v_mov_b32_e32 v25, v2
	v_mov_b32_e32 v30, v2
	v_mov_b32_e32 v31, v2
	v_mov_b32_e32 v32, v2
	v_mov_b32_e32 v33, v2
	v_mov_b32_e32 v38, v2
	v_mov_b32_e32 v39, v2
	v_mov_b32_e32 v40, v2
	v_mov_b32_e32 v41, v2
	v_mov_b32_e32 v46, v2
	v_mov_b32_e32 v47, v2
	v_mov_b32_e32 v48, v2
	v_mov_b32_e32 v49, v2
	v_mov_b32_e32 v54, v2
	v_mov_b32_e32 v55, v2
	v_mov_b32_e32 v56, v2
	v_mov_b32_e32 v57, v2
	v_mov_b32_e32 v58, v2
	v_mov_b32_e32 v59, v2
	v_mov_b32_e32 v60, v2
	v_mov_b32_e32 v61, v2
	v_mov_b32_e32 v62, v2
	v_mov_b32_e32 v63, v2
	v_mov_b32_e32 v64, v2
	v_mov_b32_e32 v65, v2
	v_mov_b32_e32 v66, v2
	v_mov_b32_e32 v67, v2
	v_mov_b32_e32 v68, v2
	v_mov_b32_e32 v69, v2
	v_mov_b32_e32 v70, v2
	v_mov_b32_e32 v71, v2
	v_mov_b32_e32 v72, v2
	v_mov_b32_e32 v73, v2
	v_mov_b32_e32 v82, v2
	v_mov_b32_e32 v83, v2
	v_mov_b32_e32 v84, v2
	v_mov_b32_e32 v85, v2
	v_mov_b32_e32 v86, v2
	v_mov_b32_e32 v87, v2
	v_mov_b32_e32 v88, v2
	v_mov_b32_e32 v89, v2
	v_mov_b32_e32 v98, v2
	v_mov_b32_e32 v99, v2
	v_mov_b32_e32 v100, v2
	v_mov_b32_e32 v101, v2
	v_mov_b32_e32 v102, v2
	v_mov_b32_e32 v103, v2
	v_mov_b32_e32 v104, v2
	v_mov_b32_e32 v105, v2
	v_mov_b32_e32 v114, v2
	v_mov_b32_e32 v115, v2
	v_mov_b32_e32 v116, v2
	v_mov_b32_e32 v117, v2
	v_mov_b32_e32 v118, v2
	v_mov_b32_e32 v119, v2
	v_mov_b32_e32 v120, v2
	v_mov_b32_e32 v121, v2
	v_mov_b32_e32 v74, v2
	v_mov_b32_e32 v75, v2
	v_mov_b32_e32 v76, v2
	v_mov_b32_e32 v77, v2
	v_mov_b32_e32 v78, v2
	v_mov_b32_e32 v79, v2
	v_mov_b32_e32 v80, v2
	v_mov_b32_e32 v81, v2
	v_mov_b32_e32 v90, v2
	v_mov_b32_e32 v91, v2
	v_mov_b32_e32 v92, v2
	v_mov_b32_e32 v93, v2
	v_mov_b32_e32 v94, v2
	v_mov_b32_e32 v95, v2
	v_mov_b32_e32 v96, v2
	v_mov_b32_e32 v97, v2
	v_mov_b32_e32 v106, v2
	v_mov_b32_e32 v107, v2
	v_mov_b32_e32 v108, v2
	v_mov_b32_e32 v109, v2
	v_mov_b32_e32 v110, v2
	v_mov_b32_e32 v111, v2
	v_mov_b32_e32 v112, v2
	v_mov_b32_e32 v113, v2
	v_mov_b32_e32 v122, v2
	v_mov_b32_e32 v123, v2
	v_mov_b32_e32 v124, v2
	v_mov_b32_e32 v125, v2
	v_mov_b32_e32 v126, v2
	v_mov_b32_e32 v127, v2
	v_mov_b32_e32 v128, v2
	v_mov_b32_e32 v129, v2
	v_add_u32_e32 v202, 0x10000, v143
	ds_read_b128 v[154:157], v202
	ds_read_b128 v[158:161], v202 offset:1024
	ds_read_b128 v[162:165], v202 offset:2048
	ds_read_b128 v[166:169], v202 offset:3072
.LBB0_64:
	s_add_u32 s58, s56, 0xfff80080
	s_addc_u32 s59, s57, -1
	s_add_i32 s86, 0, 0x10000
	s_cmp_eq_u32 s85, 28
	s_cselect_b32 s61, s49, s59
	s_cselect_b32 s60, s81, s58
	s_cselect_b32 s59, s47, s84
	s_cselect_b32 s58, s82, s83
	s_add_i32 m0, s55, 0xc000
	ds_read_b128 v[170:173], v151
	ds_read_b128 v[174:177], v151 offset:1024
	ds_read_b128 v[178:181], v151 offset:2048
	ds_read_b128 v[182:185], v151 offset:3072
	ds_read_b128 v[186:189], v151 offset:4096
	ds_read_b128 v[190:193], v151 offset:5120
	ds_read_b128 v[194:197], v151 offset:6144
	ds_read_b128 v[198:201], v151 offset:7168
	global_load_lds_dwordx4 v136, s[56:57]
	s_add_i32 m0, s55, 0xe000
	s_nop 0
	global_load_lds_dwordx4 v138, s[56:57]
	s_waitcnt lgkmcnt(8)
	s_barrier
	s_waitcnt lgkmcnt(0)
	s_setprio 1
	v_mfma_f32_16x16x32_bf16 v[126:129], v[154:157], v[170:173], v[126:129]
	v_mfma_f32_16x16x32_bf16 v[122:125], v[162:165], v[170:173], v[122:125]
	v_mfma_f32_16x16x32_bf16 v[110:113], v[154:157], v[178:181], v[110:113]
	v_mfma_f32_16x16x32_bf16 v[106:109], v[162:165], v[178:181], v[106:109]
	v_mfma_f32_16x16x32_bf16 v[94:97], v[154:157], v[186:189], v[94:97]
	v_mfma_f32_16x16x32_bf16 v[90:93], v[162:165], v[186:189], v[90:93]
	v_mfma_f32_16x16x32_bf16 v[78:81], v[154:157], v[194:197], v[78:81]
	v_mfma_f32_16x16x32_bf16 v[74:77], v[162:165], v[194:197], v[74:77]
	v_mfma_f32_16x16x32_bf16 v[126:129], v[158:161], v[174:177], v[126:129]
	v_mfma_f32_16x16x32_bf16 v[122:125], v[166:169], v[174:177], v[122:125]
	v_mfma_f32_16x16x32_bf16 v[110:113], v[158:161], v[182:185], v[110:113]
	v_mfma_f32_16x16x32_bf16 v[106:109], v[166:169], v[182:185], v[106:109]
	v_mfma_f32_16x16x32_bf16 v[94:97], v[158:161], v[190:193], v[94:97]
	v_mfma_f32_16x16x32_bf16 v[90:93], v[166:169], v[190:193], v[90:93]
	v_mfma_f32_16x16x32_bf16 v[78:81], v[158:161], v[198:201], v[78:81]
	v_mfma_f32_16x16x32_bf16 v[74:77], v[166:169], v[198:201], v[74:77]
	s_setprio 0
	s_barrier
; #define PG8_STAGE(bufoff, gbase, voff) do { _Pragma("unroll") for (int _i = 0; _i < 2; ++_i) \
;         __builtin_amdgcn_global_load_lds((const unsigned*)((const char*)(gbase) + (voff)[_i]), (LAS unsigned*)(lds + (bufoff) + ldsw + _i * 8192), 16, 0, 0); } while (0)
; #define PG8_LDA(dst, b, h) do { _Pragma("unroll") for (int m = 0; m < 4; ++m) _Pragma("unroll") for (int k = 0; k < 2; ++k) dst[m][k] = *(const LAS bf16x8*)(lds + PG8_SA(b, h) + aoff + m * 2048 + k * 1024); } while (0)
; #define PG8_LDB(dst, b, h) do { _Pragma("unroll") for (int n = 0; n < 2; ++n) _Pragma("unroll") for (int k = 0; k < 2; ++k) dst[n][k] = *(const LAS bf16x8*)(lds + PG8_SB(b, h) + boff + n * 2048 + k * 1024); } while (0)
; #define PG8_MMA(ai, bj, At, Bt) do { __builtin_amdgcn_s_setprio(1); _Pragma("unroll") for (int m = 0; m < 4; ++m) _Pragma("unroll") for (int n = 0; n < 2; ++n) _Pragma("unroll") for (int k = 0; k < 2; ++k) \
;         acc[ai][bj][m][n] = __builtin_amdgcn_mfma_f32_16x16x32_bf16(Bt[n][k], At[m][k], acc[ai][bj][m][n], 0, 0, 0); __builtin_amdgcn_s_setprio(0); } while (0)
; #define PG8_WAIT_V(n) asm volatile("s_waitcnt vmcnt(" #n ")" ::: "memory")
; #define PG8_WAIT_L(n) asm volatile("s_waitcnt lgkmcnt(" #n ")" ::: "memory")
; #define PG8_BAR __builtin_amdgcn_s_barrier()
; #define PG8_SCHED __builtin_amdgcn_sched_barrier(0)
; template <class Epi>
; __device__ __forceinline__ void gemm_phase(LAS unsigned char* lds, const Gemm g, const StaticOrder& S, const Epi& E) {
;     ...
;             PG8_LDB(B0, 0, 0); PG8_SCHED; PG8_LDA(At, 0, 0); PG8_STAGE(PG8_SA(1, 1), a1 + hstep, voffA);
;             PG8_WAIT_L(8); PG8_BAR; PG8_WAIT_L(0); PG8_MMA(0, 0, At, B0); PG8_BAR; PG8_SCHED;
;             PG8_LDB(B1, 0, 1); PG8_STAGE(PG8_SB(0, 0), b2, voffB);
;             PG8_BAR; PG8_WAIT_L(0); PG8_MMA(0, 1, At, B1); PG8_BAR;
;             PG8_LDA(At, 0, 1); PG8_STAGE(PG8_SA(0, 0), a2, voffA);
;             PG8_BAR; PG8_WAIT_L(0); PG8_MMA(1, 0, At, B0); PG8_BAR; PG8_SCHED;
;             PG8_STAGE(PG8_SB(0, 1), b2 + hstep, voffB);
;             PG8_WAIT_V(6); PG8_BAR; PG8_MMA(1, 1, At, B1); PG8_BAR;
;             PG8_LDB(B0, 1, 0); PG8_SCHED; PG8_LDA(At, 1, 0); PG8_STAGE(PG8_SA(0, 1), a2 + hstep, voffA);
	s_add_i32 s88, 0, 0x14000
	s_add_i32 s86, s86, s69
	s_add_u32 s98, s58, s22
	s_addc_u32 s99, s59, s23
	s_mov_b32 m0, s86
	ds_read_b128 v[208:211], v202 offset:16384
	ds_read_b128 v[212:215], v202 offset:17408
	ds_read_b128 v[216:219], v202 offset:18432
	ds_read_b128 v[220:223], v202 offset:19456
	global_load_lds_dwordx4 v0, s[58:59]
	s_add_i32 m0, s86, 0x2000
	s_nop 0
	global_load_lds_dwordx4 v130, s[58:59]
	s_barrier
	s_waitcnt lgkmcnt(0)
	s_setprio 1
	v_mfma_f32_16x16x32_bf16 v[118:121], v[208:211], v[170:173], v[118:121]
	v_mfma_f32_16x16x32_bf16 v[114:117], v[216:219], v[170:173], v[114:117]
	v_mfma_f32_16x16x32_bf16 v[102:105], v[208:211], v[178:181], v[102:105]
	v_mfma_f32_16x16x32_bf16 v[98:101], v[216:219], v[178:181], v[98:101]
	v_mfma_f32_16x16x32_bf16 v[86:89], v[208:211], v[186:189], v[86:89]
	v_mfma_f32_16x16x32_bf16 v[82:85], v[216:219], v[186:189], v[82:85]
	v_mfma_f32_16x16x32_bf16 v[70:73], v[208:211], v[194:197], v[70:73]
	v_mfma_f32_16x16x32_bf16 v[66:69], v[216:219], v[194:197], v[66:69]
	v_mfma_f32_16x16x32_bf16 v[118:121], v[212:215], v[174:177], v[118:121]
	v_mfma_f32_16x16x32_bf16 v[114:117], v[220:223], v[174:177], v[114:117]
	v_mfma_f32_16x16x32_bf16 v[102:105], v[212:215], v[182:185], v[102:105]
	v_mfma_f32_16x16x32_bf16 v[98:101], v[220:223], v[182:185], v[98:101]
	v_mfma_f32_16x16x32_bf16 v[86:89], v[212:215], v[190:193], v[86:89]
	v_mfma_f32_16x16x32_bf16 v[82:85], v[220:223], v[190:193], v[82:85]
	v_mfma_f32_16x16x32_bf16 v[70:73], v[212:215], v[198:201], v[70:73]
	v_mfma_f32_16x16x32_bf16 v[66:69], v[220:223], v[198:201], v[66:69]
	s_setprio 0
	s_mov_b32 m0, s55
	s_add_u32 s100, s60, s22
	s_addc_u32 s101, s61, s23
	s_barrier
	ds_read_b128 v[170:173], v151 offset:16384
	ds_read_b128 v[174:177], v151 offset:17408
	ds_read_b128 v[178:181], v151 offset:18432
	ds_read_b128 v[182:185], v151 offset:19456
	ds_read_b128 v[186:189], v151 offset:20480
	ds_read_b128 v[190:193], v151 offset:21504
	ds_read_b128 v[194:197], v151 offset:22528
	ds_read_b128 v[198:201], v151 offset:23552
	global_load_lds_dwordx4 v134, s[60:61]
	s_mov_b32 m0, s72
	s_nop 0
	global_load_lds_dwordx4 v132, s[60:61]
	s_waitcnt vmcnt(10)
	s_barrier
	s_waitcnt lgkmcnt(0)
	s_setprio 1
	v_mfma_f32_16x16x32_bf16 v[62:65], v[154:157], v[170:173], v[62:65]
	v_mfma_f32_16x16x32_bf16 v[58:61], v[162:165], v[170:173], v[58:61]
	v_mfma_f32_16x16x32_bf16 v[54:57], v[154:157], v[178:181], v[54:57]
	v_mfma_f32_16x16x32_bf16 v[46:49], v[162:165], v[178:181], v[46:49]
	v_mfma_f32_16x16x32_bf16 v[38:41], v[154:157], v[186:189], v[38:41]
	v_mfma_f32_16x16x32_bf16 v[30:33], v[162:165], v[186:189], v[30:33]
	v_mfma_f32_16x16x32_bf16 v[22:25], v[154:157], v[194:197], v[22:25]
	v_mfma_f32_16x16x32_bf16 v[14:17], v[162:165], v[194:197], v[14:17]
	v_mfma_f32_16x16x32_bf16 v[62:65], v[158:161], v[174:177], v[62:65]
	v_mfma_f32_16x16x32_bf16 v[58:61], v[166:169], v[174:177], v[58:61]
	v_mfma_f32_16x16x32_bf16 v[54:57], v[158:161], v[182:185], v[54:57]
	v_mfma_f32_16x16x32_bf16 v[46:49], v[166:169], v[182:185], v[46:49]
	v_mfma_f32_16x16x32_bf16 v[38:41], v[158:161], v[190:193], v[38:41]
	v_mfma_f32_16x16x32_bf16 v[30:33], v[166:169], v[190:193], v[30:33]
	v_mfma_f32_16x16x32_bf16 v[22:25], v[158:161], v[198:201], v[22:25]
	v_mfma_f32_16x16x32_bf16 v[14:17], v[166:169], v[198:201], v[14:17]
	s_setprio 0
	s_barrier
	ds_read_b128 v[154:157], v202 offset:32768
	ds_read_b128 v[158:161], v202 offset:33792
	ds_read_b128 v[162:165], v202 offset:34816
	ds_read_b128 v[166:169], v202 offset:35840
	s_add_u32 s86, s58, 0x80000
	s_addc_u32 s87, s59, 0
	s_add_i32 s88, s88, s69
	s_mov_b32 m0, s88
	s_nop 0
	global_load_lds_dwordx4 v0, s[86:87]
	s_add_i32 m0, s88, 0x2000
	s_nop 0
	global_load_lds_dwordx4 v130, s[86:87]
	s_waitcnt vmcnt(6)
	s_barrier
	s_setprio 1
	v_mfma_f32_16x16x32_bf16 v[50:53], v[208:211], v[170:173], v[50:53]
	v_mfma_f32_16x16x32_bf16 v[42:45], v[216:219], v[170:173], v[42:45]
	v_mfma_f32_16x16x32_bf16 v[34:37], v[208:211], v[178:181], v[34:37]
	v_mfma_f32_16x16x32_bf16 v[26:29], v[216:219], v[178:181], v[26:29]
	v_mfma_f32_16x16x32_bf16 v[18:21], v[208:211], v[186:189], v[18:21]
	v_mfma_f32_16x16x32_bf16 v[10:13], v[216:219], v[186:189], v[10:13]
	v_mfma_f32_16x16x32_bf16 v[6:9], v[208:211], v[194:197], v[6:9]
	v_mfma_f32_16x16x32_bf16 v[2:5], v[216:219], v[194:197], v[2:5]
	v_mfma_f32_16x16x32_bf16 v[50:53], v[212:215], v[174:177], v[50:53]
	v_mfma_f32_16x16x32_bf16 v[42:45], v[220:223], v[174:177], v[42:45]
	v_mfma_f32_16x16x32_bf16 v[34:37], v[212:215], v[182:185], v[34:37]
	v_mfma_f32_16x16x32_bf16 v[26:29], v[220:223], v[182:185], v[26:29]
	v_mfma_f32_16x16x32_bf16 v[18:21], v[212:215], v[190:193], v[18:21]
	v_mfma_f32_16x16x32_bf16 v[10:13], v[220:223], v[190:193], v[10:13]
	v_mfma_f32_16x16x32_bf16 v[6:9], v[212:215], v[198:201], v[6:9]
	v_mfma_f32_16x16x32_bf16 v[2:5], v[220:223], v[198:201], v[2:5]
	s_setprio 0
	s_add_i32 s86, 0, 0x18000
	s_barrier
	s_add_u32 s60, s60, 0x80000
	s_addc_u32 s61, s61, 0
	s_mov_b32 m0, s73
	ds_read_b128 v[170:173], v151 offset:32768
	ds_read_b128 v[174:177], v151 offset:33792
	ds_read_b128 v[178:181], v151 offset:34816
	ds_read_b128 v[182:185], v151 offset:35840
	ds_read_b128 v[186:189], v151 offset:36864
	ds_read_b128 v[190:193], v151 offset:37888
	ds_read_b128 v[194:197], v151 offset:38912
	ds_read_b128 v[198:201], v151 offset:39936
	global_load_lds_dwordx4 v134, s[60:61]
	s_mov_b32 m0, s74
	s_nop 0
	global_load_lds_dwordx4 v132, s[60:61]
	s_waitcnt lgkmcnt(8)
	s_barrier
; #define PG8_STAGE(bufoff, gbase, voff) do { _Pragma("unroll") for (int _i = 0; _i < 2; ++_i) \
;         __builtin_amdgcn_global_load_lds((const unsigned*)((const char*)(gbase) + (voff)[_i]), (LAS unsigned*)(lds + (bufoff) + ldsw + _i * 8192), 16, 0, 0); } while (0)
; #define PG8_LDA(dst, b, h) do { _Pragma("unroll") for (int m = 0; m < 4; ++m) _Pragma("unroll") for (int k = 0; k < 2; ++k) dst[m][k] = *(const LAS bf16x8*)(lds + PG8_SA(b, h) + aoff + m * 2048 + k * 1024); } while (0)
; #define PG8_LDB(dst, b, h) do { _Pragma("unroll") for (int n = 0; n < 2; ++n) _Pragma("unroll") for (int k = 0; k < 2; ++k) dst[n][k] = *(const LAS bf16x8*)(lds + PG8_SB(b, h) + boff + n * 2048 + k * 1024); } while (0)
; #define PG8_MMA(ai, bj, At, Bt) do { __builtin_amdgcn_s_setprio(1); _Pragma("unroll") for (int m = 0; m < 4; ++m) _Pragma("unroll") for (int n = 0; n < 2; ++n) _Pragma("unroll") for (int k = 0; k < 2; ++k) \
;         acc[ai][bj][m][n] = __builtin_amdgcn_mfma_f32_16x16x32_bf16(Bt[n][k], At[m][k], acc[ai][bj][m][n], 0, 0, 0); __builtin_amdgcn_s_setprio(0); } while (0)
; #define PG8_WAIT_V(n) asm volatile("s_waitcnt vmcnt(" #n ")" ::: "memory")
; #define PG8_WAIT_L(n) asm volatile("s_waitcnt lgkmcnt(" #n ")" ::: "memory")
; #define PG8_BAR __builtin_amdgcn_s_barrier()
; #define PG8_SCHED __builtin_amdgcn_sched_barrier(0)
; template <class Epi>
; __device__ __forceinline__ void gemm_phase(LAS unsigned char* lds, const Gemm g, const StaticOrder& S, const Epi& E) {
;     ...
;             PG8_LDB(B0, 1, 0); PG8_SCHED; PG8_LDA(At, 1, 0); PG8_STAGE(PG8_SA(0, 1), a2 + hstep, voffA);
;             PG8_WAIT_L(8); PG8_BAR; PG8_WAIT_L(0); PG8_MMA(0, 0, At, B0); PG8_BAR; PG8_SCHED;
;             PG8_LDB(B1, 1, 1); PG8_STAGE(PG8_SB(1, 0), b3, voffB);
;             PG8_BAR; PG8_WAIT_L(0); PG8_MMA(0, 1, At, B1); PG8_BAR;
;             PG8_LDA(At, 1, 1); PG8_STAGE(PG8_SA(1, 0), a3, voffA);
;             PG8_BAR; PG8_WAIT_L(0); PG8_MMA(1, 0, At, B0); PG8_BAR; PG8_SCHED;
;             PG8_STAGE(PG8_SB(1, 1), b3 + hstep, voffB);
;             PG8_WAIT_V(6); PG8_BAR; PG8_MMA(1, 1, At, B1); PG8_BAR;
	s_waitcnt lgkmcnt(0)
	s_setprio 1
	v_mfma_f32_16x16x32_bf16 v[126:129], v[154:157], v[170:173], v[126:129]
	v_mfma_f32_16x16x32_bf16 v[122:125], v[162:165], v[170:173], v[122:125]
	v_mfma_f32_16x16x32_bf16 v[110:113], v[154:157], v[178:181], v[110:113]
	v_mfma_f32_16x16x32_bf16 v[106:109], v[162:165], v[178:181], v[106:109]
	v_mfma_f32_16x16x32_bf16 v[94:97], v[154:157], v[186:189], v[94:97]
	v_mfma_f32_16x16x32_bf16 v[90:93], v[162:165], v[186:189], v[90:93]
	v_mfma_f32_16x16x32_bf16 v[78:81], v[154:157], v[194:197], v[78:81]
	v_mfma_f32_16x16x32_bf16 v[74:77], v[162:165], v[194:197], v[74:77]
	v_mfma_f32_16x16x32_bf16 v[126:129], v[158:161], v[174:177], v[126:129]
	v_mfma_f32_16x16x32_bf16 v[122:125], v[166:169], v[174:177], v[122:125]
	v_mfma_f32_16x16x32_bf16 v[110:113], v[158:161], v[182:185], v[110:113]
	v_mfma_f32_16x16x32_bf16 v[106:109], v[166:169], v[182:185], v[106:109]
	v_mfma_f32_16x16x32_bf16 v[94:97], v[158:161], v[190:193], v[94:97]
	v_mfma_f32_16x16x32_bf16 v[90:93], v[166:169], v[190:193], v[90:93]
	v_mfma_f32_16x16x32_bf16 v[78:81], v[158:161], v[198:201], v[78:81]
	v_mfma_f32_16x16x32_bf16 v[74:77], v[166:169], v[198:201], v[74:77]
	s_setprio 0
	s_barrier
	s_add_i32 s60, 0, 0x1c000
	s_add_i32 s61, s86, s69
	s_mov_b32 m0, s61
	ds_read_b128 v[208:211], v202 offset:49152
	ds_read_b128 v[212:215], v202 offset:50176
	ds_read_b128 v[216:219], v202 offset:51200
	ds_read_b128 v[220:223], v202 offset:52224
	global_load_lds_dwordx4 v0, s[98:99]
	s_add_i32 m0, s61, 0x2000
	s_nop 0
	global_load_lds_dwordx4 v130, s[98:99]
	s_barrier
	s_waitcnt lgkmcnt(0)
	s_setprio 1
	v_mfma_f32_16x16x32_bf16 v[118:121], v[208:211], v[170:173], v[118:121]
	v_mfma_f32_16x16x32_bf16 v[114:117], v[216:219], v[170:173], v[114:117]
	v_mfma_f32_16x16x32_bf16 v[102:105], v[208:211], v[178:181], v[102:105]
	v_mfma_f32_16x16x32_bf16 v[98:101], v[216:219], v[178:181], v[98:101]
	v_mfma_f32_16x16x32_bf16 v[86:89], v[208:211], v[186:189], v[86:89]
	v_mfma_f32_16x16x32_bf16 v[82:85], v[216:219], v[186:189], v[82:85]
	v_mfma_f32_16x16x32_bf16 v[70:73], v[208:211], v[194:197], v[70:73]
	v_mfma_f32_16x16x32_bf16 v[66:69], v[216:219], v[194:197], v[66:69]
	v_mfma_f32_16x16x32_bf16 v[118:121], v[212:215], v[174:177], v[118:121]
	v_mfma_f32_16x16x32_bf16 v[114:117], v[220:223], v[174:177], v[114:117]
	v_mfma_f32_16x16x32_bf16 v[102:105], v[212:215], v[182:185], v[102:105]
	v_mfma_f32_16x16x32_bf16 v[98:101], v[220:223], v[182:185], v[98:101]
	v_mfma_f32_16x16x32_bf16 v[86:89], v[212:215], v[190:193], v[86:89]
	v_mfma_f32_16x16x32_bf16 v[82:85], v[220:223], v[190:193], v[82:85]
	v_mfma_f32_16x16x32_bf16 v[70:73], v[212:215], v[198:201], v[70:73]
	v_mfma_f32_16x16x32_bf16 v[66:69], v[220:223], v[198:201], v[66:69]
	s_setprio 0
	s_mov_b32 m0, s76
	s_barrier
	ds_read_b128 v[170:173], v151 offset:49152
	ds_read_b128 v[174:177], v151 offset:50176
	ds_read_b128 v[178:181], v151 offset:51200
	ds_read_b128 v[182:185], v151 offset:52224
	ds_read_b128 v[186:189], v151 offset:53248
	ds_read_b128 v[190:193], v151 offset:54272
	ds_read_b128 v[194:197], v151 offset:55296
	ds_read_b128 v[198:201], v151 offset:56320
	global_load_lds_dwordx4 v134, s[100:101]
	s_mov_b32 m0, s77
	s_nop 0
	global_load_lds_dwordx4 v132, s[100:101]
	s_waitcnt vmcnt(10)
	s_barrier
	s_waitcnt lgkmcnt(0)
	s_setprio 1
	v_mfma_f32_16x16x32_bf16 v[62:65], v[154:157], v[170:173], v[62:65]
	v_mfma_f32_16x16x32_bf16 v[58:61], v[162:165], v[170:173], v[58:61]
	v_mfma_f32_16x16x32_bf16 v[54:57], v[154:157], v[178:181], v[54:57]
	v_mfma_f32_16x16x32_bf16 v[46:49], v[162:165], v[178:181], v[46:49]
	v_mfma_f32_16x16x32_bf16 v[38:41], v[154:157], v[186:189], v[38:41]
	v_mfma_f32_16x16x32_bf16 v[30:33], v[162:165], v[186:189], v[30:33]
	v_mfma_f32_16x16x32_bf16 v[22:25], v[154:157], v[194:197], v[22:25]
	v_mfma_f32_16x16x32_bf16 v[14:17], v[162:165], v[194:197], v[14:17]
	v_mfma_f32_16x16x32_bf16 v[62:65], v[158:161], v[174:177], v[62:65]
	v_mfma_f32_16x16x32_bf16 v[58:61], v[166:169], v[174:177], v[58:61]
	v_mfma_f32_16x16x32_bf16 v[54:57], v[158:161], v[182:185], v[54:57]
	v_mfma_f32_16x16x32_bf16 v[46:49], v[166:169], v[182:185], v[46:49]
	v_mfma_f32_16x16x32_bf16 v[38:41], v[158:161], v[190:193], v[38:41]
	v_mfma_f32_16x16x32_bf16 v[30:33], v[166:169], v[190:193], v[30:33]
	v_mfma_f32_16x16x32_bf16 v[22:25], v[158:161], v[198:201], v[22:25]
	v_mfma_f32_16x16x32_bf16 v[14:17], v[166:169], v[198:201], v[14:17]
	s_setprio 0
	s_barrier
	ds_read_b128 v[154:157], v202
	ds_read_b128 v[158:161], v202 offset:1024
	ds_read_b128 v[162:165], v202 offset:2048
	ds_read_b128 v[166:169], v202 offset:3072
	s_add_u32 s58, s58, 0x80080
	s_addc_u32 s59, s59, 0
	s_add_i32 s60, s60, s69
	s_mov_b32 m0, s60
	s_nop 0
	global_load_lds_dwordx4 v0, s[58:59]
	s_add_i32 m0, s60, 0x2000
	s_nop 0
	global_load_lds_dwordx4 v130, s[58:59]
	s_waitcnt vmcnt(6)
	s_barrier
	s_setprio 1
	v_mfma_f32_16x16x32_bf16 v[50:53], v[208:211], v[170:173], v[50:53]
	v_mfma_f32_16x16x32_bf16 v[42:45], v[216:219], v[170:173], v[42:45]
	v_mfma_f32_16x16x32_bf16 v[34:37], v[208:211], v[178:181], v[34:37]
	v_mfma_f32_16x16x32_bf16 v[26:29], v[216:219], v[178:181], v[26:29]
	v_mfma_f32_16x16x32_bf16 v[18:21], v[208:211], v[186:189], v[18:21]
	v_mfma_f32_16x16x32_bf16 v[10:13], v[216:219], v[186:189], v[10:13]
	v_mfma_f32_16x16x32_bf16 v[6:9], v[208:211], v[194:197], v[6:9]
	v_mfma_f32_16x16x32_bf16 v[2:5], v[216:219], v[194:197], v[2:5]
	v_mfma_f32_16x16x32_bf16 v[50:53], v[212:215], v[174:177], v[50:53]
	v_mfma_f32_16x16x32_bf16 v[42:45], v[220:223], v[174:177], v[42:45]
	v_mfma_f32_16x16x32_bf16 v[34:37], v[212:215], v[182:185], v[34:37]
	v_mfma_f32_16x16x32_bf16 v[26:29], v[220:223], v[182:185], v[26:29]
	v_mfma_f32_16x16x32_bf16 v[18:21], v[212:215], v[190:193], v[18:21]
	v_mfma_f32_16x16x32_bf16 v[10:13], v[220:223], v[190:193], v[10:13]
	v_mfma_f32_16x16x32_bf16 v[6:9], v[212:215], v[198:201], v[6:9]
	v_mfma_f32_16x16x32_bf16 v[2:5], v[220:223], v[198:201], v[2:5]
	s_setprio 0
	s_add_i32 s85, s85, 2
	s_add_u32 s56, s56, 0x100
	s_addc_u32 s57, s57, 0
	s_add_u32 s83, s83, 0x100
	s_addc_u32 s84, s84, 0
	s_cmp_gt_u32 s85, 29
	s_barrier
; __device__ __forceinline__ unsigned pk2(float lo, float hi) { f32x2 v = {lo, hi}; bf16x2_t b = __builtin_convertvector(v, bf16x2_t); return __builtin_bit_cast(unsigned, b); }
;     __device__ __forceinline__ void operator()(const AccT& acc, const Unit& u, int wr, int wc, int fr, int fq) const {
;         const int row0 = u.pm * BM + wr * 64 + fr, col0 = u.pn * BM + wc * 32 + 8 * fq;
;         float rsv[8];
;         if (ss) {
;             const int ln = (fq << 4) | fr;
;             float sa = ss[u.pm * BM + wr * 64 + ln], sb = ss[u.pm * BM + HALF + wr * 64 + ln];
;             sa = __builtin_amdgcn_rsqf(sa * (1.0f / DM) + EPS); sb = __builtin_amdgcn_rsqf(sb * (1.0f / DM) + EPS);
; #pragma unroll
;             for (int m = 0; m < 4; ++m) { rsv[m] = __shfl(sa, 16 * m + fr); rsv[4 + m] = __shfl(sb, 16 * m + fr); }
;         } else {
; #pragma unroll
;             for (int i = 0; i < 8; ++i) rsv[i] = 1.0f;
;         }
; #pragma unroll
;         for (int ai = 0; ai < 2; ++ai)
; #pragma unroll
;             for (int m = 0; m < 4; ++m) {
;                 const int row = row0 + ai * HALF + m * 16;
;                 const float rs = rsv[ai * 4 + m];
; #pragma unroll
;                 for (int bj = 0; bj < 2; ++bj) {
;                     const f32x4 v0 = acc[ai][bj][m][0] * rs, v1 = acc[ai][bj][m][1] * rs;
;                     u32x4 w; w.x = pk2(v0[0], v0[1]); w.y = pk2(v0[2], v0[3]); w.z = pk2(v1[0], v1[1]); w.w = pk2(v1[2], v1[3]);
;                     *(u32x4*)(out + (size_t)row * ldo + col0 + bj * HALF) = w;
;                 }
;             }
	s_cbranch_scc0 .LBB0_64
	s_waitcnt lgkmcnt(0)
	s_lshl_b32 s47, s54, 8
	s_add_i32 s47, s47, s75
	v_or_b32_e32 v154, s47, v145
	v_ashrrev_i32_e32 v155, 31, v154
	v_lshl_add_u64 v[154:155], v[154:155], 2, s[2:3]
	global_load_dword v140, v[154:155], off
	v_add_u32_e32 v154, s47, v147
	v_ashrrev_i32_e32 v155, 31, v154
	v_lshl_add_u64 v[154:155], v[154:155], 2, s[2:3]
	global_load_dword v142, v[154:155], off
	v_lshl_or_b32 v158, s80, 8, v149
	v_ashrrev_i32_e32 v159, 31, v158
	s_and_b64 vcc, exec, s[36:37]
	s_mov_b32 s80, s46
	s_mov_b32 s54, s48
	s_mov_b64 s[58:59], s[52:53]
	s_waitcnt vmcnt(0)
	v_fmamk_f32 v140, v140, 0x3a000000, v233
	v_rsq_f32_e32 v140, v140
	v_fmamk_f32 v142, v142, 0x3a000000, v233
	ds_bpermute_b32 v154, v152, v140
	v_rsq_f32_e32 v153, v142
	ds_bpermute_b32 v156, v152, v140 offset:64
	ds_bpermute_b32 v150, v152, v140 offset:128
	ds_bpermute_b32 v148, v152, v140 offset:192
	ds_bpermute_b32 v146, v152, v153
	ds_bpermute_b32 v144, v152, v153 offset:64
	ds_bpermute_b32 v142, v152, v153 offset:128
	ds_bpermute_b32 v140, v152, v153 offset:192
	v_or_b32_e32 v153, s47, v141
	s_waitcnt lgkmcnt(0)
	v_pk_mul_f32 v[126:127], v[126:127], v[154:155] op_sel_hi:[1,0]
	v_pk_mul_f32 v[122:123], v[122:123], v[154:155] op_sel_hi:[1,0]
	v_pk_mul_f32 v[128:129], v[128:129], v[154:155] op_sel_hi:[1,0]
	v_pk_mul_f32 v[160:161], v[124:125], v[154:155] op_sel_hi:[1,0]
	v_cvt_pk_bf16_f32 v124, v126, v127
	v_cvt_pk_bf16_f32 v126, v122, v123
	v_mad_i64_i32 v[122:123], s[56:57], v153, s63, 0
	v_cvt_pk_bf16_f32 v125, v128, v129
	v_lshl_add_u64 v[128:129], v[122:123], 1, s[44:45]
	v_lshlrev_b64 v[122:123], 1, v[158:159]
	v_cvt_pk_bf16_f32 v127, v160, v161
	v_lshl_add_u64 v[128:129], v[128:129], 0, v[122:123]
	global_store_dwordx4 v[128:129], v[124:127], off
	v_pk_mul_f32 v[120:121], v[120:121], v[154:155] op_sel_hi:[1,0]
	v_pk_mul_f32 v[118:119], v[118:119], v[154:155] op_sel_hi:[1,0]
	v_pk_mul_f32 v[124:125], v[116:117], v[154:155] op_sel_hi:[1,0]
	v_pk_mul_f32 v[116:117], v[114:115], v[154:155] op_sel_hi:[1,0]
	v_cvt_pk_bf16_f32 v114, v118, v119
	v_cvt_pk_bf16_f32 v115, v120, v121
	v_cvt_pk_bf16_f32 v116, v116, v117
	v_cvt_pk_bf16_f32 v117, v124, v125
	global_store_dwordx4 v[128:129], v[114:117], off offset:256
	v_pk_mul_f32 v[110:111], v[110:111], v[156:157] op_sel_hi:[1,0]
	v_pk_mul_f32 v[112:113], v[112:113], v[156:157] op_sel_hi:[1,0]
	v_or_b32_e32 v116, 16, v153
	v_pk_mul_f32 v[114:115], v[108:109], v[156:157] op_sel_hi:[1,0]
	v_pk_mul_f32 v[108:109], v[106:107], v[156:157] op_sel_hi:[1,0]
	v_cvt_pk_bf16_f32 v106, v110, v111
	v_mad_i64_i32 v[110:111], s[56:57], v116, s63, 0
	v_lshl_add_u64 v[110:111], v[110:111], 1, s[44:45]
	v_cvt_pk_bf16_f32 v107, v112, v113
	v_cvt_pk_bf16_f32 v108, v108, v109
	v_cvt_pk_bf16_f32 v109, v114, v115
	v_lshl_add_u64 v[110:111], v[110:111], 0, v[122:123]
	global_store_dwordx4 v[110:111], v[106:109], off
	v_pk_mul_f32 v[104:105], v[104:105], v[156:157] op_sel_hi:[1,0]
	v_pk_mul_f32 v[102:103], v[102:103], v[156:157] op_sel_hi:[1,0]
	v_pk_mul_f32 v[106:107], v[100:101], v[156:157] op_sel_hi:[1,0]
	v_pk_mul_f32 v[100:101], v[98:99], v[156:157] op_sel_hi:[1,0]
	v_cvt_pk_bf16_f32 v98, v102, v103
	v_cvt_pk_bf16_f32 v99, v104, v105
	v_cvt_pk_bf16_f32 v100, v100, v101
	v_cvt_pk_bf16_f32 v101, v106, v107
	global_store_dwordx4 v[110:111], v[98:101], off offset:256
	v_pk_mul_f32 v[94:95], v[94:95], v[150:151] op_sel_hi:[1,0]
	v_pk_mul_f32 v[96:97], v[96:97], v[150:151] op_sel_hi:[1,0]
	v_or_b32_e32 v100, 32, v153
	v_pk_mul_f32 v[98:99], v[92:93], v[150:151] op_sel_hi:[1,0]
	v_pk_mul_f32 v[92:93], v[90:91], v[150:151] op_sel_hi:[1,0]
	v_cvt_pk_bf16_f32 v90, v94, v95
	v_mad_i64_i32 v[94:95], s[56:57], v100, s63, 0
	v_lshl_add_u64 v[94:95], v[94:95], 1, s[44:45]
	v_cvt_pk_bf16_f32 v91, v96, v97
	v_cvt_pk_bf16_f32 v92, v92, v93
	v_cvt_pk_bf16_f32 v93, v98, v99
	v_lshl_add_u64 v[94:95], v[94:95], 0, v[122:123]
	global_store_dwordx4 v[94:95], v[90:93], off
	v_pk_mul_f32 v[88:89], v[88:89], v[150:151] op_sel_hi:[1,0]
	v_pk_mul_f32 v[86:87], v[86:87], v[150:151] op_sel_hi:[1,0]
	v_pk_mul_f32 v[90:91], v[84:85], v[150:151] op_sel_hi:[1,0]
	v_pk_mul_f32 v[84:85], v[82:83], v[150:151] op_sel_hi:[1,0]
	v_cvt_pk_bf16_f32 v82, v86, v87
	v_cvt_pk_bf16_f32 v83, v88, v89
	v_cvt_pk_bf16_f32 v84, v84, v85
	v_cvt_pk_bf16_f32 v85, v90, v91
	global_store_dwordx4 v[94:95], v[82:85], off offset:256
	v_pk_mul_f32 v[78:79], v[78:79], v[148:149] op_sel_hi:[1,0]
	v_pk_mul_f32 v[80:81], v[80:81], v[148:149] op_sel_hi:[1,0]
	v_or_b32_e32 v84, 48, v153
	v_pk_mul_f32 v[82:83], v[76:77], v[148:149] op_sel_hi:[1,0]
	v_pk_mul_f32 v[76:77], v[74:75], v[148:149] op_sel_hi:[1,0]
	v_cvt_pk_bf16_f32 v74, v78, v79
	v_mad_i64_i32 v[78:79], s[56:57], v84, s63, 0
	v_lshl_add_u64 v[78:79], v[78:79], 1, s[44:45]
	v_cvt_pk_bf16_f32 v75, v80, v81
; __device__ __forceinline__ unsigned pk2(float lo, float hi) { f32x2 v = {lo, hi}; bf16x2_t b = __builtin_convertvector(v, bf16x2_t); return __builtin_bit_cast(unsigned, b); }
; #define PG8_WAIT_V(n) asm volatile("s_waitcnt vmcnt(" #n ")" ::: "memory")
; #define PG8_BAR __builtin_amdgcn_s_barrier()
;     __device__ __forceinline__ void operator()(const AccT& acc, const Unit& u, int wr, int wc, int fr, int fq) const {
;     ...
;             for (int m = 0; m < 4; ++m) {
;                 const int row = row0 + ai * HALF + m * 16;
;                 const float rs = rsv[ai * 4 + m];
; #pragma unroll
;                 for (int bj = 0; bj < 2; ++bj) {
;                     const f32x4 v0 = acc[ai][bj][m][0] * rs, v1 = acc[ai][bj][m][1] * rs;
;                     u32x4 w; w.x = pk2(v0[0], v0[1]); w.y = pk2(v0[2], v0[3]); w.z = pk2(v1[0], v1[1]); w.w = pk2(v1[2], v1[3]);
;                     *(u32x4*)(out + (size_t)row * ldo + col0 + bj * HALF) = w;
;                 }
;             }
; template <class Epi>
; __device__ __forceinline__ void gemm_phase(LAS unsigned char* lds, const Gemm g, const StaticOrder& S, const Epi& E) {
;     ...
;     PG8_WAIT_V(0);
;     if (wr == 0) PG8_BAR;
;     PG8_BAR;
	v_cvt_pk_bf16_f32 v76, v76, v77
	v_cvt_pk_bf16_f32 v77, v82, v83
	v_lshl_add_u64 v[78:79], v[78:79], 0, v[122:123]
	global_store_dwordx4 v[78:79], v[74:77], off
	v_pk_mul_f32 v[72:73], v[72:73], v[148:149] op_sel_hi:[1,0]
	v_pk_mul_f32 v[70:71], v[70:71], v[148:149] op_sel_hi:[1,0]
	v_pk_mul_f32 v[74:75], v[68:69], v[148:149] op_sel_hi:[1,0]
	v_pk_mul_f32 v[68:69], v[66:67], v[148:149] op_sel_hi:[1,0]
	v_cvt_pk_bf16_f32 v66, v70, v71
	v_cvt_pk_bf16_f32 v67, v72, v73
	v_cvt_pk_bf16_f32 v68, v68, v69
	v_cvt_pk_bf16_f32 v69, v74, v75
	global_store_dwordx4 v[78:79], v[66:69], off offset:256
	v_pk_mul_f32 v[62:63], v[62:63], v[146:147] op_sel_hi:[1,0]
	v_pk_mul_f32 v[64:65], v[64:65], v[146:147] op_sel_hi:[1,0]
	v_add_u32_e32 v68, 0x80, v153
	v_pk_mul_f32 v[66:67], v[60:61], v[146:147] op_sel_hi:[1,0]
	v_pk_mul_f32 v[60:61], v[58:59], v[146:147] op_sel_hi:[1,0]
	v_cvt_pk_bf16_f32 v58, v62, v63
	v_mad_i64_i32 v[62:63], s[56:57], v68, s63, 0
	v_lshl_add_u64 v[62:63], v[62:63], 1, s[44:45]
	v_cvt_pk_bf16_f32 v59, v64, v65
	v_cvt_pk_bf16_f32 v60, v60, v61
	v_cvt_pk_bf16_f32 v61, v66, v67
	v_lshl_add_u64 v[62:63], v[62:63], 0, v[122:123]
	global_store_dwordx4 v[62:63], v[58:61], off
	v_pk_mul_f32 v[52:53], v[52:53], v[146:147] op_sel_hi:[1,0]
	v_pk_mul_f32 v[50:51], v[50:51], v[146:147] op_sel_hi:[1,0]
	v_pk_mul_f32 v[58:59], v[44:45], v[146:147] op_sel_hi:[1,0]
	v_pk_mul_f32 v[44:45], v[42:43], v[146:147] op_sel_hi:[1,0]
	v_cvt_pk_bf16_f32 v42, v50, v51
	v_cvt_pk_bf16_f32 v43, v52, v53
	v_cvt_pk_bf16_f32 v44, v44, v45
	v_cvt_pk_bf16_f32 v45, v58, v59
	global_store_dwordx4 v[62:63], v[42:45], off offset:256
	v_add_u32_e32 v50, 0x90, v153
	v_pk_mul_f32 v[46:47], v[46:47], v[144:145] op_sel_hi:[1,0]
	v_pk_mul_f32 v[44:45], v[56:57], v[144:145] op_sel_hi:[1,0]
	v_pk_mul_f32 v[42:43], v[54:55], v[144:145] op_sel_hi:[1,0]
	v_pk_mul_f32 v[48:49], v[48:49], v[144:145] op_sel_hi:[1,0]
	v_cvt_pk_bf16_f32 v42, v42, v43
	v_cvt_pk_bf16_f32 v43, v44, v45
	v_cvt_pk_bf16_f32 v44, v46, v47
	v_mad_i64_i32 v[46:47], s[56:57], v50, s63, 0
	v_lshl_add_u64 v[46:47], v[46:47], 1, s[44:45]
	v_cvt_pk_bf16_f32 v45, v48, v49
	v_lshl_add_u64 v[46:47], v[46:47], 0, v[122:123]
	global_store_dwordx4 v[46:47], v[42:45], off
	v_pk_mul_f32 v[36:37], v[36:37], v[144:145] op_sel_hi:[1,0]
	v_pk_mul_f32 v[34:35], v[34:35], v[144:145] op_sel_hi:[1,0]
	v_pk_mul_f32 v[42:43], v[28:29], v[144:145] op_sel_hi:[1,0]
	v_pk_mul_f32 v[28:29], v[26:27], v[144:145] op_sel_hi:[1,0]
	v_cvt_pk_bf16_f32 v26, v34, v35
	v_cvt_pk_bf16_f32 v27, v36, v37
	v_cvt_pk_bf16_f32 v28, v28, v29
	v_cvt_pk_bf16_f32 v29, v42, v43
	global_store_dwordx4 v[46:47], v[26:29], off offset:256
	v_add_u32_e32 v34, 0xa0, v153
	v_pk_mul_f32 v[30:31], v[30:31], v[142:143] op_sel_hi:[1,0]
	v_pk_mul_f32 v[28:29], v[40:41], v[142:143] op_sel_hi:[1,0]
	v_pk_mul_f32 v[26:27], v[38:39], v[142:143] op_sel_hi:[1,0]
	v_pk_mul_f32 v[32:33], v[32:33], v[142:143] op_sel_hi:[1,0]
	v_cvt_pk_bf16_f32 v26, v26, v27
	v_cvt_pk_bf16_f32 v27, v28, v29
	v_cvt_pk_bf16_f32 v28, v30, v31
	v_mad_i64_i32 v[30:31], s[56:57], v34, s63, 0
	v_lshl_add_u64 v[30:31], v[30:31], 1, s[44:45]
	v_cvt_pk_bf16_f32 v29, v32, v33
	v_lshl_add_u64 v[30:31], v[30:31], 0, v[122:123]
	global_store_dwordx4 v[30:31], v[26:29], off
	v_pk_mul_f32 v[20:21], v[20:21], v[142:143] op_sel_hi:[1,0]
	v_pk_mul_f32 v[18:19], v[18:19], v[142:143] op_sel_hi:[1,0]
	v_pk_mul_f32 v[26:27], v[12:13], v[142:143] op_sel_hi:[1,0]
	v_pk_mul_f32 v[12:13], v[10:11], v[142:143] op_sel_hi:[1,0]
	v_cvt_pk_bf16_f32 v10, v18, v19
	v_cvt_pk_bf16_f32 v11, v20, v21
	v_cvt_pk_bf16_f32 v12, v12, v13
	v_cvt_pk_bf16_f32 v13, v26, v27
	global_store_dwordx4 v[30:31], v[10:13], off offset:256
	v_add_u32_e32 v18, 0xb0, v153
	v_pk_mul_f32 v[14:15], v[14:15], v[140:141] op_sel_hi:[1,0]
	v_pk_mul_f32 v[12:13], v[24:25], v[140:141] op_sel_hi:[1,0]
	v_pk_mul_f32 v[10:11], v[22:23], v[140:141] op_sel_hi:[1,0]
	v_pk_mul_f32 v[16:17], v[16:17], v[140:141] op_sel_hi:[1,0]
	v_cvt_pk_bf16_f32 v10, v10, v11
	v_cvt_pk_bf16_f32 v11, v12, v13
	v_cvt_pk_bf16_f32 v12, v14, v15
	v_mad_i64_i32 v[14:15], s[56:57], v18, s63, 0
	v_lshl_add_u64 v[14:15], v[14:15], 1, s[44:45]
	v_cvt_pk_bf16_f32 v13, v16, v17
	v_lshl_add_u64 v[14:15], v[14:15], 0, v[122:123]
	global_store_dwordx4 v[14:15], v[10:13], off
	v_pk_mul_f32 v[8:9], v[8:9], v[140:141] op_sel_hi:[1,0]
	v_pk_mul_f32 v[6:7], v[6:7], v[140:141] op_sel_hi:[1,0]
	v_pk_mul_f32 v[10:11], v[4:5], v[140:141] op_sel_hi:[1,0]
	v_pk_mul_f32 v[4:5], v[2:3], v[140:141] op_sel_hi:[1,0]
	v_cvt_pk_bf16_f32 v2, v6, v7
	v_cvt_pk_bf16_f32 v3, v8, v9
	v_cvt_pk_bf16_f32 v4, v4, v5
	v_cvt_pk_bf16_f32 v5, v10, v11
	s_mov_b64 s[56:57], s[50:51]
	global_store_dwordx4 v[14:15], v[2:5], off offset:256
	s_cbranch_vccz .LBB0_61
	s_waitcnt vmcnt(0)
	s_cmpk_gt_u32 s64, 0xff
	s_cbranch_scc1 .LBB0_68
	s_barrier

; #define PG8_STAGE(bufoff, gbase, voff) do { _Pragma("unroll") for (int _i = 0; _i < 2; ++_i) \
;         __builtin_amdgcn_global_load_lds((const unsigned*)((const char*)(gbase) + (voff)[_i]), (LAS unsigned*)(lds + (bufoff) + ldsw + _i * 8192), 16, 0, 0); } while (0)
; #define PG8_LDA(dst, b, h) do { _Pragma("unroll") for (int m = 0; m < 4; ++m) _Pragma("unroll") for (int k = 0; k < 2; ++k) dst[m][k] = *(const LAS bf16x8*)(lds + PG8_SA(b, h) + aoff + m * 2048 + k * 1024); } while (0)
; #define PG8_LDB(dst, b, h) do { _Pragma("unroll") for (int n = 0; n < 2; ++n) _Pragma("unroll") for (int k = 0; k < 2; ++k) dst[n][k] = *(const LAS bf16x8*)(lds + PG8_SB(b, h) + boff + n * 2048 + k * 1024); } while (0)
; #define PG8_SCHED __builtin_amdgcn_sched_barrier(0)
; template <class Epi>
; __device__ __forceinline__ void gemm_phase(LAS unsigned char* lds, const Gemm g, const StaticOrder& S, const Epi& E) {
;     ...
;         const bool has_next = S.next(ui + 1, nxt);
;         const char* nA = has_next ? (const char*)g.A + (size_t)nxt.pm * tstep : cA; const char* nB = has_next ? (const char*)g.Bt + (size_t)nxt.pn * tstep : cB;
;         for (int t = 0; t < nt; t += 2) {
;             const bool last = (t == nt - 2);
;             const char* a1 = cA + (size_t)(t + 1) * kstep;
;             const char* a2 = last ? nA : cA + (size_t)(t + 2) * kstep; const char* b2 = last ? nB : cB + (size_t)(t + 2) * kstep;
;             const char* a3 = a2 + kstep; const char* b3 = b2 + kstep;
;             PG8_LDB(B0, 0, 0); PG8_SCHED; PG8_LDA(At, 0, 0); PG8_STAGE(PG8_SA(1, 1), a1 + hstep, voffA);
;     ...
;         for (int a = 0; a < 2; ++a)
; #pragma unroll
;             for (int b = 0; b < 2; ++b)
; #pragma unroll
;                 for (int m = 0; m < 4; ++m)
; #pragma unroll
;                     for (int n = 0; n < 2; ++n) acc[a][b][m][n] = (f32x4){0.f, 0.f, 0.f, 0.f};
;         cur = nxt; cA = nA; cB = nB; ++ui;
.LBB0_76:
	s_ashr_i32 s49, s48, 31
	v_cmp_lt_i64_e64 s[58:59], s[50:51], 4
	s_lshl_b64 s[50:51], s[48:49], 20
	s_add_u32 s50, s36, s50
	s_addc_u32 s51, s37, s51
	s_and_b64 s[52:53], s[58:59], exec
	s_cselect_b32 s49, s51, s55
	s_cselect_b32 s76, s50, s54
	s_ashr_i32 s47, s46, 31
	s_lshl_b64 s[52:53], s[46:47], 20
	s_add_u32 s52, s61, s52
	s_addc_u32 s53, s63, s53
	s_and_b64 s[58:59], s[58:59], exec
	s_cselect_b32 s47, s53, s57
	s_cselect_b32 s77, s52, s56
	s_add_u32 s54, s54, 0x80080
	s_addc_u32 s55, s55, 0
	s_add_u32 s78, s56, 0x100
	v_mov_b32_e32 v2, 0
	s_addc_u32 s79, s57, 0
	s_mov_b32 s80, -2
	v_mov_b32_e32 v3, v2
	v_mov_b32_e32 v4, v2
	v_mov_b32_e32 v5, v2
	v_mov_b32_e32 v6, v2
	v_mov_b32_e32 v7, v2
	v_mov_b32_e32 v8, v2
	v_mov_b32_e32 v9, v2
	v_mov_b32_e32 v10, v2
	v_mov_b32_e32 v11, v2
	v_mov_b32_e32 v12, v2
	v_mov_b32_e32 v13, v2
	v_mov_b32_e32 v14, v2
	v_mov_b32_e32 v15, v2
	v_mov_b32_e32 v16, v2
	v_mov_b32_e32 v17, v2
	v_mov_b32_e32 v26, v2
	v_mov_b32_e32 v27, v2
	v_mov_b32_e32 v28, v2
	v_mov_b32_e32 v29, v2
	v_mov_b32_e32 v30, v2
	v_mov_b32_e32 v31, v2
	v_mov_b32_e32 v32, v2
	v_mov_b32_e32 v33, v2
	v_mov_b32_e32 v42, v2
	v_mov_b32_e32 v43, v2
	v_mov_b32_e32 v44, v2
	v_mov_b32_e32 v45, v2
	v_mov_b32_e32 v46, v2
	v_mov_b32_e32 v47, v2
	v_mov_b32_e32 v48, v2
	v_mov_b32_e32 v49, v2
	v_mov_b32_e32 v18, v2
	v_mov_b32_e32 v19, v2
	v_mov_b32_e32 v20, v2
	v_mov_b32_e32 v21, v2
	v_mov_b32_e32 v22, v2
	v_mov_b32_e32 v23, v2
	v_mov_b32_e32 v24, v2
	v_mov_b32_e32 v25, v2
	v_mov_b32_e32 v34, v2
	v_mov_b32_e32 v35, v2
	v_mov_b32_e32 v36, v2
	v_mov_b32_e32 v37, v2
	v_mov_b32_e32 v38, v2
	v_mov_b32_e32 v39, v2
	v_mov_b32_e32 v40, v2
	v_mov_b32_e32 v41, v2
	v_mov_b32_e32 v50, v2
	v_mov_b32_e32 v51, v2
	v_mov_b32_e32 v52, v2
	v_mov_b32_e32 v53, v2
	v_mov_b32_e32 v54, v2
	v_mov_b32_e32 v55, v2
	v_mov_b32_e32 v56, v2
	v_mov_b32_e32 v57, v2
	v_mov_b32_e32 v58, v2
	v_mov_b32_e32 v59, v2
	v_mov_b32_e32 v60, v2
	v_mov_b32_e32 v61, v2
	v_mov_b32_e32 v62, v2
	v_mov_b32_e32 v63, v2
	v_mov_b32_e32 v64, v2
	v_mov_b32_e32 v65, v2
	v_mov_b32_e32 v66, v2
	v_mov_b32_e32 v67, v2
	v_mov_b32_e32 v68, v2
	v_mov_b32_e32 v69, v2
	v_mov_b32_e32 v70, v2
	v_mov_b32_e32 v71, v2
	v_mov_b32_e32 v72, v2
	v_mov_b32_e32 v73, v2
	v_mov_b32_e32 v74, v2
	v_mov_b32_e32 v75, v2
	v_mov_b32_e32 v76, v2
	v_mov_b32_e32 v77, v2
	v_mov_b32_e32 v78, v2
	v_mov_b32_e32 v79, v2
	v_mov_b32_e32 v80, v2
	v_mov_b32_e32 v81, v2
	v_mov_b32_e32 v90, v2
	v_mov_b32_e32 v91, v2
	v_mov_b32_e32 v92, v2
	v_mov_b32_e32 v93, v2
	v_mov_b32_e32 v94, v2
	v_mov_b32_e32 v95, v2
	v_mov_b32_e32 v96, v2
	v_mov_b32_e32 v97, v2
	v_mov_b32_e32 v106, v2
	v_mov_b32_e32 v107, v2
	v_mov_b32_e32 v108, v2
	v_mov_b32_e32 v109, v2
	v_mov_b32_e32 v110, v2
	v_mov_b32_e32 v111, v2
	v_mov_b32_e32 v112, v2
	v_mov_b32_e32 v113, v2
	v_mov_b32_e32 v82, v2
	v_mov_b32_e32 v83, v2
	v_mov_b32_e32 v84, v2
	v_mov_b32_e32 v85, v2
	v_mov_b32_e32 v86, v2
	v_mov_b32_e32 v87, v2
	v_mov_b32_e32 v88, v2
	v_mov_b32_e32 v89, v2
	v_mov_b32_e32 v98, v2
	v_mov_b32_e32 v99, v2
	v_mov_b32_e32 v100, v2
	v_mov_b32_e32 v101, v2
	v_mov_b32_e32 v102, v2
	v_mov_b32_e32 v103, v2
	v_mov_b32_e32 v104, v2
	v_mov_b32_e32 v105, v2
	v_mov_b32_e32 v114, v2
	v_mov_b32_e32 v115, v2
	v_mov_b32_e32 v116, v2
	v_mov_b32_e32 v117, v2
	v_mov_b32_e32 v118, v2
	v_mov_b32_e32 v119, v2
	v_mov_b32_e32 v120, v2
	v_mov_b32_e32 v121, v2
	v_mov_b32_e32 v122, v2
	v_mov_b32_e32 v123, v2
	v_mov_b32_e32 v124, v2
	v_mov_b32_e32 v125, v2
	v_mov_b32_e32 v126, v2
	v_mov_b32_e32 v127, v2
	v_mov_b32_e32 v128, v2
	v_mov_b32_e32 v129, v2
	v_add_u32_e32 v202, 0x10000, v141
	ds_read_b128 v[144:147], v202
	ds_read_b128 v[148:151], v202 offset:1024
	ds_read_b128 v[152:155], v202 offset:2048
	ds_read_b128 v[156:159], v202 offset:3072
.LBB0_77:
	s_add_u32 s56, s54, 0xfff80080
	s_addc_u32 s57, s55, -1
	s_add_i32 s81, 0, 0x10000
	s_cmp_eq_u32 s80, 28
	s_cselect_b32 s59, s49, s57
	s_cselect_b32 s58, s76, s56
	s_cselect_b32 s57, s47, s79
	s_cselect_b32 s56, s77, s78
	s_add_i32 m0, s65, 0xc000
	ds_read_b128 v[160:163], v143
	ds_read_b128 v[164:167], v143 offset:1024
	ds_read_b128 v[168:171], v143 offset:2048
	ds_read_b128 v[172:175], v143 offset:3072
	ds_read_b128 v[176:179], v143 offset:4096
	ds_read_b128 v[180:183], v143 offset:5120
	ds_read_b128 v[184:187], v143 offset:6144
	ds_read_b128 v[188:191], v143 offset:7168
	global_load_lds_dwordx4 v136, s[54:55]
	s_add_i32 m0, s65, 0xe000
	s_nop 0
	global_load_lds_dwordx4 v138, s[54:55]
	s_waitcnt lgkmcnt(8)
	s_barrier
	s_waitcnt lgkmcnt(0)
	s_setprio 1
	v_mfma_f32_16x16x32_bf16 v[126:129], v[144:147], v[160:163], v[126:129]
	v_mfma_f32_16x16x32_bf16 v[122:125], v[152:155], v[160:163], v[122:125]
	v_mfma_f32_16x16x32_bf16 v[118:121], v[144:147], v[168:171], v[118:121]
	v_mfma_f32_16x16x32_bf16 v[114:117], v[152:155], v[168:171], v[114:117]
	v_mfma_f32_16x16x32_bf16 v[102:105], v[144:147], v[176:179], v[102:105]
	v_mfma_f32_16x16x32_bf16 v[98:101], v[152:155], v[176:179], v[98:101]
	v_mfma_f32_16x16x32_bf16 v[86:89], v[144:147], v[184:187], v[86:89]
	v_mfma_f32_16x16x32_bf16 v[82:85], v[152:155], v[184:187], v[82:85]
	v_mfma_f32_16x16x32_bf16 v[126:129], v[148:151], v[164:167], v[126:129]
	v_mfma_f32_16x16x32_bf16 v[122:125], v[156:159], v[164:167], v[122:125]
	v_mfma_f32_16x16x32_bf16 v[118:121], v[148:151], v[172:175], v[118:121]
	v_mfma_f32_16x16x32_bf16 v[114:117], v[156:159], v[172:175], v[114:117]
	v_mfma_f32_16x16x32_bf16 v[102:105], v[148:151], v[180:183], v[102:105]
	v_mfma_f32_16x16x32_bf16 v[98:101], v[156:159], v[180:183], v[98:101]
	v_mfma_f32_16x16x32_bf16 v[86:89], v[148:151], v[188:191], v[86:89]
	v_mfma_f32_16x16x32_bf16 v[82:85], v[156:159], v[188:191], v[82:85]
	s_setprio 0
	s_barrier
; #define PG8_STAGE(bufoff, gbase, voff) do { _Pragma("unroll") for (int _i = 0; _i < 2; ++_i) \
;         __builtin_amdgcn_global_load_lds((const unsigned*)((const char*)(gbase) + (voff)[_i]), (LAS unsigned*)(lds + (bufoff) + ldsw + _i * 8192), 16, 0, 0); } while (0)
; #define PG8_LDA(dst, b, h) do { _Pragma("unroll") for (int m = 0; m < 4; ++m) _Pragma("unroll") for (int k = 0; k < 2; ++k) dst[m][k] = *(const LAS bf16x8*)(lds + PG8_SA(b, h) + aoff + m * 2048 + k * 1024); } while (0)
; #define PG8_LDB(dst, b, h) do { _Pragma("unroll") for (int n = 0; n < 2; ++n) _Pragma("unroll") for (int k = 0; k < 2; ++k) dst[n][k] = *(const LAS bf16x8*)(lds + PG8_SB(b, h) + boff + n * 2048 + k * 1024); } while (0)
; #define PG8_MMA(ai, bj, At, Bt) do { __builtin_amdgcn_s_setprio(1); _Pragma("unroll") for (int m = 0; m < 4; ++m) _Pragma("unroll") for (int n = 0; n < 2; ++n) _Pragma("unroll") for (int k = 0; k < 2; ++k) \
;         acc[ai][bj][m][n] = __builtin_amdgcn_mfma_f32_16x16x32_bf16(Bt[n][k], At[m][k], acc[ai][bj][m][n], 0, 0, 0); __builtin_amdgcn_s_setprio(0); } while (0)
; #define PG8_WAIT_V(n) asm volatile("s_waitcnt vmcnt(" #n ")" ::: "memory")
; #define PG8_WAIT_L(n) asm volatile("s_waitcnt lgkmcnt(" #n ")" ::: "memory")
; #define PG8_BAR __builtin_amdgcn_s_barrier()
; #define PG8_SCHED __builtin_amdgcn_sched_barrier(0)
; template <class Epi>
; __device__ __forceinline__ void gemm_phase(LAS unsigned char* lds, const Gemm g, const StaticOrder& S, const Epi& E) {
;     ...
;             PG8_LDB(B1, 0, 1); PG8_STAGE(PG8_SB(0, 0), b2, voffB);
;             PG8_BAR; PG8_WAIT_L(0); PG8_MMA(0, 1, At, B1); PG8_BAR;
;             PG8_LDA(At, 0, 1); PG8_STAGE(PG8_SA(0, 0), a2, voffA);
;             PG8_BAR; PG8_WAIT_L(0); PG8_MMA(1, 0, At, B0); PG8_BAR; PG8_SCHED;
;             PG8_STAGE(PG8_SB(0, 1), b2 + hstep, voffB);
;             PG8_WAIT_V(6); PG8_BAR; PG8_MMA(1, 1, At, B1); PG8_BAR;
;             PG8_LDB(B0, 1, 0); PG8_SCHED; PG8_LDA(At, 1, 0); PG8_STAGE(PG8_SA(0, 1), a2 + hstep, voffA);
;             PG8_WAIT_L(8); PG8_BAR; PG8_WAIT_L(0); PG8_MMA(0, 0, At, B0); PG8_BAR; PG8_SCHED;
	s_add_i32 s84, 0, 0x14000
	s_add_i32 s81, s81, s64
	ds_read_b128 v[192:195], v202 offset:16384
	ds_read_b128 v[196:199], v202 offset:17408
	ds_read_b128 v[208:211], v202 offset:18432
	ds_read_b128 v[212:215], v202 offset:19456
	s_mov_b32 m0, s81
	s_add_u32 s98, s56, s22
	s_addc_u32 s99, s57, s23
	global_load_lds_dwordx4 v0, s[56:57]
	s_add_i32 m0, s81, 0x2000
	s_nop 0
	global_load_lds_dwordx4 v130, s[56:57]
	s_barrier
	s_waitcnt lgkmcnt(0)
	s_setprio 1
	v_mfma_f32_16x16x32_bf16 v[110:113], v[192:195], v[160:163], v[110:113]
	v_mfma_f32_16x16x32_bf16 v[106:109], v[208:211], v[160:163], v[106:109]
	v_mfma_f32_16x16x32_bf16 v[94:97], v[192:195], v[168:171], v[94:97]
	v_mfma_f32_16x16x32_bf16 v[90:93], v[208:211], v[168:171], v[90:93]
	v_mfma_f32_16x16x32_bf16 v[78:81], v[192:195], v[176:179], v[78:81]
	v_mfma_f32_16x16x32_bf16 v[74:77], v[208:211], v[176:179], v[74:77]
	v_mfma_f32_16x16x32_bf16 v[70:73], v[192:195], v[184:187], v[70:73]
	v_mfma_f32_16x16x32_bf16 v[66:69], v[208:211], v[184:187], v[66:69]
	v_mfma_f32_16x16x32_bf16 v[110:113], v[196:199], v[164:167], v[110:113]
	v_mfma_f32_16x16x32_bf16 v[106:109], v[212:215], v[164:167], v[106:109]
	v_mfma_f32_16x16x32_bf16 v[94:97], v[196:199], v[172:175], v[94:97]
	v_mfma_f32_16x16x32_bf16 v[90:93], v[212:215], v[172:175], v[90:93]
	v_mfma_f32_16x16x32_bf16 v[78:81], v[196:199], v[180:183], v[78:81]
	v_mfma_f32_16x16x32_bf16 v[74:77], v[212:215], v[180:183], v[74:77]
	v_mfma_f32_16x16x32_bf16 v[70:73], v[196:199], v[188:191], v[70:73]
	v_mfma_f32_16x16x32_bf16 v[66:69], v[212:215], v[188:191], v[66:69]
	s_setprio 0
	s_mov_b32 m0, s65
	s_add_u32 s100, s58, s22
	s_addc_u32 s101, s59, s23
	s_barrier
	ds_read_b128 v[160:163], v143 offset:16384
	ds_read_b128 v[164:167], v143 offset:17408
	ds_read_b128 v[168:171], v143 offset:18432
	ds_read_b128 v[172:175], v143 offset:19456
	ds_read_b128 v[176:179], v143 offset:20480
	ds_read_b128 v[180:183], v143 offset:21504
	ds_read_b128 v[184:187], v143 offset:22528
	ds_read_b128 v[188:191], v143 offset:23552
	global_load_lds_dwordx4 v134, s[58:59]
	s_mov_b32 m0, s68
	s_nop 0
	global_load_lds_dwordx4 v132, s[58:59]
	s_waitcnt vmcnt(10)
	s_barrier
	s_waitcnt lgkmcnt(0)
	s_setprio 1
	v_mfma_f32_16x16x32_bf16 v[62:65], v[144:147], v[160:163], v[62:65]
	v_mfma_f32_16x16x32_bf16 v[58:61], v[152:155], v[160:163], v[58:61]
	v_mfma_f32_16x16x32_bf16 v[54:57], v[144:147], v[168:171], v[54:57]
	v_mfma_f32_16x16x32_bf16 v[50:53], v[152:155], v[168:171], v[50:53]
	v_mfma_f32_16x16x32_bf16 v[38:41], v[144:147], v[176:179], v[38:41]
	v_mfma_f32_16x16x32_bf16 v[34:37], v[152:155], v[176:179], v[34:37]
	v_mfma_f32_16x16x32_bf16 v[22:25], v[144:147], v[184:187], v[22:25]
	v_mfma_f32_16x16x32_bf16 v[18:21], v[152:155], v[184:187], v[18:21]
	v_mfma_f32_16x16x32_bf16 v[62:65], v[148:151], v[164:167], v[62:65]
	v_mfma_f32_16x16x32_bf16 v[58:61], v[156:159], v[164:167], v[58:61]
	v_mfma_f32_16x16x32_bf16 v[54:57], v[148:151], v[172:175], v[54:57]
	v_mfma_f32_16x16x32_bf16 v[50:53], v[156:159], v[172:175], v[50:53]
	v_mfma_f32_16x16x32_bf16 v[38:41], v[148:151], v[180:183], v[38:41]
	v_mfma_f32_16x16x32_bf16 v[34:37], v[156:159], v[180:183], v[34:37]
	v_mfma_f32_16x16x32_bf16 v[22:25], v[148:151], v[188:191], v[22:25]
	v_mfma_f32_16x16x32_bf16 v[18:21], v[156:159], v[188:191], v[18:21]
	s_setprio 0
	s_barrier
	ds_read_b128 v[144:147], v202 offset:32768
	ds_read_b128 v[148:151], v202 offset:33792
	ds_read_b128 v[152:155], v202 offset:34816
	ds_read_b128 v[156:159], v202 offset:35840
	s_add_u32 s82, s56, 0x80000
	s_addc_u32 s83, s57, 0
	s_add_i32 s81, s84, s64
	s_mov_b32 m0, s81
	s_nop 0
	global_load_lds_dwordx4 v0, s[82:83]
	s_add_i32 m0, s81, 0x2000
	s_nop 0
	global_load_lds_dwordx4 v130, s[82:83]
	s_waitcnt vmcnt(6)
	s_barrier
	s_setprio 1
	v_mfma_f32_16x16x32_bf16 v[46:49], v[192:195], v[160:163], v[46:49]
	v_mfma_f32_16x16x32_bf16 v[42:45], v[208:211], v[160:163], v[42:45]
	v_mfma_f32_16x16x32_bf16 v[30:33], v[192:195], v[168:171], v[30:33]
	v_mfma_f32_16x16x32_bf16 v[26:29], v[208:211], v[168:171], v[26:29]
	v_mfma_f32_16x16x32_bf16 v[14:17], v[192:195], v[176:179], v[14:17]
	v_mfma_f32_16x16x32_bf16 v[10:13], v[208:211], v[176:179], v[10:13]
	v_mfma_f32_16x16x32_bf16 v[6:9], v[192:195], v[184:187], v[6:9]
	v_mfma_f32_16x16x32_bf16 v[2:5], v[208:211], v[184:187], v[2:5]
	v_mfma_f32_16x16x32_bf16 v[46:49], v[196:199], v[164:167], v[46:49]
	v_mfma_f32_16x16x32_bf16 v[42:45], v[212:215], v[164:167], v[42:45]
	v_mfma_f32_16x16x32_bf16 v[30:33], v[196:199], v[172:175], v[30:33]
	v_mfma_f32_16x16x32_bf16 v[26:29], v[212:215], v[172:175], v[26:29]
	v_mfma_f32_16x16x32_bf16 v[14:17], v[196:199], v[180:183], v[14:17]
	v_mfma_f32_16x16x32_bf16 v[10:13], v[212:215], v[180:183], v[10:13]
	v_mfma_f32_16x16x32_bf16 v[6:9], v[196:199], v[188:191], v[6:9]
	v_mfma_f32_16x16x32_bf16 v[2:5], v[212:215], v[188:191], v[2:5]
	s_setprio 0
	s_add_i32 s81, 0, 0x18000
	s_barrier
	s_add_u32 s58, s58, 0x80000
	s_addc_u32 s59, s59, 0
	s_mov_b32 m0, s69
	ds_read_b128 v[160:163], v143 offset:32768
	ds_read_b128 v[164:167], v143 offset:33792
	ds_read_b128 v[168:171], v143 offset:34816
	ds_read_b128 v[172:175], v143 offset:35840
	ds_read_b128 v[176:179], v143 offset:36864
	ds_read_b128 v[180:183], v143 offset:37888
	ds_read_b128 v[184:187], v143 offset:38912
	ds_read_b128 v[188:191], v143 offset:39936
	global_load_lds_dwordx4 v134, s[58:59]
	s_mov_b32 m0, s70
	s_nop 0
	global_load_lds_dwordx4 v132, s[58:59]
	s_waitcnt lgkmcnt(8)
	s_barrier
; #define PG8_STAGE(bufoff, gbase, voff) do { _Pragma("unroll") for (int _i = 0; _i < 2; ++_i) \
;         __builtin_amdgcn_global_load_lds((const unsigned*)((const char*)(gbase) + (voff)[_i]), (LAS unsigned*)(lds + (bufoff) + ldsw + _i * 8192), 16, 0, 0); } while (0)
; #define PG8_LDA(dst, b, h) do { _Pragma("unroll") for (int m = 0; m < 4; ++m) _Pragma("unroll") for (int k = 0; k < 2; ++k) dst[m][k] = *(const LAS bf16x8*)(lds + PG8_SA(b, h) + aoff + m * 2048 + k * 1024); } while (0)
; #define PG8_LDB(dst, b, h) do { _Pragma("unroll") for (int n = 0; n < 2; ++n) _Pragma("unroll") for (int k = 0; k < 2; ++k) dst[n][k] = *(const LAS bf16x8*)(lds + PG8_SB(b, h) + boff + n * 2048 + k * 1024); } while (0)
; #define PG8_MMA(ai, bj, At, Bt) do { __builtin_amdgcn_s_setprio(1); _Pragma("unroll") for (int m = 0; m < 4; ++m) _Pragma("unroll") for (int n = 0; n < 2; ++n) _Pragma("unroll") for (int k = 0; k < 2; ++k) \
;         acc[ai][bj][m][n] = __builtin_amdgcn_mfma_f32_16x16x32_bf16(Bt[n][k], At[m][k], acc[ai][bj][m][n], 0, 0, 0); __builtin_amdgcn_s_setprio(0); } while (0)
; #define PG8_WAIT_V(n) asm volatile("s_waitcnt vmcnt(" #n ")" ::: "memory")
; #define PG8_WAIT_L(n) asm volatile("s_waitcnt lgkmcnt(" #n ")" ::: "memory")
; #define PG8_BAR __builtin_amdgcn_s_barrier()
; #define PG8_SCHED __builtin_amdgcn_sched_barrier(0)
; template <class Epi>
; __device__ __forceinline__ void gemm_phase(LAS unsigned char* lds, const Gemm g, const StaticOrder& S, const Epi& E) {
;     ...
;             PG8_WAIT_L(8); PG8_BAR; PG8_WAIT_L(0); PG8_MMA(0, 0, At, B0); PG8_BAR; PG8_SCHED;
;             PG8_LDB(B1, 1, 1); PG8_STAGE(PG8_SB(1, 0), b3, voffB);
;             PG8_BAR; PG8_WAIT_L(0); PG8_MMA(0, 1, At, B1); PG8_BAR;
;             PG8_LDA(At, 1, 1); PG8_STAGE(PG8_SA(1, 0), a3, voffA);
;             PG8_BAR; PG8_WAIT_L(0); PG8_MMA(1, 0, At, B0); PG8_BAR; PG8_SCHED;
;             PG8_STAGE(PG8_SB(1, 1), b3 + hstep, voffB);
;             PG8_WAIT_V(6); PG8_BAR; PG8_MMA(1, 1, At, B1); PG8_BAR;
	s_waitcnt lgkmcnt(0)
	s_setprio 1
	v_mfma_f32_16x16x32_bf16 v[126:129], v[144:147], v[160:163], v[126:129]
	v_mfma_f32_16x16x32_bf16 v[122:125], v[152:155], v[160:163], v[122:125]
	v_mfma_f32_16x16x32_bf16 v[118:121], v[144:147], v[168:171], v[118:121]
	v_mfma_f32_16x16x32_bf16 v[114:117], v[152:155], v[168:171], v[114:117]
	v_mfma_f32_16x16x32_bf16 v[102:105], v[144:147], v[176:179], v[102:105]
	v_mfma_f32_16x16x32_bf16 v[98:101], v[152:155], v[176:179], v[98:101]
	v_mfma_f32_16x16x32_bf16 v[86:89], v[144:147], v[184:187], v[86:89]
	v_mfma_f32_16x16x32_bf16 v[82:85], v[152:155], v[184:187], v[82:85]
	v_mfma_f32_16x16x32_bf16 v[126:129], v[148:151], v[164:167], v[126:129]
	v_mfma_f32_16x16x32_bf16 v[122:125], v[156:159], v[164:167], v[122:125]
	v_mfma_f32_16x16x32_bf16 v[118:121], v[148:151], v[172:175], v[118:121]
	v_mfma_f32_16x16x32_bf16 v[114:117], v[156:159], v[172:175], v[114:117]
	v_mfma_f32_16x16x32_bf16 v[102:105], v[148:151], v[180:183], v[102:105]
	v_mfma_f32_16x16x32_bf16 v[98:101], v[156:159], v[180:183], v[98:101]
	v_mfma_f32_16x16x32_bf16 v[86:89], v[148:151], v[188:191], v[86:89]
	v_mfma_f32_16x16x32_bf16 v[82:85], v[156:159], v[188:191], v[82:85]
	s_setprio 0
	s_barrier
	s_add_i32 s58, 0, 0x1c000
	s_add_i32 s59, s81, s64
	s_mov_b32 m0, s59
	ds_read_b128 v[192:195], v202 offset:49152
	ds_read_b128 v[196:199], v202 offset:50176
	ds_read_b128 v[208:211], v202 offset:51200
	ds_read_b128 v[212:215], v202 offset:52224
	global_load_lds_dwordx4 v0, s[98:99]
	s_add_i32 m0, s59, 0x2000
	s_nop 0
	global_load_lds_dwordx4 v130, s[98:99]
	s_barrier
	s_waitcnt lgkmcnt(0)
	s_setprio 1
	v_mfma_f32_16x16x32_bf16 v[110:113], v[192:195], v[160:163], v[110:113]
	v_mfma_f32_16x16x32_bf16 v[106:109], v[208:211], v[160:163], v[106:109]
	v_mfma_f32_16x16x32_bf16 v[94:97], v[192:195], v[168:171], v[94:97]
	v_mfma_f32_16x16x32_bf16 v[90:93], v[208:211], v[168:171], v[90:93]
	v_mfma_f32_16x16x32_bf16 v[78:81], v[192:195], v[176:179], v[78:81]
	v_mfma_f32_16x16x32_bf16 v[74:77], v[208:211], v[176:179], v[74:77]
	v_mfma_f32_16x16x32_bf16 v[70:73], v[192:195], v[184:187], v[70:73]
	v_mfma_f32_16x16x32_bf16 v[66:69], v[208:211], v[184:187], v[66:69]
	v_mfma_f32_16x16x32_bf16 v[110:113], v[196:199], v[164:167], v[110:113]
	v_mfma_f32_16x16x32_bf16 v[106:109], v[212:215], v[164:167], v[106:109]
	v_mfma_f32_16x16x32_bf16 v[94:97], v[196:199], v[172:175], v[94:97]
	v_mfma_f32_16x16x32_bf16 v[90:93], v[212:215], v[172:175], v[90:93]
	v_mfma_f32_16x16x32_bf16 v[78:81], v[196:199], v[180:183], v[78:81]
	v_mfma_f32_16x16x32_bf16 v[74:77], v[212:215], v[180:183], v[74:77]
	v_mfma_f32_16x16x32_bf16 v[70:73], v[196:199], v[188:191], v[70:73]
	v_mfma_f32_16x16x32_bf16 v[66:69], v[212:215], v[188:191], v[66:69]
	s_setprio 0
	s_mov_b32 m0, s71
	s_barrier
	ds_read_b128 v[160:163], v143 offset:49152
	ds_read_b128 v[164:167], v143 offset:50176
	ds_read_b128 v[168:171], v143 offset:51200
	ds_read_b128 v[172:175], v143 offset:52224
	ds_read_b128 v[176:179], v143 offset:53248
	ds_read_b128 v[180:183], v143 offset:54272
	ds_read_b128 v[184:187], v143 offset:55296
	ds_read_b128 v[188:191], v143 offset:56320
	global_load_lds_dwordx4 v134, s[100:101]
	s_mov_b32 m0, s72
	s_nop 0
	global_load_lds_dwordx4 v132, s[100:101]
	s_waitcnt vmcnt(10)
	s_barrier
	s_waitcnt lgkmcnt(0)
	s_setprio 1
	v_mfma_f32_16x16x32_bf16 v[62:65], v[144:147], v[160:163], v[62:65]
	v_mfma_f32_16x16x32_bf16 v[58:61], v[152:155], v[160:163], v[58:61]
	v_mfma_f32_16x16x32_bf16 v[54:57], v[144:147], v[168:171], v[54:57]
	v_mfma_f32_16x16x32_bf16 v[50:53], v[152:155], v[168:171], v[50:53]
	v_mfma_f32_16x16x32_bf16 v[38:41], v[144:147], v[176:179], v[38:41]
	v_mfma_f32_16x16x32_bf16 v[34:37], v[152:155], v[176:179], v[34:37]
	v_mfma_f32_16x16x32_bf16 v[22:25], v[144:147], v[184:187], v[22:25]
	v_mfma_f32_16x16x32_bf16 v[18:21], v[152:155], v[184:187], v[18:21]
	v_mfma_f32_16x16x32_bf16 v[62:65], v[148:151], v[164:167], v[62:65]
	v_mfma_f32_16x16x32_bf16 v[58:61], v[156:159], v[164:167], v[58:61]
	v_mfma_f32_16x16x32_bf16 v[54:57], v[148:151], v[172:175], v[54:57]
	v_mfma_f32_16x16x32_bf16 v[50:53], v[156:159], v[172:175], v[50:53]
	v_mfma_f32_16x16x32_bf16 v[38:41], v[148:151], v[180:183], v[38:41]
	v_mfma_f32_16x16x32_bf16 v[34:37], v[156:159], v[180:183], v[34:37]
	v_mfma_f32_16x16x32_bf16 v[22:25], v[148:151], v[188:191], v[22:25]
	v_mfma_f32_16x16x32_bf16 v[18:21], v[156:159], v[188:191], v[18:21]
	s_setprio 0
	s_barrier
	ds_read_b128 v[144:147], v202
	ds_read_b128 v[148:151], v202 offset:1024
	ds_read_b128 v[152:155], v202 offset:2048
	ds_read_b128 v[156:159], v202 offset:3072
	s_add_u32 s56, s56, 0x80080
	s_addc_u32 s57, s57, 0
	s_add_i32 s58, s58, s64
	s_mov_b32 m0, s58
	s_nop 0
	global_load_lds_dwordx4 v0, s[56:57]
	s_add_i32 m0, s58, 0x2000
	s_nop 0
	global_load_lds_dwordx4 v130, s[56:57]
	s_waitcnt vmcnt(6)
	s_barrier
	s_setprio 1
	v_mfma_f32_16x16x32_bf16 v[46:49], v[192:195], v[160:163], v[46:49]
	v_mfma_f32_16x16x32_bf16 v[42:45], v[208:211], v[160:163], v[42:45]
	v_mfma_f32_16x16x32_bf16 v[30:33], v[192:195], v[168:171], v[30:33]
	v_mfma_f32_16x16x32_bf16 v[26:29], v[208:211], v[168:171], v[26:29]
	v_mfma_f32_16x16x32_bf16 v[14:17], v[192:195], v[176:179], v[14:17]
	v_mfma_f32_16x16x32_bf16 v[10:13], v[208:211], v[176:179], v[10:13]
	v_mfma_f32_16x16x32_bf16 v[6:9], v[192:195], v[184:187], v[6:9]
	v_mfma_f32_16x16x32_bf16 v[2:5], v[208:211], v[184:187], v[2:5]
	v_mfma_f32_16x16x32_bf16 v[46:49], v[196:199], v[164:167], v[46:49]
	v_mfma_f32_16x16x32_bf16 v[42:45], v[212:215], v[164:167], v[42:45]
	v_mfma_f32_16x16x32_bf16 v[30:33], v[196:199], v[172:175], v[30:33]
	v_mfma_f32_16x16x32_bf16 v[26:29], v[212:215], v[172:175], v[26:29]
	v_mfma_f32_16x16x32_bf16 v[14:17], v[196:199], v[180:183], v[14:17]
	v_mfma_f32_16x16x32_bf16 v[10:13], v[212:215], v[180:183], v[10:13]
	v_mfma_f32_16x16x32_bf16 v[6:9], v[196:199], v[188:191], v[6:9]
	v_mfma_f32_16x16x32_bf16 v[2:5], v[212:215], v[188:191], v[2:5]
	s_setprio 0
	s_add_i32 s80, s80, 2
	s_add_u32 s54, s54, 0x100
	s_addc_u32 s55, s55, 0
	s_add_u32 s78, s78, 0x100
	s_addc_u32 s79, s79, 0
	s_cmp_gt_u32 s80, 29
	s_barrier
; __device__ __forceinline__ unsigned pk2(float lo, float hi) { f32x2 v = {lo, hi}; bf16x2_t b = __builtin_convertvector(v, bf16x2_t); return __builtin_bit_cast(unsigned, b); }
; #define PG8_WAIT_V(n) asm volatile("s_waitcnt vmcnt(" #n ")" ::: "memory")
; #define PG8_BAR __builtin_amdgcn_s_barrier()
;     __device__ __forceinline__ void operator()(const AccT& acc, const Unit& u, int wr, int wc, int fr, int fq) const {
;     ...
; #pragma unroll
;         for (int ai = 0; ai < 2; ++ai)
; #pragma unroll
;             for (int m = 0; m < 4; ++m) {
;                 const int row = row0 + ai * HALF + m * 16;
;                 const float rs = rsv[ai * 4 + m];
; #pragma unroll
;                 for (int bj = 0; bj < 2; ++bj) {
;                     const f32x4 v0 = acc[ai][bj][m][0] * rs, v1 = acc[ai][bj][m][1] * rs;
;                     u32x4 w; w.x = pk2(v0[0], v0[1]); w.y = pk2(v0[2], v0[3]); w.z = pk2(v1[0], v1[1]); w.w = pk2(v1[2], v1[3]);
;                     *(u32x4*)(out + (size_t)row * ldo + col0 + bj * HALF) = w;
;                 }
;             }
; template <class Epi>
; __device__ __forceinline__ void gemm_phase(LAS unsigned char* lds, const Gemm g, const StaticOrder& S, const Epi& E) {
;     ...
;         E(acc, cur, wr, wc, fr, fq);
;         if (!has_next) break;
; #pragma unroll
;         for (int a = 0; a < 2; ++a)
; #pragma unroll
;             for (int b = 0; b < 2; ++b)
; #pragma unroll
;                 for (int m = 0; m < 4; ++m)
; #pragma unroll
;                     for (int n = 0; n < 2; ++n) acc[a][b][m][n] = (f32x4){0.f, 0.f, 0.f, 0.f};
;         cur = nxt; cA = nA; cB = nB; ++ui;
;     }
;     PG8_WAIT_V(0);
;     if (wr == 0) PG8_BAR;
;     PG8_BAR;
	s_cbranch_scc0 .LBB0_77
	s_waitcnt lgkmcnt(0)
	v_lshl_add_u32 v146, s74, 8, v140
	v_lshl_or_b32 v144, s75, 8, v142
	v_ashrrev_i32_e32 v147, 31, v146
	v_ashrrev_i32_e32 v145, 31, v144
	v_cvt_pk_bf16_f32 v126, v126, v127
	v_cvt_pk_bf16_f32 v127, v128, v129
	v_cvt_pk_bf16_f32 v128, v122, v123
	v_lshlrev_b64 v[122:123], 11, v[146:147]
	v_cvt_pk_bf16_f32 v129, v124, v125
	v_lshl_add_u64 v[122:123], s[42:43], 0, v[122:123]
	v_lshlrev_b64 v[124:125], 1, v[144:145]
	v_lshl_add_u64 v[122:123], v[122:123], 0, v[124:125]
	v_cvt_pk_bf16_f32 v110, v110, v111
	v_cvt_pk_bf16_f32 v111, v112, v113
	v_cvt_pk_bf16_f32 v112, v106, v107
	v_cvt_pk_bf16_f32 v113, v108, v109
	global_store_dwordx4 v[122:123], v[110:113], off offset:256
	v_cvt_pk_bf16_f32 v94, v94, v95
	v_cvt_pk_bf16_f32 v95, v96, v97
	v_or_b32_e32 v110, 16, v146
	v_ashrrev_i32_e32 v111, 31, v110
	v_lshlrev_b64 v[110:111], 11, v[110:111]
	v_lshl_add_u64 v[110:111], s[42:43], 0, v[110:111]
	v_lshl_add_u64 v[110:111], v[110:111], 0, v[124:125]
	v_cvt_pk_bf16_f32 v96, v90, v91
	v_cvt_pk_bf16_f32 v97, v92, v93
	global_store_dwordx4 v[110:111], v[94:97], off offset:256
	s_mov_b32 s47, 0x40000
	v_cvt_pk_bf16_f32 v62, v62, v63
	v_or_b32_e32 v94, 32, v146
	v_ashrrev_i32_e32 v95, 31, v94
	v_cvt_pk_bf16_f32 v63, v64, v65
	v_cvt_pk_bf16_f32 v65, v60, v61
	s_mov_b64 s[54:55], 0x40000
	v_add_co_u32_e32 v60, vcc, s47, v122
	v_lshlrev_b64 v[94:95], 11, v[94:95]
	v_cvt_pk_bf16_f32 v64, v58, v59
	v_lshl_add_u64 v[58:59], v[122:123], 0, s[54:55]
	v_addc_co_u32_e32 v61, vcc, 0, v123, vcc
	v_cvt_pk_bf16_f32 v46, v46, v47
	v_cvt_pk_bf16_f32 v47, v48, v49
	v_cvt_pk_bf16_f32 v48, v42, v43
	v_cvt_pk_bf16_f32 v49, v44, v45
	s_mov_b32 s47, 0x48000
	v_lshl_add_u64 v[94:95], s[42:43], 0, v[94:95]
	global_store_dwordx4 v[58:59], v[46:49], off offset:256
	s_mov_b64 s[54:55], 0x48000
	v_lshl_add_u64 v[94:95], v[94:95], 0, v[124:125]
	v_add_co_u32_e32 v48, vcc, s47, v122
	v_cvt_pk_bf16_f32 v78, v78, v79
	v_cvt_pk_bf16_f32 v79, v80, v81
	v_cvt_pk_bf16_f32 v80, v74, v75
	v_cvt_pk_bf16_f32 v81, v76, v77
	v_lshl_add_u64 v[46:47], v[122:123], 0, s[54:55]
	v_addc_co_u32_e32 v49, vcc, 0, v123, vcc
	v_cvt_pk_bf16_f32 v30, v30, v31
	v_cvt_pk_bf16_f32 v31, v32, v33
	v_cvt_pk_bf16_f32 v32, v26, v27
	v_cvt_pk_bf16_f32 v33, v28, v29
	s_mov_b32 s47, 0x50000
	global_store_dwordx4 v[94:95], v[78:81], off offset:256
	global_store_dwordx4 v[46:47], v[30:33], off offset:256
	s_mov_b64 s[54:55], 0x50000
	v_or_b32_e32 v78, 48, v146
	v_add_co_u32_e32 v32, vcc, s47, v122
	v_ashrrev_i32_e32 v79, 31, v78
	v_lshl_add_u64 v[30:31], v[122:123], 0, s[54:55]
	v_addc_co_u32_e32 v33, vcc, 0, v123, vcc
	v_cvt_pk_bf16_f32 v14, v14, v15
	v_cvt_pk_bf16_f32 v15, v16, v17
	v_cvt_pk_bf16_f32 v16, v10, v11
	v_cvt_pk_bf16_f32 v17, v12, v13
	s_mov_b32 s47, 0x58000
	v_lshlrev_b64 v[78:79], 11, v[78:79]
	global_store_dwordx4 v[30:31], v[14:17], off offset:256
	v_lshl_add_u64 v[78:79], s[42:43], 0, v[78:79]
	s_mov_b64 s[54:55], 0x58000
	v_add_co_u32_e32 v16, vcc, s47, v122
	v_cvt_pk_bf16_f32 v106, v118, v119
	s_nop 0
	v_addc_co_u32_e32 v17, vcc, 0, v123, vcc
	v_cvt_pk_bf16_f32 v107, v120, v121
	v_cvt_pk_bf16_f32 v108, v114, v115
	v_cvt_pk_bf16_f32 v109, v116, v117
	v_cvt_pk_bf16_f32 v90, v102, v103
	v_cvt_pk_bf16_f32 v91, v104, v105
	v_cvt_pk_bf16_f32 v92, v98, v99
	v_cvt_pk_bf16_f32 v93, v100, v101
	v_cvt_pk_bf16_f32 v74, v86, v87
	v_cvt_pk_bf16_f32 v75, v88, v89
	v_cvt_pk_bf16_f32 v76, v82, v83
	v_cvt_pk_bf16_f32 v77, v84, v85
	v_lshl_add_u64 v[78:79], v[78:79], 0, v[124:125]
	v_cvt_pk_bf16_f32 v70, v70, v71
	v_cvt_pk_bf16_f32 v71, v72, v73
	v_cvt_pk_bf16_f32 v72, v66, v67
	v_cvt_pk_bf16_f32 v73, v68, v69
	v_cvt_pk_bf16_f32 v42, v54, v55
	v_cvt_pk_bf16_f32 v43, v56, v57
	v_cvt_pk_bf16_f32 v44, v50, v51
	v_cvt_pk_bf16_f32 v45, v52, v53
	v_cvt_pk_bf16_f32 v26, v38, v39
	v_cvt_pk_bf16_f32 v27, v40, v41
	v_cvt_pk_bf16_f32 v28, v34, v35
	v_cvt_pk_bf16_f32 v29, v36, v37
	v_cvt_pk_bf16_f32 v10, v22, v23
	v_cvt_pk_bf16_f32 v11, v24, v25
	v_cvt_pk_bf16_f32 v12, v18, v19
	v_cvt_pk_bf16_f32 v13, v20, v21
	v_lshl_add_u64 v[14:15], v[122:123], 0, s[54:55]
	v_cvt_pk_bf16_f32 v6, v6, v7
	v_cvt_pk_bf16_f32 v7, v8, v9
	v_cvt_pk_bf16_f32 v8, v2, v3
	v_cvt_pk_bf16_f32 v9, v4, v5
	s_and_b64 vcc, exec, s[44:45]
	s_mov_b32 s75, s46
	s_mov_b32 s74, s48
	s_mov_b64 s[56:57], s[52:53]
	s_mov_b64 s[54:55], s[50:51]
	global_store_dwordx4 v[122:123], v[126:129], off
	global_store_dwordx4 v[110:111], v[106:109], off
	global_store_dwordx4 v[94:95], v[90:93], off
	global_store_dwordx4 v[78:79], v[74:77], off
	global_store_dwordx4 v[78:79], v[70:73], off offset:256
	global_store_dwordx4 v[60:61], v[62:65], off
	global_store_dwordx4 v[48:49], v[42:45], off
	global_store_dwordx4 v[32:33], v[26:29], off
	global_store_dwordx4 v[16:17], v[10:13], off
	global_store_dwordx4 v[14:15], v[6:9], off offset:256
	s_cbranch_vccz .LBB0_74
	s_waitcnt vmcnt(0)
	s_cmpk_gt_u32 s60, 0xff
	s_cbranch_scc1 .LBB0_81
	s_barrier

; #define PG8_STAGE(bufoff, gbase, voff) do { _Pragma("unroll") for (int _i = 0; _i < 2; ++_i) \
;         __builtin_amdgcn_global_load_lds((const unsigned*)((const char*)(gbase) + (voff)[_i]), (LAS unsigned*)(lds + (bufoff) + ldsw + _i * 8192), 16, 0, 0); } while (0)
; #define PG8_LDA(dst, b, h) do { _Pragma("unroll") for (int m = 0; m < 4; ++m) _Pragma("unroll") for (int k = 0; k < 2; ++k) dst[m][k] = *(const LAS bf16x8*)(lds + PG8_SA(b, h) + aoff + m * 2048 + k * 1024); } while (0)
; #define PG8_LDB(dst, b, h) do { _Pragma("unroll") for (int n = 0; n < 2; ++n) _Pragma("unroll") for (int k = 0; k < 2; ++k) dst[n][k] = *(const LAS bf16x8*)(lds + PG8_SB(b, h) + boff + n * 2048 + k * 1024); } while (0)
; #define PG8_SCHED __builtin_amdgcn_sched_barrier(0)
; template <class Epi>
; __device__ __forceinline__ void gemm_phase(LAS unsigned char* lds, const Gemm g, const StaticOrder& S, const Epi& E) {
;     ...
;         const bool has_next = S.next(ui + 1, nxt);
;         const char* nA = has_next ? (const char*)g.A + (size_t)nxt.pm * tstep : cA; const char* nB = has_next ? (const char*)g.Bt + (size_t)nxt.pn * tstep : cB;
;         for (int t = 0; t < nt; t += 2) {
;             const bool last = (t == nt - 2);
;             const char* a1 = cA + (size_t)(t + 1) * kstep;
;             const char* a2 = last ? nA : cA + (size_t)(t + 2) * kstep; const char* b2 = last ? nB : cB + (size_t)(t + 2) * kstep;
;             const char* a3 = a2 + kstep; const char* b3 = b2 + kstep;
;             PG8_LDB(B0, 0, 0); PG8_SCHED; PG8_LDA(At, 0, 0); PG8_STAGE(PG8_SA(1, 1), a1 + hstep, voffA);
;     ...
;         for (int a = 0; a < 2; ++a)
; #pragma unroll
;             for (int b = 0; b < 2; ++b)
; #pragma unroll
;                 for (int m = 0; m < 4; ++m)
; #pragma unroll
;                     for (int n = 0; n < 2; ++n) acc[a][b][m][n] = (f32x4){0.f, 0.f, 0.f, 0.f};
;         cur = nxt; cA = nA; cB = nB; ++ui;
.LBB0_89:
	v_mov_b64_e32 v[2:3], 0x580
	s_ashr_i32 s41, s40, 31
	v_cmp_lt_i64_e32 vcc, s[42:43], v[2:3]
	s_lshl_b64 s[42:43], s[40:41], 20
	v_readlane_b32 s44, v254, 8
	v_readlane_b32 s45, v254, 9
	s_add_u32 s42, s44, s42
	s_addc_u32 s43, s45, s43
	s_and_b64 s[44:45], vcc, exec
	s_cselect_b32 s41, s43, s47
	s_cselect_b32 s69, s42, s46
	s_ashr_i32 s39, s38, 31
	s_lshl_b64 s[44:45], s[38:39], 20
	s_add_u32 s44, s53, s44
	s_addc_u32 s45, s54, s45
	s_and_b64 s[50:51], vcc, exec
	s_cselect_b32 s39, s45, s49
	s_cselect_b32 s70, s44, s48
	s_add_u32 s46, s46, 0x80080
	s_addc_u32 s47, s47, 0
	s_add_u32 s71, s48, 0x100
	v_mov_b32_e32 v2, 0
	s_addc_u32 s72, s49, 0
	s_mov_b32 s73, -2
	v_mov_b32_e32 v3, v2
	v_mov_b32_e32 v4, v2
	v_mov_b32_e32 v5, v2
	v_mov_b32_e32 v10, v2
	v_mov_b32_e32 v11, v2
	v_mov_b32_e32 v12, v2
	v_mov_b32_e32 v13, v2
	v_mov_b32_e32 v18, v2
	v_mov_b32_e32 v19, v2
	v_mov_b32_e32 v20, v2
	v_mov_b32_e32 v21, v2
	s_waitcnt vmcnt(0)
	v_mov_b32_e32 v26, v2
	v_mov_b32_e32 v27, v2
	v_mov_b32_e32 v28, v2
	v_mov_b32_e32 v29, v2
	v_mov_b32_e32 v34, v2
	v_mov_b32_e32 v35, v2
	v_mov_b32_e32 v36, v2
	v_mov_b32_e32 v37, v2
	v_mov_b32_e32 v42, v2
	v_mov_b32_e32 v43, v2
	v_mov_b32_e32 v44, v2
	v_mov_b32_e32 v45, v2
	v_mov_b32_e32 v50, v2
	v_mov_b32_e32 v51, v2
	v_mov_b32_e32 v52, v2
	v_mov_b32_e32 v53, v2
	v_mov_b32_e32 v58, v2
	v_mov_b32_e32 v59, v2
	v_mov_b32_e32 v60, v2
	v_mov_b32_e32 v61, v2
	v_mov_b32_e32 v6, v2
	v_mov_b32_e32 v7, v2
	v_mov_b32_e32 v8, v2
	v_mov_b32_e32 v9, v2
	v_mov_b32_e32 v14, v2
	v_mov_b32_e32 v15, v2
	v_mov_b32_e32 v16, v2
	v_mov_b32_e32 v17, v2
	v_mov_b32_e32 v22, v2
	v_mov_b32_e32 v23, v2
	v_mov_b32_e32 v24, v2
	v_mov_b32_e32 v25, v2
	v_mov_b32_e32 v30, v2
	v_mov_b32_e32 v31, v2
	v_mov_b32_e32 v32, v2
	v_mov_b32_e32 v33, v2
	v_mov_b32_e32 v38, v2
	v_mov_b32_e32 v39, v2
	v_mov_b32_e32 v40, v2
	v_mov_b32_e32 v41, v2
	v_mov_b32_e32 v46, v2
	v_mov_b32_e32 v47, v2
	v_mov_b32_e32 v48, v2
	v_mov_b32_e32 v49, v2
	v_mov_b32_e32 v54, v2
	v_mov_b32_e32 v55, v2
	v_mov_b32_e32 v56, v2
	v_mov_b32_e32 v57, v2
	v_mov_b32_e32 v62, v2
	v_mov_b32_e32 v63, v2
	v_mov_b32_e32 v64, v2
	v_mov_b32_e32 v65, v2
	v_mov_b32_e32 v66, v2
	v_mov_b32_e32 v67, v2
	v_mov_b32_e32 v68, v2
	v_mov_b32_e32 v69, v2
	v_mov_b32_e32 v74, v2
	v_mov_b32_e32 v75, v2
	v_mov_b32_e32 v76, v2
	v_mov_b32_e32 v77, v2
	v_mov_b32_e32 v82, v2
	v_mov_b32_e32 v83, v2
	v_mov_b32_e32 v84, v2
	v_mov_b32_e32 v85, v2
	v_mov_b32_e32 v90, v2
	v_mov_b32_e32 v91, v2
	v_mov_b32_e32 v92, v2
	v_mov_b32_e32 v93, v2
	v_mov_b32_e32 v98, v2
	v_mov_b32_e32 v99, v2
	v_mov_b32_e32 v100, v2
	v_mov_b32_e32 v101, v2
	v_mov_b32_e32 v106, v2
	v_mov_b32_e32 v107, v2
	v_mov_b32_e32 v108, v2
	v_mov_b32_e32 v109, v2
	v_mov_b32_e32 v114, v2
	v_mov_b32_e32 v115, v2
	v_mov_b32_e32 v116, v2
	v_mov_b32_e32 v117, v2
	v_mov_b32_e32 v118, v2
	v_mov_b32_e32 v119, v2
	v_mov_b32_e32 v120, v2
	v_mov_b32_e32 v121, v2
	v_mov_b32_e32 v70, v2
	v_mov_b32_e32 v71, v2
	v_mov_b32_e32 v72, v2
	v_mov_b32_e32 v73, v2
	v_mov_b32_e32 v78, v2
	v_mov_b32_e32 v79, v2
	v_mov_b32_e32 v80, v2
	v_mov_b32_e32 v81, v2
	v_mov_b32_e32 v86, v2
	v_mov_b32_e32 v87, v2
	v_mov_b32_e32 v88, v2
	v_mov_b32_e32 v89, v2
	v_mov_b32_e32 v94, v2
	v_mov_b32_e32 v95, v2
	v_mov_b32_e32 v96, v2
	v_mov_b32_e32 v97, v2
	v_mov_b32_e32 v102, v2
	v_mov_b32_e32 v103, v2
	v_mov_b32_e32 v104, v2
	v_mov_b32_e32 v105, v2
	v_mov_b32_e32 v110, v2
	v_mov_b32_e32 v111, v2
	v_mov_b32_e32 v112, v2
	v_mov_b32_e32 v113, v2
	v_mov_b32_e32 v122, v2
	v_mov_b32_e32 v123, v2
	v_mov_b32_e32 v124, v2
	v_mov_b32_e32 v125, v2
	v_mov_b32_e32 v126, v2
	v_mov_b32_e32 v127, v2
	v_mov_b32_e32 v128, v2
	v_mov_b32_e32 v129, v2
	v_add_u32_e32 v200, 0x10000, v143
	ds_read_b128 v[152:155], v200
	ds_read_b128 v[156:159], v200 offset:1024
	ds_read_b128 v[160:163], v200 offset:2048
	ds_read_b128 v[164:167], v200 offset:3072
.LBB0_90:
	s_add_u32 s48, s46, 0xfff80080
	s_addc_u32 s49, s47, -1
	s_add_i32 s74, 0, 0x10000
	s_cmp_eq_u32 s73, 28
	s_cselect_b32 s51, s41, s49
	s_cselect_b32 s50, s69, s48
	s_cselect_b32 s49, s39, s72
	s_cselect_b32 s48, s70, s71
	s_add_i32 m0, s56, 0xc000
	ds_read_b128 v[168:171], v151
	ds_read_b128 v[172:175], v151 offset:1024
	ds_read_b128 v[176:179], v151 offset:2048
	ds_read_b128 v[180:183], v151 offset:3072
	ds_read_b128 v[184:187], v151 offset:4096
	ds_read_b128 v[188:191], v151 offset:5120
	ds_read_b128 v[192:195], v151 offset:6144
	ds_read_b128 v[196:199], v151 offset:7168
	global_load_lds_dwordx4 v136, s[46:47]
	s_add_i32 m0, s56, 0xe000
	s_nop 0
	global_load_lds_dwordx4 v138, s[46:47]
	s_waitcnt lgkmcnt(8)
	s_barrier
	s_waitcnt lgkmcnt(0)
	s_setprio 1
	v_mfma_f32_16x16x32_bf16 v[126:129], v[152:155], v[168:171], v[126:129]
	v_mfma_f32_16x16x32_bf16 v[122:125], v[160:163], v[168:171], v[122:125]
	v_mfma_f32_16x16x32_bf16 v[110:113], v[152:155], v[176:179], v[110:113]
	v_mfma_f32_16x16x32_bf16 v[102:105], v[160:163], v[176:179], v[102:105]
	v_mfma_f32_16x16x32_bf16 v[94:97], v[152:155], v[184:187], v[94:97]
	v_mfma_f32_16x16x32_bf16 v[86:89], v[160:163], v[184:187], v[86:89]
	v_mfma_f32_16x16x32_bf16 v[78:81], v[152:155], v[192:195], v[78:81]
	v_mfma_f32_16x16x32_bf16 v[70:73], v[160:163], v[192:195], v[70:73]
	v_mfma_f32_16x16x32_bf16 v[126:129], v[156:159], v[172:175], v[126:129]
	v_mfma_f32_16x16x32_bf16 v[122:125], v[164:167], v[172:175], v[122:125]
	v_mfma_f32_16x16x32_bf16 v[110:113], v[156:159], v[180:183], v[110:113]
	v_mfma_f32_16x16x32_bf16 v[102:105], v[164:167], v[180:183], v[102:105]
	v_mfma_f32_16x16x32_bf16 v[94:97], v[156:159], v[188:191], v[94:97]
	v_mfma_f32_16x16x32_bf16 v[86:89], v[164:167], v[188:191], v[86:89]
	v_mfma_f32_16x16x32_bf16 v[78:81], v[156:159], v[196:199], v[78:81]
	v_mfma_f32_16x16x32_bf16 v[70:73], v[164:167], v[196:199], v[70:73]
	s_setprio 0
	s_barrier
; #define PG8_STAGE(bufoff, gbase, voff) do { _Pragma("unroll") for (int _i = 0; _i < 2; ++_i) \
;         __builtin_amdgcn_global_load_lds((const unsigned*)((const char*)(gbase) + (voff)[_i]), (LAS unsigned*)(lds + (bufoff) + ldsw + _i * 8192), 16, 0, 0); } while (0)
; #define PG8_LDA(dst, b, h) do { _Pragma("unroll") for (int m = 0; m < 4; ++m) _Pragma("unroll") for (int k = 0; k < 2; ++k) dst[m][k] = *(const LAS bf16x8*)(lds + PG8_SA(b, h) + aoff + m * 2048 + k * 1024); } while (0)
; #define PG8_LDB(dst, b, h) do { _Pragma("unroll") for (int n = 0; n < 2; ++n) _Pragma("unroll") for (int k = 0; k < 2; ++k) dst[n][k] = *(const LAS bf16x8*)(lds + PG8_SB(b, h) + boff + n * 2048 + k * 1024); } while (0)
; #define PG8_MMA(ai, bj, At, Bt) do { __builtin_amdgcn_s_setprio(1); _Pragma("unroll") for (int m = 0; m < 4; ++m) _Pragma("unroll") for (int n = 0; n < 2; ++n) _Pragma("unroll") for (int k = 0; k < 2; ++k) \
;         acc[ai][bj][m][n] = __builtin_amdgcn_mfma_f32_16x16x32_bf16(Bt[n][k], At[m][k], acc[ai][bj][m][n], 0, 0, 0); __builtin_amdgcn_s_setprio(0); } while (0)
; #define PG8_WAIT_V(n) asm volatile("s_waitcnt vmcnt(" #n ")" ::: "memory")
; #define PG8_WAIT_L(n) asm volatile("s_waitcnt lgkmcnt(" #n ")" ::: "memory")
; #define PG8_BAR __builtin_amdgcn_s_barrier()
; #define PG8_SCHED __builtin_amdgcn_sched_barrier(0)
; template <class Epi>
; __device__ __forceinline__ void gemm_phase(LAS unsigned char* lds, const Gemm g, const StaticOrder& S, const Epi& E) {
;     ...
;             PG8_LDB(B1, 0, 1); PG8_STAGE(PG8_SB(0, 0), b2, voffB);
;             PG8_BAR; PG8_WAIT_L(0); PG8_MMA(0, 1, At, B1); PG8_BAR;
;             PG8_LDA(At, 0, 1); PG8_STAGE(PG8_SA(0, 0), a2, voffA);
;             PG8_BAR; PG8_WAIT_L(0); PG8_MMA(1, 0, At, B0); PG8_BAR; PG8_SCHED;
;             PG8_STAGE(PG8_SB(0, 1), b2 + hstep, voffB);
;             PG8_WAIT_V(6); PG8_BAR; PG8_MMA(1, 1, At, B1); PG8_BAR;
;             PG8_LDB(B0, 1, 0); PG8_SCHED; PG8_LDA(At, 1, 0); PG8_STAGE(PG8_SA(0, 1), a2 + hstep, voffA);
;             PG8_WAIT_L(8); PG8_BAR; PG8_WAIT_L(0); PG8_MMA(0, 0, At, B0); PG8_BAR; PG8_SCHED;
	s_add_i32 s76, 0, 0x14000
	s_add_i32 s74, s74, s55
	s_mov_b32 m0, s74
	ds_read_b128 v[208:211], v200 offset:16384
	ds_read_b128 v[212:215], v200 offset:17408
	ds_read_b128 v[216:219], v200 offset:18432
	ds_read_b128 v[220:223], v200 offset:19456
	global_load_lds_dwordx4 v0, s[48:49]
	s_add_i32 m0, s74, 0x2000
	s_add_u32 s98, s48, s22
	global_load_lds_dwordx4 v130, s[48:49]
	s_addc_u32 s99, s49, s23
	s_barrier
	s_waitcnt lgkmcnt(0)
	s_setprio 1
	v_mfma_f32_16x16x32_bf16 v[118:121], v[208:211], v[168:171], v[118:121]
	v_mfma_f32_16x16x32_bf16 v[114:117], v[216:219], v[168:171], v[114:117]
	v_mfma_f32_16x16x32_bf16 v[106:109], v[208:211], v[176:179], v[106:109]
	v_mfma_f32_16x16x32_bf16 v[98:101], v[216:219], v[176:179], v[98:101]
	v_mfma_f32_16x16x32_bf16 v[90:93], v[208:211], v[184:187], v[90:93]
	v_mfma_f32_16x16x32_bf16 v[82:85], v[216:219], v[184:187], v[82:85]
	v_mfma_f32_16x16x32_bf16 v[74:77], v[208:211], v[192:195], v[74:77]
	v_mfma_f32_16x16x32_bf16 v[66:69], v[216:219], v[192:195], v[66:69]
	v_mfma_f32_16x16x32_bf16 v[118:121], v[212:215], v[172:175], v[118:121]
	v_mfma_f32_16x16x32_bf16 v[114:117], v[220:223], v[172:175], v[114:117]
	v_mfma_f32_16x16x32_bf16 v[106:109], v[212:215], v[180:183], v[106:109]
	v_mfma_f32_16x16x32_bf16 v[98:101], v[220:223], v[180:183], v[98:101]
	v_mfma_f32_16x16x32_bf16 v[90:93], v[212:215], v[188:191], v[90:93]
	v_mfma_f32_16x16x32_bf16 v[82:85], v[220:223], v[188:191], v[82:85]
	v_mfma_f32_16x16x32_bf16 v[74:77], v[212:215], v[196:199], v[74:77]
	v_mfma_f32_16x16x32_bf16 v[66:69], v[220:223], v[196:199], v[66:69]
	s_setprio 0
	s_mov_b32 m0, s56
	s_add_u32 s100, s50, s22
	s_addc_u32 s101, s51, s23
	s_barrier
	ds_read_b128 v[168:171], v151 offset:16384
	ds_read_b128 v[172:175], v151 offset:17408
	ds_read_b128 v[176:179], v151 offset:18432
	ds_read_b128 v[180:183], v151 offset:19456
	ds_read_b128 v[184:187], v151 offset:20480
	ds_read_b128 v[188:191], v151 offset:21504
	ds_read_b128 v[192:195], v151 offset:22528
	ds_read_b128 v[196:199], v151 offset:23552
	global_load_lds_dwordx4 v134, s[50:51]
	s_mov_b32 m0, s57
	s_nop 0
	global_load_lds_dwordx4 v132, s[50:51]
	s_waitcnt vmcnt(10)
	s_barrier
	s_waitcnt lgkmcnt(0)
	s_setprio 1
	v_mfma_f32_16x16x32_bf16 v[62:65], v[152:155], v[168:171], v[62:65]
	v_mfma_f32_16x16x32_bf16 v[54:57], v[160:163], v[168:171], v[54:57]
	v_mfma_f32_16x16x32_bf16 v[46:49], v[152:155], v[176:179], v[46:49]
	v_mfma_f32_16x16x32_bf16 v[38:41], v[160:163], v[176:179], v[38:41]
	v_mfma_f32_16x16x32_bf16 v[30:33], v[152:155], v[184:187], v[30:33]
	v_mfma_f32_16x16x32_bf16 v[22:25], v[160:163], v[184:187], v[22:25]
	v_mfma_f32_16x16x32_bf16 v[14:17], v[152:155], v[192:195], v[14:17]
	v_mfma_f32_16x16x32_bf16 v[6:9], v[160:163], v[192:195], v[6:9]
	v_mfma_f32_16x16x32_bf16 v[62:65], v[156:159], v[172:175], v[62:65]
	v_mfma_f32_16x16x32_bf16 v[54:57], v[164:167], v[172:175], v[54:57]
	v_mfma_f32_16x16x32_bf16 v[46:49], v[156:159], v[180:183], v[46:49]
	v_mfma_f32_16x16x32_bf16 v[38:41], v[164:167], v[180:183], v[38:41]
	v_mfma_f32_16x16x32_bf16 v[30:33], v[156:159], v[188:191], v[30:33]
	v_mfma_f32_16x16x32_bf16 v[22:25], v[164:167], v[188:191], v[22:25]
	v_mfma_f32_16x16x32_bf16 v[14:17], v[156:159], v[196:199], v[14:17]
	v_mfma_f32_16x16x32_bf16 v[6:9], v[164:167], v[196:199], v[6:9]
	s_setprio 0
	s_barrier
	ds_read_b128 v[152:155], v200 offset:32768
	ds_read_b128 v[156:159], v200 offset:33792
	ds_read_b128 v[160:163], v200 offset:34816
	ds_read_b128 v[164:167], v200 offset:35840
	s_add_u32 s74, s48, 0x80000
	s_addc_u32 s75, s49, 0
	s_add_i32 s76, s76, s55
	s_mov_b32 m0, s76
	s_nop 0
	global_load_lds_dwordx4 v0, s[74:75]
	s_add_i32 m0, s76, 0x2000
	s_nop 0
	global_load_lds_dwordx4 v130, s[74:75]
	s_waitcnt vmcnt(6)
	s_barrier
	s_setprio 1
	v_mfma_f32_16x16x32_bf16 v[58:61], v[208:211], v[168:171], v[58:61]
	v_mfma_f32_16x16x32_bf16 v[50:53], v[216:219], v[168:171], v[50:53]
	v_mfma_f32_16x16x32_bf16 v[42:45], v[208:211], v[176:179], v[42:45]
	v_mfma_f32_16x16x32_bf16 v[34:37], v[216:219], v[176:179], v[34:37]
	v_mfma_f32_16x16x32_bf16 v[26:29], v[208:211], v[184:187], v[26:29]
	v_mfma_f32_16x16x32_bf16 v[18:21], v[216:219], v[184:187], v[18:21]
	v_mfma_f32_16x16x32_bf16 v[10:13], v[208:211], v[192:195], v[10:13]
	v_mfma_f32_16x16x32_bf16 v[2:5], v[216:219], v[192:195], v[2:5]
	v_mfma_f32_16x16x32_bf16 v[58:61], v[212:215], v[172:175], v[58:61]
	v_mfma_f32_16x16x32_bf16 v[50:53], v[220:223], v[172:175], v[50:53]
	v_mfma_f32_16x16x32_bf16 v[42:45], v[212:215], v[180:183], v[42:45]
	v_mfma_f32_16x16x32_bf16 v[34:37], v[220:223], v[180:183], v[34:37]
	v_mfma_f32_16x16x32_bf16 v[26:29], v[212:215], v[188:191], v[26:29]
	v_mfma_f32_16x16x32_bf16 v[18:21], v[220:223], v[188:191], v[18:21]
	v_mfma_f32_16x16x32_bf16 v[10:13], v[212:215], v[196:199], v[10:13]
	v_mfma_f32_16x16x32_bf16 v[2:5], v[220:223], v[196:199], v[2:5]
	s_setprio 0
	s_add_i32 s74, 0, 0x18000
	s_barrier
	s_add_u32 s50, s50, 0x80000
	s_addc_u32 s51, s51, 0
	s_mov_b32 m0, s58
	ds_read_b128 v[168:171], v151 offset:32768
	ds_read_b128 v[172:175], v151 offset:33792
	ds_read_b128 v[176:179], v151 offset:34816
	ds_read_b128 v[180:183], v151 offset:35840
	ds_read_b128 v[184:187], v151 offset:36864
	ds_read_b128 v[188:191], v151 offset:37888
	ds_read_b128 v[192:195], v151 offset:38912
	ds_read_b128 v[196:199], v151 offset:39936
	global_load_lds_dwordx4 v134, s[50:51]
	s_mov_b32 m0, s59
	s_nop 0
	global_load_lds_dwordx4 v132, s[50:51]
	s_waitcnt lgkmcnt(8)
	s_barrier
; #define PG8_STAGE(bufoff, gbase, voff) do { _Pragma("unroll") for (int _i = 0; _i < 2; ++_i) \
;         __builtin_amdgcn_global_load_lds((const unsigned*)((const char*)(gbase) + (voff)[_i]), (LAS unsigned*)(lds + (bufoff) + ldsw + _i * 8192), 16, 0, 0); } while (0)
; #define PG8_LDA(dst, b, h) do { _Pragma("unroll") for (int m = 0; m < 4; ++m) _Pragma("unroll") for (int k = 0; k < 2; ++k) dst[m][k] = *(const LAS bf16x8*)(lds + PG8_SA(b, h) + aoff + m * 2048 + k * 1024); } while (0)
; #define PG8_LDB(dst, b, h) do { _Pragma("unroll") for (int n = 0; n < 2; ++n) _Pragma("unroll") for (int k = 0; k < 2; ++k) dst[n][k] = *(const LAS bf16x8*)(lds + PG8_SB(b, h) + boff + n * 2048 + k * 1024); } while (0)
; #define PG8_MMA(ai, bj, At, Bt) do { __builtin_amdgcn_s_setprio(1); _Pragma("unroll") for (int m = 0; m < 4; ++m) _Pragma("unroll") for (int n = 0; n < 2; ++n) _Pragma("unroll") for (int k = 0; k < 2; ++k) \
;         acc[ai][bj][m][n] = __builtin_amdgcn_mfma_f32_16x16x32_bf16(Bt[n][k], At[m][k], acc[ai][bj][m][n], 0, 0, 0); __builtin_amdgcn_s_setprio(0); } while (0)
; #define PG8_WAIT_V(n) asm volatile("s_waitcnt vmcnt(" #n ")" ::: "memory")
; #define PG8_WAIT_L(n) asm volatile("s_waitcnt lgkmcnt(" #n ")" ::: "memory")
; #define PG8_BAR __builtin_amdgcn_s_barrier()
; #define PG8_SCHED __builtin_amdgcn_sched_barrier(0)
; template <class Epi>
; __device__ __forceinline__ void gemm_phase(LAS unsigned char* lds, const Gemm g, const StaticOrder& S, const Epi& E) {
;     ...
;             PG8_WAIT_L(8); PG8_BAR; PG8_WAIT_L(0); PG8_MMA(0, 0, At, B0); PG8_BAR; PG8_SCHED;
;             PG8_LDB(B1, 1, 1); PG8_STAGE(PG8_SB(1, 0), b3, voffB);
;             PG8_BAR; PG8_WAIT_L(0); PG8_MMA(0, 1, At, B1); PG8_BAR;
;             PG8_LDA(At, 1, 1); PG8_STAGE(PG8_SA(1, 0), a3, voffA);
;             PG8_BAR; PG8_WAIT_L(0); PG8_MMA(1, 0, At, B0); PG8_BAR; PG8_SCHED;
;             PG8_STAGE(PG8_SB(1, 1), b3 + hstep, voffB);
;             PG8_WAIT_V(6); PG8_BAR; PG8_MMA(1, 1, At, B1); PG8_BAR;
	s_waitcnt lgkmcnt(0)
	s_setprio 1
	v_mfma_f32_16x16x32_bf16 v[126:129], v[152:155], v[168:171], v[126:129]
	v_mfma_f32_16x16x32_bf16 v[122:125], v[160:163], v[168:171], v[122:125]
	v_mfma_f32_16x16x32_bf16 v[110:113], v[152:155], v[176:179], v[110:113]
	v_mfma_f32_16x16x32_bf16 v[102:105], v[160:163], v[176:179], v[102:105]
	v_mfma_f32_16x16x32_bf16 v[94:97], v[152:155], v[184:187], v[94:97]
	v_mfma_f32_16x16x32_bf16 v[86:89], v[160:163], v[184:187], v[86:89]
	v_mfma_f32_16x16x32_bf16 v[78:81], v[152:155], v[192:195], v[78:81]
	v_mfma_f32_16x16x32_bf16 v[70:73], v[160:163], v[192:195], v[70:73]
	v_mfma_f32_16x16x32_bf16 v[126:129], v[156:159], v[172:175], v[126:129]
	v_mfma_f32_16x16x32_bf16 v[122:125], v[164:167], v[172:175], v[122:125]
	v_mfma_f32_16x16x32_bf16 v[110:113], v[156:159], v[180:183], v[110:113]
	v_mfma_f32_16x16x32_bf16 v[102:105], v[164:167], v[180:183], v[102:105]
	v_mfma_f32_16x16x32_bf16 v[94:97], v[156:159], v[188:191], v[94:97]
	v_mfma_f32_16x16x32_bf16 v[86:89], v[164:167], v[188:191], v[86:89]
	v_mfma_f32_16x16x32_bf16 v[78:81], v[156:159], v[196:199], v[78:81]
	v_mfma_f32_16x16x32_bf16 v[70:73], v[164:167], v[196:199], v[70:73]
	s_setprio 0
	s_barrier
	s_add_i32 s50, 0, 0x1c000
	s_add_i32 s51, s74, s55
	s_mov_b32 m0, s51
	ds_read_b128 v[208:211], v200 offset:49152
	ds_read_b128 v[212:215], v200 offset:50176
	ds_read_b128 v[216:219], v200 offset:51200
	ds_read_b128 v[220:223], v200 offset:52224
	global_load_lds_dwordx4 v0, s[98:99]
	s_add_i32 m0, s51, 0x2000
	s_nop 0
	global_load_lds_dwordx4 v130, s[98:99]
	s_barrier
	s_waitcnt lgkmcnt(0)
	s_setprio 1
	v_mfma_f32_16x16x32_bf16 v[118:121], v[208:211], v[168:171], v[118:121]
	v_mfma_f32_16x16x32_bf16 v[114:117], v[216:219], v[168:171], v[114:117]
	v_mfma_f32_16x16x32_bf16 v[106:109], v[208:211], v[176:179], v[106:109]
	v_mfma_f32_16x16x32_bf16 v[98:101], v[216:219], v[176:179], v[98:101]
	v_mfma_f32_16x16x32_bf16 v[90:93], v[208:211], v[184:187], v[90:93]
	v_mfma_f32_16x16x32_bf16 v[82:85], v[216:219], v[184:187], v[82:85]
	v_mfma_f32_16x16x32_bf16 v[74:77], v[208:211], v[192:195], v[74:77]
	v_mfma_f32_16x16x32_bf16 v[66:69], v[216:219], v[192:195], v[66:69]
	v_mfma_f32_16x16x32_bf16 v[118:121], v[212:215], v[172:175], v[118:121]
	v_mfma_f32_16x16x32_bf16 v[114:117], v[220:223], v[172:175], v[114:117]
	v_mfma_f32_16x16x32_bf16 v[106:109], v[212:215], v[180:183], v[106:109]
	v_mfma_f32_16x16x32_bf16 v[98:101], v[220:223], v[180:183], v[98:101]
	v_mfma_f32_16x16x32_bf16 v[90:93], v[212:215], v[188:191], v[90:93]
	v_mfma_f32_16x16x32_bf16 v[82:85], v[220:223], v[188:191], v[82:85]
	v_mfma_f32_16x16x32_bf16 v[74:77], v[212:215], v[196:199], v[74:77]
	v_mfma_f32_16x16x32_bf16 v[66:69], v[220:223], v[196:199], v[66:69]
	s_setprio 0
	s_mov_b32 m0, s61
	s_barrier
	ds_read_b128 v[168:171], v151 offset:49152
	ds_read_b128 v[172:175], v151 offset:50176
	ds_read_b128 v[176:179], v151 offset:51200
	ds_read_b128 v[180:183], v151 offset:52224
	ds_read_b128 v[184:187], v151 offset:53248
	ds_read_b128 v[188:191], v151 offset:54272
	ds_read_b128 v[192:195], v151 offset:55296
	ds_read_b128 v[196:199], v151 offset:56320
	global_load_lds_dwordx4 v134, s[100:101]
	s_mov_b32 m0, s63
	s_nop 0
	global_load_lds_dwordx4 v132, s[100:101]
	s_waitcnt vmcnt(10)
	s_barrier
	s_waitcnt lgkmcnt(0)
	s_setprio 1
	v_mfma_f32_16x16x32_bf16 v[62:65], v[152:155], v[168:171], v[62:65]
	v_mfma_f32_16x16x32_bf16 v[54:57], v[160:163], v[168:171], v[54:57]
	v_mfma_f32_16x16x32_bf16 v[46:49], v[152:155], v[176:179], v[46:49]
	v_mfma_f32_16x16x32_bf16 v[38:41], v[160:163], v[176:179], v[38:41]
	v_mfma_f32_16x16x32_bf16 v[30:33], v[152:155], v[184:187], v[30:33]
	v_mfma_f32_16x16x32_bf16 v[22:25], v[160:163], v[184:187], v[22:25]
	v_mfma_f32_16x16x32_bf16 v[14:17], v[152:155], v[192:195], v[14:17]
	v_mfma_f32_16x16x32_bf16 v[6:9], v[160:163], v[192:195], v[6:9]
	v_mfma_f32_16x16x32_bf16 v[62:65], v[156:159], v[172:175], v[62:65]
	v_mfma_f32_16x16x32_bf16 v[54:57], v[164:167], v[172:175], v[54:57]
	v_mfma_f32_16x16x32_bf16 v[46:49], v[156:159], v[180:183], v[46:49]
	v_mfma_f32_16x16x32_bf16 v[38:41], v[164:167], v[180:183], v[38:41]
	v_mfma_f32_16x16x32_bf16 v[30:33], v[156:159], v[188:191], v[30:33]
	v_mfma_f32_16x16x32_bf16 v[22:25], v[164:167], v[188:191], v[22:25]
	v_mfma_f32_16x16x32_bf16 v[14:17], v[156:159], v[196:199], v[14:17]
	v_mfma_f32_16x16x32_bf16 v[6:9], v[164:167], v[196:199], v[6:9]
	s_setprio 0
	s_barrier
	ds_read_b128 v[152:155], v200
	ds_read_b128 v[156:159], v200 offset:1024
	ds_read_b128 v[160:163], v200 offset:2048
	ds_read_b128 v[164:167], v200 offset:3072
	s_add_u32 s48, s48, 0x80080
	s_addc_u32 s49, s49, 0
	s_add_i32 s50, s50, s55
	s_mov_b32 m0, s50
	s_nop 0
	global_load_lds_dwordx4 v0, s[48:49]
	s_add_i32 m0, s50, 0x2000
	s_nop 0
	global_load_lds_dwordx4 v130, s[48:49]
	s_waitcnt vmcnt(6)
	s_barrier
	s_setprio 1
	v_mfma_f32_16x16x32_bf16 v[58:61], v[208:211], v[168:171], v[58:61]
	v_mfma_f32_16x16x32_bf16 v[50:53], v[216:219], v[168:171], v[50:53]
	v_mfma_f32_16x16x32_bf16 v[42:45], v[208:211], v[176:179], v[42:45]
	v_mfma_f32_16x16x32_bf16 v[34:37], v[216:219], v[176:179], v[34:37]
	v_mfma_f32_16x16x32_bf16 v[26:29], v[208:211], v[184:187], v[26:29]
	v_mfma_f32_16x16x32_bf16 v[18:21], v[216:219], v[184:187], v[18:21]
	v_mfma_f32_16x16x32_bf16 v[10:13], v[208:211], v[192:195], v[10:13]
	v_mfma_f32_16x16x32_bf16 v[2:5], v[216:219], v[192:195], v[2:5]
	v_mfma_f32_16x16x32_bf16 v[58:61], v[212:215], v[172:175], v[58:61]
	v_mfma_f32_16x16x32_bf16 v[50:53], v[220:223], v[172:175], v[50:53]
	v_mfma_f32_16x16x32_bf16 v[42:45], v[212:215], v[180:183], v[42:45]
	v_mfma_f32_16x16x32_bf16 v[34:37], v[220:223], v[180:183], v[34:37]
	v_mfma_f32_16x16x32_bf16 v[26:29], v[212:215], v[188:191], v[26:29]
	v_mfma_f32_16x16x32_bf16 v[18:21], v[220:223], v[188:191], v[18:21]
	v_mfma_f32_16x16x32_bf16 v[10:13], v[212:215], v[196:199], v[10:13]
	v_mfma_f32_16x16x32_bf16 v[2:5], v[220:223], v[196:199], v[2:5]
	s_setprio 0
	s_add_i32 s73, s73, 2
	s_add_u32 s46, s46, 0x100
	s_addc_u32 s47, s47, 0
	s_add_u32 s71, s71, 0x100
	s_addc_u32 s72, s72, 0
	s_cmp_gt_u32 s73, 29
	s_barrier
; __device__ __forceinline__ unsigned pk2(float lo, float hi) { f32x2 v = {lo, hi}; bf16x2_t b = __builtin_convertvector(v, bf16x2_t); return __builtin_bit_cast(unsigned, b); }
;     __device__ __forceinline__ void operator()(const AccT& acc, const Unit& u, int wr, int wc, int fr, int fq) const {
;         const int row0 = u.pm * BM + wr * 64 + fr, col0 = u.pn * 128 + wc * 32 + 8 * fq;
;         float rsv[8];
;         {
;             const int ln = (fq << 4) | fr;
;             float sa = ss[u.pm * BM + wr * 64 + ln], sb = ss[u.pm * BM + HALF + wr * 64 + ln];
;             sa = __builtin_amdgcn_rsqf(sa * (1.0f / DM) + EPS); sb = __builtin_amdgcn_rsqf(sb * (1.0f / DM) + EPS);
; #pragma unroll
;             for (int m = 0; m < 4; ++m) { rsv[m] = __shfl(sa, 16 * m + fr); rsv[4 + m] = __shfl(sb, 16 * m + fr); }
;         }
; #pragma unroll
;         for (int ai = 0; ai < 2; ++ai)
; #pragma unroll
;             for (int m = 0; m < 4; ++m) {
;                 const int row = row0 + ai * HALF + m * 16;
;                 const float rs = rsv[ai * 4 + m];
;                 float v[8];
; #pragma unroll
;                 for (int n = 0; n < 2; ++n)
; #pragma unroll
;                     for (int j = 0; j < 4; ++j) {
;                         const float g = acc[ai][0][m][n][j] * rs, up = acc[ai][1][m][n][j] * rs;
;                         const float sg = __builtin_amdgcn_rcpf(1.0f + __builtin_amdgcn_exp2f(-g * LOG2E));
;                         v[4 * n + j] = g * sg * up;
;                     }
;                 u32x4 w; w.x = pk2(v[0], v[1]); w.y = pk2(v[2], v[3]); w.z = pk2(v[4], v[5]); w.w = pk2(v[6], v[7]);
;                 *(u32x4*)(mid + (size_t)row * FF + col0) = w;
	s_cbranch_scc0 .LBB0_90
	s_waitcnt lgkmcnt(0)
	s_lshl_b32 s39, s68, 8
	s_add_i32 s39, s39, s60
	v_or_b32_e32 v154, s39, v145
	v_ashrrev_i32_e32 v155, 31, v154
	v_lshl_add_u64 v[154:155], v[154:155], 2, s[2:3]
	global_load_dword v140, v[154:155], off
	v_add_u32_e32 v154, s39, v147
	v_ashrrev_i32_e32 v155, 31, v154
	v_lshl_add_u64 v[154:155], v[154:155], 2, s[2:3]
	global_load_dword v142, v[154:155], off
	v_readlane_b32 s46, v251, 58
	v_readlane_b32 s47, v251, 59
	v_or_b32_e32 v153, s39, v141
	s_movk_i32 s39, 0x2c00
	s_and_b64 vcc, exec, s[36:37]
	s_mov_b32 s68, s40
	s_mov_b64 s[48:49], s[44:45]
	s_waitcnt vmcnt(0)
	v_fmamk_f32 v140, v140, 0x3a000000, v233
	v_rsq_f32_e32 v140, v140
	v_fmamk_f32 v142, v142, 0x3a000000, v233
	v_rsq_f32_e32 v154, v142
	v_and_or_b32 v142, v234, 64, v141
	v_lshlrev_b32_e32 v155, 2, v142
	ds_bpermute_b32 v156, v155, v140
	ds_bpermute_b32 v152, v155, v140 offset:64
	ds_bpermute_b32 v146, v155, v154
	ds_bpermute_b32 v144, v155, v154 offset:64
	ds_bpermute_b32 v150, v155, v140 offset:128
	s_waitcnt lgkmcnt(0)
	v_pk_mul_f32 v[126:127], v[126:127], v[156:157] op_sel_hi:[1,0]
	ds_bpermute_b32 v142, v155, v154 offset:128
	v_mul_f32_e32 v157, 0xbfb8aa3b, v126
	v_exp_f32_e32 v157, v157
	ds_bpermute_b32 v148, v155, v140 offset:192
	ds_bpermute_b32 v140, v155, v154 offset:192
	v_lshl_or_b32 v154, s65, 7, v149
	v_add_f32_e32 v157, 1.0, v157
	v_rcp_f32_e32 v158, v157
	v_pk_mul_f32 v[118:119], v[118:119], v[156:157] op_sel_hi:[1,0]
	v_mul_f32_e32 v157, 0xbfb8aa3b, v127
	v_exp_f32_e32 v157, v157
	v_ashrrev_i32_e32 v155, 31, v154
	v_pk_mul_f32 v[110:111], v[110:111], v[152:153] op_sel_hi:[1,0]
	v_pk_mul_f32 v[106:107], v[106:107], v[152:153] op_sel_hi:[1,0]
	v_add_f32_e32 v157, 1.0, v157
	v_rcp_f32_e32 v159, v157
	v_pk_mul_f32 v[120:121], v[120:121], v[156:157] op_sel_hi:[1,0]
	v_pk_mul_f32 v[122:123], v[122:123], v[156:157] op_sel_hi:[1,0]
	v_pk_mul_f32 v[114:115], v[114:115], v[156:157] op_sel_hi:[1,0]
	v_pk_mul_f32 v[126:127], v[126:127], v[158:159]
	v_pk_mul_f32 v[116:117], v[116:117], v[156:157] op_sel_hi:[1,0]
	v_pk_mul_f32 v[118:119], v[118:119], v[126:127]
	v_pk_mul_f32 v[126:127], v[128:129], v[156:157] op_sel_hi:[1,0]
	v_pk_mul_f32 v[108:109], v[108:109], v[152:153] op_sel_hi:[1,0]
	v_mul_f32_e32 v128, 0xbfb8aa3b, v126
	v_mul_f32_e32 v129, 0xbfb8aa3b, v127
	v_exp_f32_e32 v128, v128
	v_exp_f32_e32 v129, v129
	v_pk_mul_f32 v[102:103], v[102:103], v[152:153] op_sel_hi:[1,0]
	v_pk_mul_f32 v[98:99], v[98:99], v[152:153] op_sel_hi:[1,0]
	v_add_f32_e32 v128, 1.0, v128
	v_add_f32_e32 v129, 1.0, v129
	v_rcp_f32_e32 v128, v128
	v_rcp_f32_e32 v129, v129
	v_pk_mul_f32 v[100:101], v[100:101], v[152:153] op_sel_hi:[1,0]
	v_pk_mul_f32 v[94:95], v[94:95], v[150:151] op_sel_hi:[1,0]
	v_pk_mul_f32 v[90:91], v[90:91], v[150:151] op_sel_hi:[1,0]
	v_pk_mul_f32 v[126:127], v[126:127], v[128:129]
	v_pk_mul_f32 v[92:93], v[92:93], v[150:151] op_sel_hi:[1,0]
	v_pk_mul_f32 v[120:121], v[120:121], v[126:127]
	v_mul_f32_e32 v126, 0xbfb8aa3b, v122
	v_mul_f32_e32 v127, 0xbfb8aa3b, v123
	v_exp_f32_e32 v126, v126
	v_exp_f32_e32 v127, v127
	v_pk_mul_f32 v[86:87], v[86:87], v[150:151] op_sel_hi:[1,0]
	v_pk_mul_f32 v[82:83], v[82:83], v[150:151] op_sel_hi:[1,0]
	v_add_f32_e32 v126, 1.0, v126
	v_add_f32_e32 v127, 1.0, v127
	v_rcp_f32_e32 v126, v126
	v_rcp_f32_e32 v127, v127
	v_pk_mul_f32 v[84:85], v[84:85], v[150:151] op_sel_hi:[1,0]
	s_waitcnt lgkmcnt(1)
	v_pk_mul_f32 v[78:79], v[78:79], v[148:149] op_sel_hi:[1,0]
	v_pk_mul_f32 v[74:75], v[74:75], v[148:149] op_sel_hi:[1,0]
	v_pk_mul_f32 v[122:123], v[122:123], v[126:127]
	v_pk_mul_f32 v[76:77], v[76:77], v[148:149] op_sel_hi:[1,0]
	v_pk_mul_f32 v[122:123], v[114:115], v[122:123]
	v_pk_mul_f32 v[114:115], v[124:125], v[156:157] op_sel_hi:[1,0]
	v_pk_mul_f32 v[70:71], v[70:71], v[148:149] op_sel_hi:[1,0]
	v_mul_f32_e32 v124, 0xbfb8aa3b, v114
	v_mul_f32_e32 v125, 0xbfb8aa3b, v115
	v_exp_f32_e32 v124, v124
	v_exp_f32_e32 v125, v125
	v_pk_mul_f32 v[66:67], v[66:67], v[148:149] op_sel_hi:[1,0]
	v_pk_mul_f32 v[68:69], v[68:69], v[148:149] op_sel_hi:[1,0]
	v_add_f32_e32 v124, 1.0, v124
	v_add_f32_e32 v125, 1.0, v125
	v_rcp_f32_e32 v124, v124
	v_rcp_f32_e32 v125, v125
	v_pk_mul_f32 v[62:63], v[62:63], v[146:147] op_sel_hi:[1,0]
	v_pk_mul_f32 v[58:59], v[58:59], v[146:147] op_sel_hi:[1,0]
	v_pk_mul_f32 v[60:61], v[60:61], v[146:147] op_sel_hi:[1,0]
	v_pk_mul_f32 v[114:115], v[114:115], v[124:125]
	v_pk_mul_f32 v[54:55], v[54:55], v[146:147] op_sel_hi:[1,0]
	v_pk_mul_f32 v[124:125], v[116:117], v[114:115]
	v_cvt_pk_bf16_f32 v114, v118, v119
	v_mov_b64_e32 v[118:119], s[46:47]
	v_cvt_pk_bf16_f32 v115, v120, v121
	v_cvt_pk_bf16_f32 v116, v122, v123
	v_mad_i64_i32 v[122:123], s[46:47], v153, s39, v[118:119]
	v_lshlrev_b64 v[120:121], 1, v[154:155]
	v_cvt_pk_bf16_f32 v117, v124, v125
	v_lshl_add_u64 v[122:123], v[122:123], 0, v[120:121]
	global_store_dwordx4 v[122:123], v[114:117], off
	v_pk_mul_f32 v[50:51], v[50:51], v[146:147] op_sel_hi:[1,0]
	v_pk_mul_f32 v[52:53], v[52:53], v[146:147] op_sel_hi:[1,0]
	v_mul_f32_e32 v114, 0xbfb8aa3b, v110
	v_mul_f32_e32 v115, 0xbfb8aa3b, v111
	v_exp_f32_e32 v114, v114
	v_exp_f32_e32 v115, v115
	v_pk_mul_f32 v[46:47], v[46:47], v[144:145] op_sel_hi:[1,0]
	v_pk_mul_f32 v[42:43], v[42:43], v[144:145] op_sel_hi:[1,0]
	v_add_f32_e32 v114, 1.0, v114
	v_add_f32_e32 v115, 1.0, v115
	v_rcp_f32_e32 v114, v114
	v_rcp_f32_e32 v115, v115
	v_pk_mul_f32 v[44:45], v[44:45], v[144:145] op_sel_hi:[1,0]
	v_pk_mul_f32 v[38:39], v[38:39], v[144:145] op_sel_hi:[1,0]
	v_pk_mul_f32 v[34:35], v[34:35], v[144:145] op_sel_hi:[1,0]
	v_pk_mul_f32 v[110:111], v[110:111], v[114:115]
	v_pk_mul_f32 v[36:37], v[36:37], v[144:145] op_sel_hi:[1,0]
	v_pk_mul_f32 v[106:107], v[106:107], v[110:111]
	v_pk_mul_f32 v[110:111], v[112:113], v[152:153] op_sel_hi:[1,0]
	v_pk_mul_f32 v[30:31], v[30:31], v[142:143] op_sel_hi:[1,0]
	v_mul_f32_e32 v112, 0xbfb8aa3b, v110
	v_mul_f32_e32 v113, 0xbfb8aa3b, v111
	v_exp_f32_e32 v112, v112
	v_exp_f32_e32 v113, v113
	v_pk_mul_f32 v[26:27], v[26:27], v[142:143] op_sel_hi:[1,0]
	v_pk_mul_f32 v[28:29], v[28:29], v[142:143] op_sel_hi:[1,0]
	v_add_f32_e32 v112, 1.0, v112
	v_add_f32_e32 v113, 1.0, v113
	v_rcp_f32_e32 v112, v112
	v_rcp_f32_e32 v113, v113
	v_pk_mul_f32 v[22:23], v[22:23], v[142:143] op_sel_hi:[1,0]
	v_pk_mul_f32 v[18:19], v[18:19], v[142:143] op_sel_hi:[1,0]
	v_pk_mul_f32 v[20:21], v[20:21], v[142:143] op_sel_hi:[1,0]
	v_pk_mul_f32 v[110:111], v[110:111], v[112:113]
	s_waitcnt lgkmcnt(0)
; __device__ __forceinline__ unsigned pk2(float lo, float hi) { f32x2 v = {lo, hi}; bf16x2_t b = __builtin_convertvector(v, bf16x2_t); return __builtin_bit_cast(unsigned, b); }
;     __device__ __forceinline__ void operator()(const AccT& acc, const Unit& u, int wr, int wc, int fr, int fq) const {
;     ...
; #pragma unroll
;         for (int ai = 0; ai < 2; ++ai)
; #pragma unroll
;             for (int m = 0; m < 4; ++m) {
;                 const int row = row0 + ai * HALF + m * 16;
;                 const float rs = rsv[ai * 4 + m];
;                 float v[8];
; #pragma unroll
;                 for (int n = 0; n < 2; ++n)
; #pragma unroll
;                     for (int j = 0; j < 4; ++j) {
;                         const float g = acc[ai][0][m][n][j] * rs, up = acc[ai][1][m][n][j] * rs;
;                         const float sg = __builtin_amdgcn_rcpf(1.0f + __builtin_amdgcn_exp2f(-g * LOG2E));
;                         v[4 * n + j] = g * sg * up;
;                     }
;                 u32x4 w; w.x = pk2(v[0], v[1]); w.y = pk2(v[2], v[3]); w.z = pk2(v[4], v[5]); w.w = pk2(v[6], v[7]);
;                 *(u32x4*)(mid + (size_t)row * FF + col0) = w;
	v_pk_mul_f32 v[14:15], v[14:15], v[140:141] op_sel_hi:[1,0]
	v_pk_mul_f32 v[108:109], v[108:109], v[110:111]
	v_mul_f32_e32 v110, 0xbfb8aa3b, v102
	v_mul_f32_e32 v111, 0xbfb8aa3b, v103
	v_exp_f32_e32 v110, v110
	v_exp_f32_e32 v111, v111
	v_pk_mul_f32 v[10:11], v[10:11], v[140:141] op_sel_hi:[1,0]
	v_pk_mul_f32 v[12:13], v[12:13], v[140:141] op_sel_hi:[1,0]
	v_add_f32_e32 v110, 1.0, v110
	v_add_f32_e32 v111, 1.0, v111
	v_rcp_f32_e32 v110, v110
	v_rcp_f32_e32 v111, v111
	v_pk_mul_f32 v[6:7], v[6:7], v[140:141] op_sel_hi:[1,0]
	v_pk_mul_f32 v[2:3], v[2:3], v[140:141] op_sel_hi:[1,0]
	v_pk_mul_f32 v[4:5], v[4:5], v[140:141] op_sel_hi:[1,0]
	v_pk_mul_f32 v[102:103], v[102:103], v[110:111]
	v_or_b32_e32 v110, 16, v153
	v_pk_mul_f32 v[102:103], v[98:99], v[102:103]
	v_pk_mul_f32 v[98:99], v[104:105], v[152:153] op_sel_hi:[1,0]
	s_mov_b32 s65, s38
	v_mul_f32_e32 v104, 0xbfb8aa3b, v98
	v_mul_f32_e32 v105, 0xbfb8aa3b, v99
	v_exp_f32_e32 v104, v104
	v_exp_f32_e32 v105, v105
	v_add_f32_e32 v104, 1.0, v104
	v_add_f32_e32 v105, 1.0, v105
	v_rcp_f32_e32 v104, v104
	v_rcp_f32_e32 v105, v105
	s_nop 0
	v_pk_mul_f32 v[98:99], v[98:99], v[104:105]
	s_nop 0
	v_pk_mul_f32 v[104:105], v[100:101], v[98:99]
	v_cvt_pk_bf16_f32 v100, v102, v103
	v_mad_i64_i32 v[102:103], s[46:47], v110, s39, v[118:119]
	v_cvt_pk_bf16_f32 v98, v106, v107
	v_cvt_pk_bf16_f32 v99, v108, v109
	v_cvt_pk_bf16_f32 v101, v104, v105
	v_lshl_add_u64 v[102:103], v[102:103], 0, v[120:121]
	global_store_dwordx4 v[102:103], v[98:101], off
	s_nop 1
	v_mul_f32_e32 v98, 0xbfb8aa3b, v94
	v_mul_f32_e32 v99, 0xbfb8aa3b, v95
	v_exp_f32_e32 v98, v98
	v_exp_f32_e32 v99, v99
	v_add_f32_e32 v98, 1.0, v98
	v_add_f32_e32 v99, 1.0, v99
	v_rcp_f32_e32 v98, v98
	v_rcp_f32_e32 v99, v99
	s_nop 0
	v_pk_mul_f32 v[94:95], v[94:95], v[98:99]
	s_nop 0
	v_pk_mul_f32 v[90:91], v[90:91], v[94:95]
	v_pk_mul_f32 v[94:95], v[96:97], v[150:151] op_sel_hi:[1,0]
	s_nop 0
	v_mul_f32_e32 v96, 0xbfb8aa3b, v94
	v_mul_f32_e32 v97, 0xbfb8aa3b, v95
	v_exp_f32_e32 v96, v96
	v_exp_f32_e32 v97, v97
	v_add_f32_e32 v96, 1.0, v96
	v_add_f32_e32 v97, 1.0, v97
	v_rcp_f32_e32 v96, v96
	v_rcp_f32_e32 v97, v97
	s_nop 0
	v_pk_mul_f32 v[94:95], v[94:95], v[96:97]
	s_nop 0
	v_pk_mul_f32 v[92:93], v[92:93], v[94:95]
	v_mul_f32_e32 v94, 0xbfb8aa3b, v86
	v_mul_f32_e32 v95, 0xbfb8aa3b, v87
	v_exp_f32_e32 v94, v94
	v_exp_f32_e32 v95, v95
	v_add_f32_e32 v94, 1.0, v94
	v_add_f32_e32 v95, 1.0, v95
	v_rcp_f32_e32 v94, v94
	v_rcp_f32_e32 v95, v95
	s_nop 0
	v_pk_mul_f32 v[86:87], v[86:87], v[94:95]
	s_nop 0
	v_pk_mul_f32 v[86:87], v[82:83], v[86:87]
	v_pk_mul_f32 v[82:83], v[88:89], v[150:151] op_sel_hi:[1,0]
	v_or_b32_e32 v94, 32, v153
	v_mul_f32_e32 v88, 0xbfb8aa3b, v82
	v_mul_f32_e32 v89, 0xbfb8aa3b, v83
	v_exp_f32_e32 v88, v88
	v_exp_f32_e32 v89, v89
	v_add_f32_e32 v88, 1.0, v88
	v_add_f32_e32 v89, 1.0, v89
	v_rcp_f32_e32 v88, v88
	v_rcp_f32_e32 v89, v89
	s_nop 0
	v_pk_mul_f32 v[82:83], v[82:83], v[88:89]
	s_nop 0
	v_pk_mul_f32 v[88:89], v[84:85], v[82:83]
	v_cvt_pk_bf16_f32 v84, v86, v87
	v_mad_i64_i32 v[86:87], s[46:47], v94, s39, v[118:119]
	v_cvt_pk_bf16_f32 v82, v90, v91
	v_cvt_pk_bf16_f32 v83, v92, v93
	v_cvt_pk_bf16_f32 v85, v88, v89
	v_lshl_add_u64 v[86:87], v[86:87], 0, v[120:121]
	global_store_dwordx4 v[86:87], v[82:85], off
	s_nop 1
	v_mul_f32_e32 v82, 0xbfb8aa3b, v78
	v_mul_f32_e32 v83, 0xbfb8aa3b, v79
	v_exp_f32_e32 v82, v82
	v_exp_f32_e32 v83, v83
	v_add_f32_e32 v82, 1.0, v82
	v_add_f32_e32 v83, 1.0, v83
	v_rcp_f32_e32 v82, v82
	v_rcp_f32_e32 v83, v83
	s_nop 0
	v_pk_mul_f32 v[78:79], v[78:79], v[82:83]
	s_nop 0
	v_pk_mul_f32 v[74:75], v[74:75], v[78:79]
	v_pk_mul_f32 v[78:79], v[80:81], v[148:149] op_sel_hi:[1,0]
	s_nop 0
	v_mul_f32_e32 v80, 0xbfb8aa3b, v78
	v_mul_f32_e32 v81, 0xbfb8aa3b, v79
	v_exp_f32_e32 v80, v80
	v_exp_f32_e32 v81, v81
	v_add_f32_e32 v80, 1.0, v80
	v_add_f32_e32 v81, 1.0, v81
	v_rcp_f32_e32 v80, v80
	v_rcp_f32_e32 v81, v81
	s_nop 0
	v_pk_mul_f32 v[78:79], v[78:79], v[80:81]
	s_nop 0
	v_pk_mul_f32 v[76:77], v[76:77], v[78:79]
	v_mul_f32_e32 v78, 0xbfb8aa3b, v70
	v_mul_f32_e32 v79, 0xbfb8aa3b, v71
	v_exp_f32_e32 v78, v78
	v_exp_f32_e32 v79, v79
	v_add_f32_e32 v78, 1.0, v78
	v_add_f32_e32 v79, 1.0, v79
	v_rcp_f32_e32 v78, v78
	v_rcp_f32_e32 v79, v79
	s_nop 0
	v_pk_mul_f32 v[70:71], v[70:71], v[78:79]
	s_nop 0
	v_pk_mul_f32 v[70:71], v[66:67], v[70:71]
	v_pk_mul_f32 v[66:67], v[72:73], v[148:149] op_sel_hi:[1,0]
	v_or_b32_e32 v78, 48, v153
	v_mul_f32_e32 v72, 0xbfb8aa3b, v66
	v_mul_f32_e32 v73, 0xbfb8aa3b, v67
	v_exp_f32_e32 v72, v72
	v_exp_f32_e32 v73, v73
	v_add_f32_e32 v72, 1.0, v72
	v_add_f32_e32 v73, 1.0, v73
	v_rcp_f32_e32 v72, v72
	v_rcp_f32_e32 v73, v73
	s_nop 0
	v_pk_mul_f32 v[66:67], v[66:67], v[72:73]
	s_nop 0
	v_pk_mul_f32 v[72:73], v[68:69], v[66:67]
	v_cvt_pk_bf16_f32 v68, v70, v71
	v_mad_i64_i32 v[70:71], s[46:47], v78, s39, v[118:119]
	v_cvt_pk_bf16_f32 v66, v74, v75
	v_cvt_pk_bf16_f32 v67, v76, v77
	v_cvt_pk_bf16_f32 v69, v72, v73
	v_lshl_add_u64 v[70:71], v[70:71], 0, v[120:121]
	global_store_dwordx4 v[70:71], v[66:69], off
	s_nop 1
	v_mul_f32_e32 v66, 0xbfb8aa3b, v62
	v_mul_f32_e32 v67, 0xbfb8aa3b, v63
	v_exp_f32_e32 v66, v66
	v_exp_f32_e32 v67, v67
	v_add_u32_e32 v68, 0x80, v153
	v_add_f32_e32 v66, 1.0, v66
	v_add_f32_e32 v67, 1.0, v67
	v_rcp_f32_e32 v66, v66
	v_rcp_f32_e32 v67, v67
	s_nop 0
	v_pk_mul_f32 v[62:63], v[62:63], v[66:67]
	s_nop 0
	v_pk_mul_f32 v[58:59], v[58:59], v[62:63]
	v_pk_mul_f32 v[62:63], v[64:65], v[146:147] op_sel_hi:[1,0]
	s_nop 0
	v_mul_f32_e32 v64, 0xbfb8aa3b, v62
	v_mul_f32_e32 v65, 0xbfb8aa3b, v63
	v_exp_f32_e32 v64, v64
	v_exp_f32_e32 v65, v65
	v_add_f32_e32 v64, 1.0, v64
; __device__ __forceinline__ unsigned pk2(float lo, float hi) { f32x2 v = {lo, hi}; bf16x2_t b = __builtin_convertvector(v, bf16x2_t); return __builtin_bit_cast(unsigned, b); }
; #define PG8_WAIT_V(n) asm volatile("s_waitcnt vmcnt(" #n ")" ::: "memory")
; #define PG8_BAR __builtin_amdgcn_s_barrier()
;     __device__ __forceinline__ void operator()(const AccT& acc, const Unit& u, int wr, int wc, int fr, int fq) const {
;     ...
;         for (int ai = 0; ai < 2; ++ai)
; #pragma unroll
;             for (int m = 0; m < 4; ++m) {
;                 const int row = row0 + ai * HALF + m * 16;
;                 const float rs = rsv[ai * 4 + m];
;                 float v[8];
; #pragma unroll
;                 for (int n = 0; n < 2; ++n)
; #pragma unroll
;                     for (int j = 0; j < 4; ++j) {
;                         const float g = acc[ai][0][m][n][j] * rs, up = acc[ai][1][m][n][j] * rs;
;                         const float sg = __builtin_amdgcn_rcpf(1.0f + __builtin_amdgcn_exp2f(-g * LOG2E));
;                         v[4 * n + j] = g * sg * up;
;                     }
;                 u32x4 w; w.x = pk2(v[0], v[1]); w.y = pk2(v[2], v[3]); w.z = pk2(v[4], v[5]); w.w = pk2(v[6], v[7]);
;                 *(u32x4*)(mid + (size_t)row * FF + col0) = w;
; template <class Epi>
; __device__ __forceinline__ void gemm_phase(LAS unsigned char* lds, const Gemm g, const StaticOrder& S, const Epi& E) {
;     ...
;         E(acc, cur, wr, wc, fr, fq);
;         if (!has_next) break;
; #pragma unroll
;         for (int a = 0; a < 2; ++a)
; #pragma unroll
;             for (int b = 0; b < 2; ++b)
; #pragma unroll
;                 for (int m = 0; m < 4; ++m)
; #pragma unroll
;                     for (int n = 0; n < 2; ++n) acc[a][b][m][n] = (f32x4){0.f, 0.f, 0.f, 0.f};
;         cur = nxt; cA = nA; cB = nB; ++ui;
;     }
;     PG8_WAIT_V(0);
;     if (wr == 0) PG8_BAR;
;     PG8_BAR;
	v_add_f32_e32 v65, 1.0, v65
	v_rcp_f32_e32 v64, v64
	v_rcp_f32_e32 v65, v65
	s_nop 0
	v_pk_mul_f32 v[62:63], v[62:63], v[64:65]
	s_nop 0
	v_pk_mul_f32 v[60:61], v[60:61], v[62:63]
	v_mul_f32_e32 v62, 0xbfb8aa3b, v54
	v_mul_f32_e32 v63, 0xbfb8aa3b, v55
	v_exp_f32_e32 v62, v62
	v_exp_f32_e32 v63, v63
	v_add_f32_e32 v62, 1.0, v62
	v_add_f32_e32 v63, 1.0, v63
	v_rcp_f32_e32 v62, v62
	v_rcp_f32_e32 v63, v63
	s_nop 0
	v_pk_mul_f32 v[54:55], v[54:55], v[62:63]
	s_nop 0
	v_pk_mul_f32 v[54:55], v[50:51], v[54:55]
	v_pk_mul_f32 v[50:51], v[56:57], v[146:147] op_sel_hi:[1,0]
	s_nop 0
	v_mul_f32_e32 v56, 0xbfb8aa3b, v50
	v_mul_f32_e32 v57, 0xbfb8aa3b, v51
	v_exp_f32_e32 v56, v56
	v_exp_f32_e32 v57, v57
	v_add_f32_e32 v56, 1.0, v56
	v_add_f32_e32 v57, 1.0, v57
	v_rcp_f32_e32 v56, v56
	v_rcp_f32_e32 v57, v57
	s_nop 0
	v_pk_mul_f32 v[50:51], v[50:51], v[56:57]
	s_nop 0
	v_pk_mul_f32 v[56:57], v[52:53], v[50:51]
	v_cvt_pk_bf16_f32 v52, v54, v55
	v_mad_i64_i32 v[54:55], s[46:47], v68, s39, v[118:119]
	v_cvt_pk_bf16_f32 v50, v58, v59
	v_cvt_pk_bf16_f32 v51, v60, v61
	v_cvt_pk_bf16_f32 v53, v56, v57
	v_lshl_add_u64 v[54:55], v[54:55], 0, v[120:121]
	global_store_dwordx4 v[54:55], v[50:53], off
	s_nop 1
	v_mul_f32_e32 v50, 0xbfb8aa3b, v46
	v_mul_f32_e32 v51, 0xbfb8aa3b, v47
	v_exp_f32_e32 v50, v50
	v_exp_f32_e32 v51, v51
	v_add_f32_e32 v50, 1.0, v50
	v_add_f32_e32 v51, 1.0, v51
	v_rcp_f32_e32 v50, v50
	v_rcp_f32_e32 v51, v51
	s_nop 0
	v_pk_mul_f32 v[46:47], v[46:47], v[50:51]
	s_nop 0
	v_pk_mul_f32 v[42:43], v[42:43], v[46:47]
	v_pk_mul_f32 v[46:47], v[48:49], v[144:145] op_sel_hi:[1,0]
	s_nop 0
	v_mul_f32_e32 v48, 0xbfb8aa3b, v46
	v_mul_f32_e32 v49, 0xbfb8aa3b, v47
	v_exp_f32_e32 v48, v48
	v_exp_f32_e32 v49, v49
	v_add_f32_e32 v48, 1.0, v48
	v_add_f32_e32 v49, 1.0, v49
	v_rcp_f32_e32 v48, v48
	v_rcp_f32_e32 v49, v49
	s_nop 0
	v_pk_mul_f32 v[46:47], v[46:47], v[48:49]
	s_nop 0
	v_pk_mul_f32 v[44:45], v[44:45], v[46:47]
	v_mul_f32_e32 v46, 0xbfb8aa3b, v38
	v_mul_f32_e32 v47, 0xbfb8aa3b, v39
	v_exp_f32_e32 v46, v46
	v_exp_f32_e32 v47, v47
	v_add_f32_e32 v46, 1.0, v46
	v_add_f32_e32 v47, 1.0, v47
	v_rcp_f32_e32 v46, v46
	v_rcp_f32_e32 v47, v47
	s_nop 0
	v_pk_mul_f32 v[38:39], v[38:39], v[46:47]
	s_nop 0
	v_pk_mul_f32 v[38:39], v[34:35], v[38:39]
	v_pk_mul_f32 v[34:35], v[40:41], v[144:145] op_sel_hi:[1,0]
	v_add_u32_e32 v46, 0x90, v153
	v_mul_f32_e32 v40, 0xbfb8aa3b, v34
	v_mul_f32_e32 v41, 0xbfb8aa3b, v35
	v_exp_f32_e32 v40, v40
	v_exp_f32_e32 v41, v41
	v_add_f32_e32 v40, 1.0, v40
	v_add_f32_e32 v41, 1.0, v41
	v_rcp_f32_e32 v40, v40
	v_rcp_f32_e32 v41, v41
	s_nop 0
	v_pk_mul_f32 v[34:35], v[34:35], v[40:41]
	s_nop 0
	v_pk_mul_f32 v[40:41], v[36:37], v[34:35]
	v_cvt_pk_bf16_f32 v36, v38, v39
	v_mad_i64_i32 v[38:39], s[46:47], v46, s39, v[118:119]
	v_cvt_pk_bf16_f32 v34, v42, v43
	v_cvt_pk_bf16_f32 v35, v44, v45
	v_cvt_pk_bf16_f32 v37, v40, v41
	v_lshl_add_u64 v[38:39], v[38:39], 0, v[120:121]
	global_store_dwordx4 v[38:39], v[34:37], off
	s_nop 1
	v_mul_f32_e32 v34, 0xbfb8aa3b, v30
	v_mul_f32_e32 v35, 0xbfb8aa3b, v31
	v_exp_f32_e32 v34, v34
	v_exp_f32_e32 v35, v35
	v_add_f32_e32 v34, 1.0, v34
	v_add_f32_e32 v35, 1.0, v35
	v_rcp_f32_e32 v34, v34
	v_rcp_f32_e32 v35, v35
	s_nop 0
	v_pk_mul_f32 v[30:31], v[30:31], v[34:35]
	s_nop 0
	v_pk_mul_f32 v[26:27], v[26:27], v[30:31]
	v_pk_mul_f32 v[30:31], v[32:33], v[142:143] op_sel_hi:[1,0]
	s_nop 0
	v_mul_f32_e32 v32, 0xbfb8aa3b, v30
	v_mul_f32_e32 v33, 0xbfb8aa3b, v31
	v_exp_f32_e32 v32, v32
	v_exp_f32_e32 v33, v33
	v_add_f32_e32 v32, 1.0, v32
	v_add_f32_e32 v33, 1.0, v33
	v_rcp_f32_e32 v32, v32
	v_rcp_f32_e32 v33, v33
	s_nop 0
	v_pk_mul_f32 v[30:31], v[30:31], v[32:33]
	s_nop 0
	v_pk_mul_f32 v[28:29], v[28:29], v[30:31]
	v_mul_f32_e32 v30, 0xbfb8aa3b, v22
	v_mul_f32_e32 v31, 0xbfb8aa3b, v23
	v_exp_f32_e32 v30, v30
	v_exp_f32_e32 v31, v31
	v_add_f32_e32 v30, 1.0, v30
	v_add_f32_e32 v31, 1.0, v31
	v_rcp_f32_e32 v30, v30
	v_rcp_f32_e32 v31, v31
	s_nop 0
	v_pk_mul_f32 v[22:23], v[22:23], v[30:31]
	s_nop 0
	v_pk_mul_f32 v[22:23], v[18:19], v[22:23]
	v_pk_mul_f32 v[18:19], v[24:25], v[142:143] op_sel_hi:[1,0]
	v_add_u32_e32 v30, 0xa0, v153
	v_mul_f32_e32 v24, 0xbfb8aa3b, v18
	v_mul_f32_e32 v25, 0xbfb8aa3b, v19
	v_exp_f32_e32 v24, v24
	v_exp_f32_e32 v25, v25
	v_add_f32_e32 v24, 1.0, v24
	v_add_f32_e32 v25, 1.0, v25
	v_rcp_f32_e32 v24, v24
	v_rcp_f32_e32 v25, v25
	s_nop 0
	v_pk_mul_f32 v[18:19], v[18:19], v[24:25]
	s_nop 0
	v_pk_mul_f32 v[24:25], v[20:21], v[18:19]
	v_cvt_pk_bf16_f32 v20, v22, v23
	v_mad_i64_i32 v[22:23], s[46:47], v30, s39, v[118:119]
	v_cvt_pk_bf16_f32 v18, v26, v27
	v_cvt_pk_bf16_f32 v19, v28, v29
	v_cvt_pk_bf16_f32 v21, v24, v25
	v_lshl_add_u64 v[22:23], v[22:23], 0, v[120:121]
	global_store_dwordx4 v[22:23], v[18:21], off
	s_nop 1
	v_mul_f32_e32 v18, 0xbfb8aa3b, v14
	v_mul_f32_e32 v19, 0xbfb8aa3b, v15
	v_exp_f32_e32 v18, v18
	v_exp_f32_e32 v19, v19
	v_add_f32_e32 v18, 1.0, v18
	v_add_f32_e32 v19, 1.0, v19
	v_rcp_f32_e32 v18, v18
	v_rcp_f32_e32 v19, v19
	s_nop 0
	v_pk_mul_f32 v[14:15], v[14:15], v[18:19]
	s_nop 0
	v_pk_mul_f32 v[10:11], v[10:11], v[14:15]
	v_pk_mul_f32 v[14:15], v[16:17], v[140:141] op_sel_hi:[1,0]
	s_nop 0
	v_mul_f32_e32 v16, 0xbfb8aa3b, v14
	v_mul_f32_e32 v17, 0xbfb8aa3b, v15
	v_exp_f32_e32 v16, v16
	v_exp_f32_e32 v17, v17
	v_add_f32_e32 v16, 1.0, v16
	v_add_f32_e32 v17, 1.0, v17
	v_rcp_f32_e32 v16, v16
	v_rcp_f32_e32 v17, v17
	s_nop 0
	v_pk_mul_f32 v[14:15], v[14:15], v[16:17]
	s_nop 0
	v_pk_mul_f32 v[12:13], v[12:13], v[14:15]
	v_mul_f32_e32 v14, 0xbfb8aa3b, v6
	v_mul_f32_e32 v15, 0xbfb8aa3b, v7
	v_exp_f32_e32 v14, v14
	v_exp_f32_e32 v15, v15
	v_add_f32_e32 v14, 1.0, v14
	v_add_f32_e32 v15, 1.0, v15
	v_rcp_f32_e32 v14, v14
	v_rcp_f32_e32 v15, v15
	s_nop 0
	v_pk_mul_f32 v[6:7], v[6:7], v[14:15]
	s_nop 0
	v_pk_mul_f32 v[6:7], v[2:3], v[6:7]
	v_pk_mul_f32 v[2:3], v[8:9], v[140:141] op_sel_hi:[1,0]
	v_add_u32_e32 v14, 0xb0, v153
	v_mul_f32_e32 v8, 0xbfb8aa3b, v2
	v_mul_f32_e32 v9, 0xbfb8aa3b, v3
	v_exp_f32_e32 v8, v8
	v_exp_f32_e32 v9, v9
	v_add_f32_e32 v8, 1.0, v8
	v_add_f32_e32 v9, 1.0, v9
	v_rcp_f32_e32 v8, v8
	v_rcp_f32_e32 v9, v9
	s_nop 0
	v_pk_mul_f32 v[2:3], v[2:3], v[8:9]
	s_nop 0
	v_pk_mul_f32 v[8:9], v[4:5], v[2:3]
	v_cvt_pk_bf16_f32 v4, v6, v7
	v_mad_i64_i32 v[6:7], s[46:47], v14, s39, v[118:119]
	v_cvt_pk_bf16_f32 v2, v10, v11
	v_cvt_pk_bf16_f32 v3, v12, v13
	v_cvt_pk_bf16_f32 v5, v8, v9
	v_lshl_add_u64 v[6:7], v[6:7], 0, v[120:121]
	s_mov_b64 s[46:47], s[42:43]
	global_store_dwordx4 v[6:7], v[2:5], off
	s_cbranch_vccz .LBB0_87
	s_waitcnt vmcnt(0)
	s_cmpk_gt_u32 s52, 0xff
	s_cbranch_scc1 .LBB0_94
	s_barrier

; #define PG8_STAGE(bufoff, gbase, voff) do { _Pragma("unroll") for (int _i = 0; _i < 2; ++_i) \
;         __builtin_amdgcn_global_load_lds((const unsigned*)((const char*)(gbase) + (voff)[_i]), (LAS unsigned*)(lds + (bufoff) + ldsw + _i * 8192), 16, 0, 0); } while (0)
; #define PG8_LDA(dst, b, h) do { _Pragma("unroll") for (int m = 0; m < 4; ++m) _Pragma("unroll") for (int k = 0; k < 2; ++k) dst[m][k] = *(const LAS bf16x8*)(lds + PG8_SA(b, h) + aoff + m * 2048 + k * 1024); } while (0)
; #define PG8_LDB(dst, b, h) do { _Pragma("unroll") for (int n = 0; n < 2; ++n) _Pragma("unroll") for (int k = 0; k < 2; ++k) dst[n][k] = *(const LAS bf16x8*)(lds + PG8_SB(b, h) + boff + n * 2048 + k * 1024); } while (0)
; #define PG8_MMA(ai, bj, At, Bt) do { __builtin_amdgcn_s_setprio(1); _Pragma("unroll") for (int m = 0; m < 4; ++m) _Pragma("unroll") for (int n = 0; n < 2; ++n) _Pragma("unroll") for (int k = 0; k < 2; ++k) \
;         acc[ai][bj][m][n] = __builtin_amdgcn_mfma_f32_16x16x32_bf16(Bt[n][k], At[m][k], acc[ai][bj][m][n], 0, 0, 0); __builtin_amdgcn_s_setprio(0); } while (0)
; #define PG8_WAIT_L(n) asm volatile("s_waitcnt lgkmcnt(" #n ")" ::: "memory")
; template <class Epi>
; __device__ __forceinline__ void gemm_phase(LAS unsigned char* lds, const Gemm g, const StaticOrder& S, const Epi& E) {
;     ...
;         const bool has_next = S.next(ui + 1, nxt);
;         const char* nA = has_next ? (const char*)g.A + (size_t)nxt.pm * tstep : cA; const char* nB = has_next ? (const char*)g.Bt + (size_t)nxt.pn * tstep : cB;
;         for (int t = 0; t < nt; t += 2) {
;             const bool last = (t == nt - 2);
;             const char* a1 = cA + (size_t)(t + 1) * kstep;
;             const char* a2 = last ? nA : cA + (size_t)(t + 2) * kstep; const char* b2 = last ? nB : cB + (size_t)(t + 2) * kstep;
;             const char* a3 = a2 + kstep; const char* b3 = b2 + kstep;
;             PG8_LDB(B0, 0, 0); PG8_SCHED; PG8_LDA(At, 0, 0); PG8_STAGE(PG8_SA(1, 1), a1 + hstep, voffA);
;             PG8_WAIT_L(8); PG8_BAR; PG8_WAIT_L(0); PG8_MMA(0, 0, At, B0); PG8_BAR; PG8_SCHED;
;     ...
;         for (int a = 0; a < 2; ++a)
; #pragma unroll
;             for (int b = 0; b < 2; ++b)
; #pragma unroll
;                 for (int m = 0; m < 4; ++m)
; #pragma unroll
;                     for (int n = 0; n < 2; ++n) acc[a][b][m][n] = (f32x4){0.f, 0.f, 0.f, 0.f};
;         cur = nxt; cA = nA; cB = nB; ++ui;
.LBB0_653:
	s_add_u32 s60, s60, 0x80
	s_addc_u32 s61, s61, 0
	s_add_u32 s82, s62, 0x100
	v_mov_b32_e32 v2, 0
	s_addc_u32 s83, s63, 0
	s_mov_b32 s62, 0
	v_mov_b32_e32 v3, v2
	v_mov_b32_e32 v4, v2
	v_mov_b32_e32 v5, v2
	v_mov_b32_e32 v6, v2
	v_mov_b32_e32 v7, v2
	v_mov_b32_e32 v8, v2
	v_mov_b32_e32 v9, v2
	v_mov_b32_e32 v18, v2
	v_mov_b32_e32 v19, v2
	v_mov_b32_e32 v20, v2
	v_mov_b32_e32 v21, v2
	v_mov_b32_e32 v22, v2
	v_mov_b32_e32 v23, v2
	v_mov_b32_e32 v24, v2
	v_mov_b32_e32 v25, v2
	v_mov_b32_e32 v34, v2
	v_mov_b32_e32 v35, v2
	v_mov_b32_e32 v36, v2
	v_mov_b32_e32 v37, v2
	v_mov_b32_e32 v38, v2
	v_mov_b32_e32 v39, v2
	v_mov_b32_e32 v40, v2
	v_mov_b32_e32 v41, v2
	v_mov_b32_e32 v50, v2
	v_mov_b32_e32 v51, v2
	v_mov_b32_e32 v52, v2
	v_mov_b32_e32 v53, v2
	v_mov_b32_e32 v54, v2
	v_mov_b32_e32 v55, v2
	v_mov_b32_e32 v56, v2
	v_mov_b32_e32 v57, v2
	v_mov_b32_e32 v10, v2
	v_mov_b32_e32 v11, v2
	v_mov_b32_e32 v12, v2
	v_mov_b32_e32 v13, v2
	v_mov_b32_e32 v14, v2
	v_mov_b32_e32 v15, v2
	v_mov_b32_e32 v16, v2
	v_mov_b32_e32 v17, v2
	v_mov_b32_e32 v26, v2
	v_mov_b32_e32 v27, v2
	v_mov_b32_e32 v28, v2
	v_mov_b32_e32 v29, v2
	v_mov_b32_e32 v30, v2
	v_mov_b32_e32 v31, v2
	v_mov_b32_e32 v32, v2
	v_mov_b32_e32 v33, v2
	v_mov_b32_e32 v42, v2
	v_mov_b32_e32 v43, v2
	v_mov_b32_e32 v44, v2
	v_mov_b32_e32 v45, v2
	v_mov_b32_e32 v46, v2
	v_mov_b32_e32 v47, v2
	v_mov_b32_e32 v48, v2
	v_mov_b32_e32 v49, v2
	v_mov_b32_e32 v74, v2
	v_mov_b32_e32 v75, v2
	v_mov_b32_e32 v76, v2
	v_mov_b32_e32 v77, v2
	v_mov_b32_e32 v78, v2
	v_mov_b32_e32 v79, v2
	v_mov_b32_e32 v80, v2
	v_mov_b32_e32 v81, v2
	v_mov_b32_e32 v82, v2
	v_mov_b32_e32 v83, v2
	v_mov_b32_e32 v84, v2
	v_mov_b32_e32 v85, v2
	v_mov_b32_e32 v86, v2
	v_mov_b32_e32 v87, v2
	v_mov_b32_e32 v88, v2
	v_mov_b32_e32 v89, v2
	v_mov_b32_e32 v98, v2
	v_mov_b32_e32 v99, v2
	v_mov_b32_e32 v100, v2
	v_mov_b32_e32 v101, v2
	v_mov_b32_e32 v102, v2
	v_mov_b32_e32 v103, v2
	v_mov_b32_e32 v104, v2
	v_mov_b32_e32 v105, v2
	v_mov_b32_e32 v114, v2
	v_mov_b32_e32 v115, v2
	v_mov_b32_e32 v116, v2
	v_mov_b32_e32 v117, v2
	v_mov_b32_e32 v118, v2
	v_mov_b32_e32 v119, v2
	v_mov_b32_e32 v120, v2
	v_mov_b32_e32 v121, v2
	v_mov_b32_e32 v130, v2
	v_mov_b32_e32 v131, v2
	v_mov_b32_e32 v132, v2
	v_mov_b32_e32 v133, v2
	v_mov_b32_e32 v134, v2
	v_mov_b32_e32 v135, v2
	v_mov_b32_e32 v136, v2
	v_mov_b32_e32 v137, v2
	v_mov_b32_e32 v90, v2
	v_mov_b32_e32 v91, v2
	v_mov_b32_e32 v92, v2
	v_mov_b32_e32 v93, v2
	v_mov_b32_e32 v94, v2
	v_mov_b32_e32 v95, v2
	v_mov_b32_e32 v96, v2
	v_mov_b32_e32 v97, v2
	v_mov_b32_e32 v106, v2
	v_mov_b32_e32 v107, v2
	v_mov_b32_e32 v108, v2
	v_mov_b32_e32 v109, v2
	v_mov_b32_e32 v110, v2
	v_mov_b32_e32 v111, v2
	v_mov_b32_e32 v112, v2
	v_mov_b32_e32 v113, v2
	v_mov_b32_e32 v122, v2
	v_mov_b32_e32 v123, v2
	v_mov_b32_e32 v124, v2
	v_mov_b32_e32 v125, v2
	v_mov_b32_e32 v126, v2
	v_mov_b32_e32 v127, v2
	v_mov_b32_e32 v128, v2
	v_mov_b32_e32 v129, v2
	v_mov_b32_e32 v138, v2
	v_mov_b32_e32 v139, v2
	v_mov_b32_e32 v140, v2
	v_mov_b32_e32 v141, v2
	v_mov_b32_e32 v142, v2
	v_mov_b32_e32 v143, v2
	v_mov_b32_e32 v144, v2
	v_mov_b32_e32 v145, v2
	v_add_u32_e32 v194, 0x10000, v241
	ds_read_b128 v[58:61], v194
	ds_read_b128 v[62:65], v194 offset:1024
	ds_read_b128 v[66:69], v194 offset:2048
	ds_read_b128 v[70:73], v194 offset:3072
.LBB0_654:
	s_add_i32 s84, s62, 2
	s_add_u32 s64, s60, 0x80
	s_addc_u32 s63, s61, 0
	s_add_i32 s85, 0, 0x10000
	s_cmp_eq_u32 s77, s62
	s_cselect_b32 s62, s2, s64
	s_cselect_b32 s63, s3, s63
	s_cselect_b32 s65, s41, s83
	s_cselect_b32 s64, s40, s82
	s_add_i32 m0, s70, 0xc000
	ds_read_b128 v[146:149], v243
	ds_read_b128 v[150:153], v243 offset:1024
	ds_read_b128 v[154:157], v243 offset:2048
	ds_read_b128 v[158:161], v243 offset:3072
	ds_read_b128 v[162:165], v243 offset:4096
	ds_read_b128 v[166:169], v243 offset:5120
	ds_read_b128 v[170:173], v243 offset:6144
	ds_read_b128 v[174:177], v243 offset:7168
	global_load_lds_dwordx4 v214, s[60:61]
	s_add_i32 m0, s70, 0xe000
	s_nop 0
	global_load_lds_dwordx4 v216, s[60:61]
	s_waitcnt lgkmcnt(8)
	s_barrier
	s_waitcnt lgkmcnt(0)
	s_setprio 1
	v_mfma_f32_16x16x32_bf16 v[142:145], v[58:61], v[146:149], v[142:145]
	v_mfma_f32_16x16x32_bf16 v[138:141], v[66:69], v[146:149], v[138:141]
	v_mfma_f32_16x16x32_bf16 v[126:129], v[58:61], v[154:157], v[126:129]
	v_mfma_f32_16x16x32_bf16 v[122:125], v[66:69], v[154:157], v[122:125]
	v_mfma_f32_16x16x32_bf16 v[110:113], v[58:61], v[162:165], v[110:113]
	v_mfma_f32_16x16x32_bf16 v[106:109], v[66:69], v[162:165], v[106:109]
	v_mfma_f32_16x16x32_bf16 v[94:97], v[58:61], v[170:173], v[94:97]
	v_mfma_f32_16x16x32_bf16 v[90:93], v[66:69], v[170:173], v[90:93]
	v_mfma_f32_16x16x32_bf16 v[142:145], v[62:65], v[150:153], v[142:145]
	v_mfma_f32_16x16x32_bf16 v[138:141], v[70:73], v[150:153], v[138:141]
	v_mfma_f32_16x16x32_bf16 v[126:129], v[62:65], v[158:161], v[126:129]
	v_mfma_f32_16x16x32_bf16 v[122:125], v[70:73], v[158:161], v[122:125]
	v_mfma_f32_16x16x32_bf16 v[110:113], v[62:65], v[166:169], v[110:113]
	v_mfma_f32_16x16x32_bf16 v[106:109], v[70:73], v[166:169], v[106:109]
	v_mfma_f32_16x16x32_bf16 v[94:97], v[62:65], v[174:177], v[94:97]
	v_mfma_f32_16x16x32_bf16 v[90:93], v[70:73], v[174:177], v[90:93]
	s_setprio 0
	s_barrier
	s_add_i32 s86, 0, 0x14000
	s_add_i32 s85, s85, s69
	s_add_u32 s98, s64, s22
	s_addc_u32 s99, s65, s23
	s_mov_b32 m0, s85
	ds_read_b128 v[178:181], v194 offset:16384
	ds_read_b128 v[182:185], v194 offset:17408
	ds_read_b128 v[186:189], v194 offset:18432
	ds_read_b128 v[190:193], v194 offset:19456
	global_load_lds_dwordx4 v0, s[64:65]
	s_add_i32 m0, s85, 0x2000
	s_nop 0
	global_load_lds_dwordx4 v208, s[64:65]
	s_barrier
; #define PG8_STAGE(bufoff, gbase, voff) do { _Pragma("unroll") for (int _i = 0; _i < 2; ++_i) \
;         __builtin_amdgcn_global_load_lds((const unsigned*)((const char*)(gbase) + (voff)[_i]), (LAS unsigned*)(lds + (bufoff) + ldsw + _i * 8192), 16, 0, 0); } while (0)
; #define PG8_LDA(dst, b, h) do { _Pragma("unroll") for (int m = 0; m < 4; ++m) _Pragma("unroll") for (int k = 0; k < 2; ++k) dst[m][k] = *(const LAS bf16x8*)(lds + PG8_SA(b, h) + aoff + m * 2048 + k * 1024); } while (0)
; #define PG8_LDB(dst, b, h) do { _Pragma("unroll") for (int n = 0; n < 2; ++n) _Pragma("unroll") for (int k = 0; k < 2; ++k) dst[n][k] = *(const LAS bf16x8*)(lds + PG8_SB(b, h) + boff + n * 2048 + k * 1024); } while (0)
; #define PG8_MMA(ai, bj, At, Bt) do { __builtin_amdgcn_s_setprio(1); _Pragma("unroll") for (int m = 0; m < 4; ++m) _Pragma("unroll") for (int n = 0; n < 2; ++n) _Pragma("unroll") for (int k = 0; k < 2; ++k) \
;         acc[ai][bj][m][n] = __builtin_amdgcn_mfma_f32_16x16x32_bf16(Bt[n][k], At[m][k], acc[ai][bj][m][n], 0, 0, 0); __builtin_amdgcn_s_setprio(0); } while (0)
; #define PG8_WAIT_V(n) asm volatile("s_waitcnt vmcnt(" #n ")" ::: "memory")
; #define PG8_WAIT_L(n) asm volatile("s_waitcnt lgkmcnt(" #n ")" ::: "memory")
; #define PG8_BAR __builtin_amdgcn_s_barrier()
; #define PG8_SCHED __builtin_amdgcn_sched_barrier(0)
; template <class Epi>
; __device__ __forceinline__ void gemm_phase(LAS unsigned char* lds, const Gemm g, const StaticOrder& S, const Epi& E) {
;     ...
;             PG8_LDB(B1, 0, 1); PG8_STAGE(PG8_SB(0, 0), b2, voffB);
;             PG8_BAR; PG8_WAIT_L(0); PG8_MMA(0, 1, At, B1); PG8_BAR;
;             PG8_LDA(At, 0, 1); PG8_STAGE(PG8_SA(0, 0), a2, voffA);
;             PG8_BAR; PG8_WAIT_L(0); PG8_MMA(1, 0, At, B0); PG8_BAR; PG8_SCHED;
;             PG8_STAGE(PG8_SB(0, 1), b2 + hstep, voffB);
;             PG8_WAIT_V(6); PG8_BAR; PG8_MMA(1, 1, At, B1); PG8_BAR;
;             PG8_LDB(B0, 1, 0); PG8_SCHED; PG8_LDA(At, 1, 0); PG8_STAGE(PG8_SA(0, 1), a2 + hstep, voffA);
;             PG8_WAIT_L(8); PG8_BAR; PG8_WAIT_L(0); PG8_MMA(0, 0, At, B0); PG8_BAR; PG8_SCHED;
	s_waitcnt lgkmcnt(0)
	s_setprio 1
	v_mfma_f32_16x16x32_bf16 v[134:137], v[178:181], v[146:149], v[134:137]
	v_mfma_f32_16x16x32_bf16 v[130:133], v[186:189], v[146:149], v[130:133]
	v_mfma_f32_16x16x32_bf16 v[118:121], v[178:181], v[154:157], v[118:121]
	v_mfma_f32_16x16x32_bf16 v[114:117], v[186:189], v[154:157], v[114:117]
	v_mfma_f32_16x16x32_bf16 v[102:105], v[178:181], v[162:165], v[102:105]
	v_mfma_f32_16x16x32_bf16 v[98:101], v[186:189], v[162:165], v[98:101]
	v_mfma_f32_16x16x32_bf16 v[86:89], v[178:181], v[170:173], v[86:89]
	v_mfma_f32_16x16x32_bf16 v[82:85], v[186:189], v[170:173], v[82:85]
	v_mfma_f32_16x16x32_bf16 v[134:137], v[182:185], v[150:153], v[134:137]
	v_mfma_f32_16x16x32_bf16 v[130:133], v[190:193], v[150:153], v[130:133]
	v_mfma_f32_16x16x32_bf16 v[118:121], v[182:185], v[158:161], v[118:121]
	v_mfma_f32_16x16x32_bf16 v[114:117], v[190:193], v[158:161], v[114:117]
	v_mfma_f32_16x16x32_bf16 v[102:105], v[182:185], v[166:169], v[102:105]
	v_mfma_f32_16x16x32_bf16 v[98:101], v[190:193], v[166:169], v[98:101]
	v_mfma_f32_16x16x32_bf16 v[86:89], v[182:185], v[174:177], v[86:89]
	v_mfma_f32_16x16x32_bf16 v[82:85], v[190:193], v[174:177], v[82:85]
	s_setprio 0
	s_mov_b32 m0, s70
	s_add_u32 s100, s62, s22
	s_addc_u32 s101, s63, s23
	s_barrier
	ds_read_b128 v[146:149], v243 offset:16384
	ds_read_b128 v[150:153], v243 offset:17408
	ds_read_b128 v[154:157], v243 offset:18432
	ds_read_b128 v[158:161], v243 offset:19456
	ds_read_b128 v[162:165], v243 offset:20480
	ds_read_b128 v[166:169], v243 offset:21504
	ds_read_b128 v[170:173], v243 offset:22528
	ds_read_b128 v[174:177], v243 offset:23552
	global_load_lds_dwordx4 v212, s[62:63]
	s_mov_b32 m0, s71
	s_nop 0
	global_load_lds_dwordx4 v210, s[62:63]
	s_waitcnt vmcnt(10)
	s_barrier
	s_waitcnt lgkmcnt(0)
	s_setprio 1
	v_mfma_f32_16x16x32_bf16 v[78:81], v[58:61], v[146:149], v[78:81]
	v_mfma_f32_16x16x32_bf16 v[74:77], v[66:69], v[146:149], v[74:77]
	v_mfma_f32_16x16x32_bf16 v[46:49], v[58:61], v[154:157], v[46:49]
	v_mfma_f32_16x16x32_bf16 v[42:45], v[66:69], v[154:157], v[42:45]
	v_mfma_f32_16x16x32_bf16 v[30:33], v[58:61], v[162:165], v[30:33]
	v_mfma_f32_16x16x32_bf16 v[26:29], v[66:69], v[162:165], v[26:29]
	v_mfma_f32_16x16x32_bf16 v[14:17], v[58:61], v[170:173], v[14:17]
	v_mfma_f32_16x16x32_bf16 v[10:13], v[66:69], v[170:173], v[10:13]
	v_mfma_f32_16x16x32_bf16 v[78:81], v[62:65], v[150:153], v[78:81]
	v_mfma_f32_16x16x32_bf16 v[74:77], v[70:73], v[150:153], v[74:77]
	v_mfma_f32_16x16x32_bf16 v[46:49], v[62:65], v[158:161], v[46:49]
	v_mfma_f32_16x16x32_bf16 v[42:45], v[70:73], v[158:161], v[42:45]
	v_mfma_f32_16x16x32_bf16 v[30:33], v[62:65], v[166:169], v[30:33]
	v_mfma_f32_16x16x32_bf16 v[26:29], v[70:73], v[166:169], v[26:29]
	v_mfma_f32_16x16x32_bf16 v[14:17], v[62:65], v[174:177], v[14:17]
	v_mfma_f32_16x16x32_bf16 v[10:13], v[70:73], v[174:177], v[10:13]
	s_setprio 0
	s_barrier
	ds_read_b128 v[58:61], v194 offset:32768
	ds_read_b128 v[62:65], v194 offset:33792
	ds_read_b128 v[66:69], v194 offset:34816
	ds_read_b128 v[70:73], v194 offset:35840
	s_add_u32 s64, s64, s50
	s_addc_u32 s65, s65, 0
	s_add_i32 s85, s86, s69
	s_mov_b32 m0, s85
	s_add_u32 vcc_lo, s64, s22
	s_addc_u32 vcc_hi, s65, s23
	global_load_lds_dwordx4 v0, s[64:65]
	s_add_i32 m0, s85, 0x2000
	s_nop 0
	global_load_lds_dwordx4 v208, s[64:65]
	s_waitcnt vmcnt(6)
	s_barrier
	s_setprio 1
	v_mfma_f32_16x16x32_bf16 v[54:57], v[178:181], v[146:149], v[54:57]
	v_mfma_f32_16x16x32_bf16 v[50:53], v[186:189], v[146:149], v[50:53]
	v_mfma_f32_16x16x32_bf16 v[38:41], v[178:181], v[154:157], v[38:41]
	v_mfma_f32_16x16x32_bf16 v[34:37], v[186:189], v[154:157], v[34:37]
	v_mfma_f32_16x16x32_bf16 v[22:25], v[178:181], v[162:165], v[22:25]
	v_mfma_f32_16x16x32_bf16 v[18:21], v[186:189], v[162:165], v[18:21]
	v_mfma_f32_16x16x32_bf16 v[6:9], v[178:181], v[170:173], v[6:9]
	v_mfma_f32_16x16x32_bf16 v[2:5], v[186:189], v[170:173], v[2:5]
	v_mfma_f32_16x16x32_bf16 v[54:57], v[182:185], v[150:153], v[54:57]
	v_mfma_f32_16x16x32_bf16 v[50:53], v[190:193], v[150:153], v[50:53]
	v_mfma_f32_16x16x32_bf16 v[38:41], v[182:185], v[158:161], v[38:41]
	v_mfma_f32_16x16x32_bf16 v[34:37], v[190:193], v[158:161], v[34:37]
	v_mfma_f32_16x16x32_bf16 v[22:25], v[182:185], v[166:169], v[22:25]
	v_mfma_f32_16x16x32_bf16 v[18:21], v[190:193], v[166:169], v[18:21]
	v_mfma_f32_16x16x32_bf16 v[6:9], v[182:185], v[174:177], v[6:9]
	v_mfma_f32_16x16x32_bf16 v[2:5], v[190:193], v[174:177], v[2:5]
	s_setprio 0
	s_add_i32 s64, 0, 0x18000
	s_barrier
	s_add_u32 s62, s62, s50
	s_addc_u32 s63, s63, 0
	s_mov_b32 m0, s72
	ds_read_b128 v[146:149], v243 offset:32768
	ds_read_b128 v[150:153], v243 offset:33792
	ds_read_b128 v[154:157], v243 offset:34816
	ds_read_b128 v[158:161], v243 offset:35840
	ds_read_b128 v[162:165], v243 offset:36864
	ds_read_b128 v[166:169], v243 offset:37888
	ds_read_b128 v[170:173], v243 offset:38912
	ds_read_b128 v[174:177], v243 offset:39936
	global_load_lds_dwordx4 v212, s[62:63]
	s_mov_b32 m0, s73
	s_nop 0
	global_load_lds_dwordx4 v210, s[62:63]
	s_waitcnt lgkmcnt(8)
	s_barrier
; #define PG8_STAGE(bufoff, gbase, voff) do { _Pragma("unroll") for (int _i = 0; _i < 2; ++_i) \
;         __builtin_amdgcn_global_load_lds((const unsigned*)((const char*)(gbase) + (voff)[_i]), (LAS unsigned*)(lds + (bufoff) + ldsw + _i * 8192), 16, 0, 0); } while (0)
; #define PG8_LDA(dst, b, h) do { _Pragma("unroll") for (int m = 0; m < 4; ++m) _Pragma("unroll") for (int k = 0; k < 2; ++k) dst[m][k] = *(const LAS bf16x8*)(lds + PG8_SA(b, h) + aoff + m * 2048 + k * 1024); } while (0)
; #define PG8_LDB(dst, b, h) do { _Pragma("unroll") for (int n = 0; n < 2; ++n) _Pragma("unroll") for (int k = 0; k < 2; ++k) dst[n][k] = *(const LAS bf16x8*)(lds + PG8_SB(b, h) + boff + n * 2048 + k * 1024); } while (0)
; #define PG8_MMA(ai, bj, At, Bt) do { __builtin_amdgcn_s_setprio(1); _Pragma("unroll") for (int m = 0; m < 4; ++m) _Pragma("unroll") for (int n = 0; n < 2; ++n) _Pragma("unroll") for (int k = 0; k < 2; ++k) \
;         acc[ai][bj][m][n] = __builtin_amdgcn_mfma_f32_16x16x32_bf16(Bt[n][k], At[m][k], acc[ai][bj][m][n], 0, 0, 0); __builtin_amdgcn_s_setprio(0); } while (0)
; #define PG8_WAIT_V(n) asm volatile("s_waitcnt vmcnt(" #n ")" ::: "memory")
; #define PG8_WAIT_L(n) asm volatile("s_waitcnt lgkmcnt(" #n ")" ::: "memory")
; #define PG8_BAR __builtin_amdgcn_s_barrier()
; #define PG8_SCHED __builtin_amdgcn_sched_barrier(0)
; template <class Epi>
; __device__ __forceinline__ void gemm_phase(LAS unsigned char* lds, const Gemm g, const StaticOrder& S, const Epi& E) {
;     ...
;             PG8_WAIT_L(8); PG8_BAR; PG8_WAIT_L(0); PG8_MMA(0, 0, At, B0); PG8_BAR; PG8_SCHED;
;             PG8_LDB(B1, 1, 1); PG8_STAGE(PG8_SB(1, 0), b3, voffB);
;             PG8_BAR; PG8_WAIT_L(0); PG8_MMA(0, 1, At, B1); PG8_BAR;
;             PG8_LDA(At, 1, 1); PG8_STAGE(PG8_SA(1, 0), a3, voffA);
;             PG8_BAR; PG8_WAIT_L(0); PG8_MMA(1, 0, At, B0); PG8_BAR; PG8_SCHED;
;             PG8_STAGE(PG8_SB(1, 1), b3 + hstep, voffB);
;             PG8_WAIT_V(6); PG8_BAR; PG8_MMA(1, 1, At, B1); PG8_BAR;
	s_waitcnt lgkmcnt(0)
	s_setprio 1
	v_mfma_f32_16x16x32_bf16 v[142:145], v[58:61], v[146:149], v[142:145]
	v_mfma_f32_16x16x32_bf16 v[138:141], v[66:69], v[146:149], v[138:141]
	v_mfma_f32_16x16x32_bf16 v[126:129], v[58:61], v[154:157], v[126:129]
	v_mfma_f32_16x16x32_bf16 v[122:125], v[66:69], v[154:157], v[122:125]
	v_mfma_f32_16x16x32_bf16 v[110:113], v[58:61], v[162:165], v[110:113]
	v_mfma_f32_16x16x32_bf16 v[106:109], v[66:69], v[162:165], v[106:109]
	v_mfma_f32_16x16x32_bf16 v[94:97], v[58:61], v[170:173], v[94:97]
	v_mfma_f32_16x16x32_bf16 v[90:93], v[66:69], v[170:173], v[90:93]
	v_mfma_f32_16x16x32_bf16 v[142:145], v[62:65], v[150:153], v[142:145]
	v_mfma_f32_16x16x32_bf16 v[138:141], v[70:73], v[150:153], v[138:141]
	v_mfma_f32_16x16x32_bf16 v[126:129], v[62:65], v[158:161], v[126:129]
	v_mfma_f32_16x16x32_bf16 v[122:125], v[70:73], v[158:161], v[122:125]
	v_mfma_f32_16x16x32_bf16 v[110:113], v[62:65], v[166:169], v[110:113]
	v_mfma_f32_16x16x32_bf16 v[106:109], v[70:73], v[166:169], v[106:109]
	v_mfma_f32_16x16x32_bf16 v[94:97], v[62:65], v[174:177], v[94:97]
	v_mfma_f32_16x16x32_bf16 v[90:93], v[70:73], v[174:177], v[90:93]
	s_setprio 0
	s_barrier
	s_add_i32 s62, 0, 0x1c000
	s_add_i32 s63, s64, s69
	s_mov_b32 m0, s63
	ds_read_b128 v[178:181], v194 offset:49152
	ds_read_b128 v[182:185], v194 offset:50176
	ds_read_b128 v[186:189], v194 offset:51200
	ds_read_b128 v[190:193], v194 offset:52224
	global_load_lds_dwordx4 v0, s[98:99]
	s_add_i32 m0, s63, 0x2000
	s_nop 0
	global_load_lds_dwordx4 v208, s[98:99]
	s_barrier
	s_waitcnt lgkmcnt(0)
	s_setprio 1
	v_mfma_f32_16x16x32_bf16 v[134:137], v[178:181], v[146:149], v[134:137]
	v_mfma_f32_16x16x32_bf16 v[130:133], v[186:189], v[146:149], v[130:133]
	v_mfma_f32_16x16x32_bf16 v[118:121], v[178:181], v[154:157], v[118:121]
	v_mfma_f32_16x16x32_bf16 v[114:117], v[186:189], v[154:157], v[114:117]
	v_mfma_f32_16x16x32_bf16 v[102:105], v[178:181], v[162:165], v[102:105]
	v_mfma_f32_16x16x32_bf16 v[98:101], v[186:189], v[162:165], v[98:101]
	v_mfma_f32_16x16x32_bf16 v[86:89], v[178:181], v[170:173], v[86:89]
	v_mfma_f32_16x16x32_bf16 v[82:85], v[186:189], v[170:173], v[82:85]
	v_mfma_f32_16x16x32_bf16 v[134:137], v[182:185], v[150:153], v[134:137]
	v_mfma_f32_16x16x32_bf16 v[130:133], v[190:193], v[150:153], v[130:133]
	v_mfma_f32_16x16x32_bf16 v[118:121], v[182:185], v[158:161], v[118:121]
	v_mfma_f32_16x16x32_bf16 v[114:117], v[190:193], v[158:161], v[114:117]
	v_mfma_f32_16x16x32_bf16 v[102:105], v[182:185], v[166:169], v[102:105]
	v_mfma_f32_16x16x32_bf16 v[98:101], v[190:193], v[166:169], v[98:101]
	v_mfma_f32_16x16x32_bf16 v[86:89], v[182:185], v[174:177], v[86:89]
	v_mfma_f32_16x16x32_bf16 v[82:85], v[190:193], v[174:177], v[82:85]
	s_setprio 0
	s_mov_b32 m0, s75
	s_barrier
	ds_read_b128 v[146:149], v243 offset:49152
	ds_read_b128 v[150:153], v243 offset:50176
	ds_read_b128 v[154:157], v243 offset:51200
	ds_read_b128 v[158:161], v243 offset:52224
	ds_read_b128 v[162:165], v243 offset:53248
	ds_read_b128 v[166:169], v243 offset:54272
	ds_read_b128 v[170:173], v243 offset:55296
	ds_read_b128 v[174:177], v243 offset:56320
	global_load_lds_dwordx4 v212, s[100:101]
	s_mov_b32 m0, s76
	s_nop 0
	global_load_lds_dwordx4 v210, s[100:101]
	s_waitcnt vmcnt(10)
	s_barrier
	s_waitcnt lgkmcnt(0)
	s_setprio 1
	v_mfma_f32_16x16x32_bf16 v[78:81], v[58:61], v[146:149], v[78:81]
	v_mfma_f32_16x16x32_bf16 v[74:77], v[66:69], v[146:149], v[74:77]
	v_mfma_f32_16x16x32_bf16 v[46:49], v[58:61], v[154:157], v[46:49]
	v_mfma_f32_16x16x32_bf16 v[42:45], v[66:69], v[154:157], v[42:45]
	v_mfma_f32_16x16x32_bf16 v[30:33], v[58:61], v[162:165], v[30:33]
	v_mfma_f32_16x16x32_bf16 v[26:29], v[66:69], v[162:165], v[26:29]
	v_mfma_f32_16x16x32_bf16 v[14:17], v[58:61], v[170:173], v[14:17]
	v_mfma_f32_16x16x32_bf16 v[10:13], v[66:69], v[170:173], v[10:13]
	v_mfma_f32_16x16x32_bf16 v[78:81], v[62:65], v[150:153], v[78:81]
	v_mfma_f32_16x16x32_bf16 v[74:77], v[70:73], v[150:153], v[74:77]
	v_mfma_f32_16x16x32_bf16 v[46:49], v[62:65], v[158:161], v[46:49]
	v_mfma_f32_16x16x32_bf16 v[42:45], v[70:73], v[158:161], v[42:45]
	v_mfma_f32_16x16x32_bf16 v[30:33], v[62:65], v[166:169], v[30:33]
	v_mfma_f32_16x16x32_bf16 v[26:29], v[70:73], v[166:169], v[26:29]
	v_mfma_f32_16x16x32_bf16 v[14:17], v[62:65], v[174:177], v[14:17]
	v_mfma_f32_16x16x32_bf16 v[10:13], v[70:73], v[174:177], v[10:13]
	s_setprio 0
	s_barrier
	ds_read_b128 v[58:61], v194
	ds_read_b128 v[62:65], v194 offset:1024
	ds_read_b128 v[66:69], v194 offset:2048
	ds_read_b128 v[70:73], v194 offset:3072
	s_add_i32 s62, s62, s69
	s_mov_b32 m0, s62
	s_nop 0
	global_load_lds_dwordx4 v0, vcc
	s_add_i32 m0, s62, 0x2000
	s_nop 0
	global_load_lds_dwordx4 v208, vcc
	s_waitcnt vmcnt(6)
	s_barrier
	s_setprio 1
	v_mfma_f32_16x16x32_bf16 v[54:57], v[178:181], v[146:149], v[54:57]
	v_mfma_f32_16x16x32_bf16 v[50:53], v[186:189], v[146:149], v[50:53]
	v_mfma_f32_16x16x32_bf16 v[38:41], v[178:181], v[154:157], v[38:41]
	v_mfma_f32_16x16x32_bf16 v[34:37], v[186:189], v[154:157], v[34:37]
	v_mfma_f32_16x16x32_bf16 v[22:25], v[178:181], v[162:165], v[22:25]
	v_mfma_f32_16x16x32_bf16 v[18:21], v[186:189], v[162:165], v[18:21]
	v_mfma_f32_16x16x32_bf16 v[6:9], v[178:181], v[170:173], v[6:9]
	v_mfma_f32_16x16x32_bf16 v[2:5], v[186:189], v[170:173], v[2:5]
	v_mfma_f32_16x16x32_bf16 v[54:57], v[182:185], v[150:153], v[54:57]
	v_mfma_f32_16x16x32_bf16 v[50:53], v[190:193], v[150:153], v[50:53]
	v_mfma_f32_16x16x32_bf16 v[38:41], v[182:185], v[158:161], v[38:41]
	v_mfma_f32_16x16x32_bf16 v[34:37], v[190:193], v[158:161], v[34:37]
	v_mfma_f32_16x16x32_bf16 v[22:25], v[182:185], v[166:169], v[22:25]
	v_mfma_f32_16x16x32_bf16 v[18:21], v[190:193], v[166:169], v[18:21]
	v_mfma_f32_16x16x32_bf16 v[6:9], v[182:185], v[174:177], v[6:9]
	v_mfma_f32_16x16x32_bf16 v[2:5], v[190:193], v[174:177], v[2:5]
	s_setprio 0
	s_add_u32 s60, s60, 0x100
	s_addc_u32 s61, s61, 0
	s_add_u32 s82, s82, 0x100
	s_addc_u32 s83, s83, 0
	s_cmp_ge_u32 s84, s74
	s_mov_b32 s62, s84
	s_barrier
; __device__ __forceinline__ unsigned pk2(float lo, float hi) { f32x2 v = {lo, hi}; bf16x2_t b = __builtin_convertvector(v, bf16x2_t); return __builtin_bit_cast(unsigned, b); }
;     __device__ __forceinline__ void operator()(const AccT& acc, const Unit& u, int wr, int wc, int fr, int fq) const {
;         const int row0 = u.pm * BM + wr * 64 + fr, col0 = u.pn * BM + wc * 32 + 8 * fq;
;         f32x4 gv[2][2];
; #pragma unroll
;         for (int bj = 0; bj < 2; ++bj)
; #pragma unroll
;             for (int n = 0; n < 2; ++n) gv[bj][n] = *(const f32x4*)(g + col0 + bj * HALF + 4 * n);
; #pragma unroll
;         for (int ai = 0; ai < 2; ++ai) {
;             f32x4 xv[4][2][2];
; #pragma unroll
;             for (int m = 0; m < 4; ++m)
; #pragma unroll
;                 for (int bj = 0; bj < 2; ++bj) {
;                     const size_t p = (size_t)(row0 + ai * HALF + m * 16) * DM + col0 + bj * HALF;
;                     xv[m][bj][0] = __builtin_nontemporal_load((const f32x4*)(xin + p)); xv[m][bj][1] = __builtin_nontemporal_load((const f32x4*)(xin + p + 4));
;                 }
; #pragma unroll
;             for (int m = 0; m < 4; ++m) {
;                 const int row = row0 + ai * HALF + m * 16;
;                 float ssa = 0.f;
; #pragma unroll
;                 for (int bj = 0; bj < 2; ++bj) {
;                     const size_t p = (size_t)row * DM + col0 + bj * HALF;
;                     const f32x4 x0 = xv[m][bj][0] + acc[ai][bj][m][0] * alpha, x1 = xv[m][bj][1] + acc[ai][bj][m][1] * alpha;
;                     __builtin_nontemporal_store(x0, (f32x4*)(xout + p)); __builtin_nontemporal_store(x1, (f32x4*)(xout + p + 4));
;                     ssa += (x0[0] * x0[0] + x0[1] * x0[1]) + (x0[2] * x0[2] + x0[3] * x0[3]) + (x1[0] * x1[0] + x1[1] * x1[1]) + (x1[2] * x1[2] + x1[3] * x1[3]);
;                     const f32x4 h0 = x0 * gv[bj][0], h1 = x1 * gv[bj][1];
;                     u32x4 w; w.x = pk2(h0[0], h0[1]); w.y = pk2(h0[2], h0[3]); w.z = pk2(h1[0], h1[1]); w.w = pk2(h1[2], h1[3]);
;                     *(u32x4*)(h + p) = w;
;                 }
;                 ssa += __shfl_xor(ssa, 16); ssa += __shfl_xor(ssa, 32);
;                 if (fq == 0) unsafeAtomicAdd(ssout + row, ssa);
	s_cbranch_scc0 .LBB0_654
	s_waitcnt lgkmcnt(0)
	v_lshl_or_b32 v218, s81, 8, v242
	v_ashrrev_i32_e32 v219, 31, v218
	v_lshl_add_u32 v220, s80, 8, v240
	v_lshlrev_b64 v[146:147], 2, v[218:219]
	v_ashrrev_i32_e32 v221, 31, v220
	v_lshl_add_u64 v[62:63], s[44:45], 0, v[146:147]
	v_lshl_add_u64 v[222:223], s[54:55], 0, v[146:147]
	v_lshlrev_b64 v[146:147], 13, v[220:221]
	v_lshl_add_u64 v[146:147], v[222:223], 0, v[146:147]
	global_load_dwordx4 v[66:69], v[62:63], off offset:16
	global_load_dwordx4 v[70:73], v[62:63], off
	global_load_dwordx4 v[58:61], v[62:63], off offset:528
	s_nop 0
	global_load_dwordx4 v[62:65], v[62:63], off offset:512
	s_nop 0
	global_load_dwordx4 v[246:249], v[146:147], off offset:16 nt
	global_load_dwordx4 v[202:205], v[146:147], off nt
	global_load_dwordx4 v[194:197], v[146:147], off offset:528 nt
	global_load_dwordx4 v[198:201], v[146:147], off offset:512 nt
	v_or_b32_e32 v228, 16, v220
	v_and_b32_e32 v149, 64, v234
	v_ashrrev_i32_e32 v229, 31, v228
	v_xor_b32_e32 v148, 16, v234
	v_add_u32_e32 v149, 64, v149
	v_lshlrev_b64 v[146:147], 13, v[228:229]
	v_or_b32_e32 v226, 32, v220
	v_cmp_lt_i32_e32 vcc, v148, v149
	v_lshl_add_u64 v[146:147], v[222:223], 0, v[146:147]
	v_ashrrev_i32_e32 v227, 31, v226
	v_cndmask_b32_e32 v148, v234, v148, vcc
	global_load_dwordx4 v[186:189], v[146:147], off offset:16 nt
	global_load_dwordx4 v[190:193], v[146:147], off nt
	global_load_dwordx4 v[178:181], v[146:147], off offset:528 nt
	global_load_dwordx4 v[182:185], v[146:147], off offset:512 nt
	v_lshlrev_b64 v[146:147], 13, v[226:227]
	v_or_b32_e32 v224, 48, v220
	v_lshlrev_b32_e32 v245, 2, v148
	v_xor_b32_e32 v148, 32, v234
	v_lshl_add_u64 v[146:147], v[222:223], 0, v[146:147]
	v_ashrrev_i32_e32 v225, 31, v224
	v_cmp_lt_i32_e32 vcc, v148, v149
	global_load_dwordx4 v[170:173], v[146:147], off offset:16 nt
	global_load_dwordx4 v[174:177], v[146:147], off nt
	global_load_dwordx4 v[154:157], v[146:147], off offset:528 nt
	global_load_dwordx4 v[158:161], v[146:147], off offset:512 nt
	v_lshlrev_b64 v[146:147], 13, v[224:225]
	v_cndmask_b32_e32 v148, v234, v148, vcc
	v_lshl_add_u64 v[150:151], v[222:223], 0, v[146:147]
	v_lshlrev_b32_e32 v244, 2, v148
	global_load_dwordx4 v[162:165], v[150:151], off offset:16 nt
	global_load_dwordx4 v[166:169], v[150:151], off nt
	global_load_dwordx4 v[146:149], v[150:151], off offset:528 nt
	s_nop 0
	global_load_dwordx4 v[150:153], v[150:151], off offset:512 nt
	v_lshlrev_b64 v[230:231], 11, v[220:221]
	v_readlane_b32 s60, v251, 56
	v_lshl_add_u64 v[230:231], v[230:231], 0, v[218:219]
	v_readlane_b32 s61, v251, 57
	v_readlane_b32 s62, v254, 8
	v_readlane_b32 s63, v254, 9
	s_waitcnt vmcnt(0)
	v_pk_fma_f32 v[140:141], s[58:59], v[140:141], v[248:249]
	v_pk_fma_f32 v[144:145], s[58:59], v[144:145], v[204:205]
	v_pk_fma_f32 v[142:143], s[46:47], v[142:143], v[202:203]
	v_lshl_add_u64 v[202:203], v[230:231], 2, s[60:61]
	v_pk_fma_f32 v[138:139], s[46:47], v[138:139], v[246:247]
	global_store_dwordx4 v[202:203], v[142:145], off nt
	global_store_dwordx4 v[202:203], v[138:141], off offset:16 nt
	v_mul_f32_e32 v202, v143, v143
	v_mul_f32_e32 v203, v145, v145
	v_fmac_f32_e32 v202, v142, v142
	v_fmac_f32_e32 v203, v144, v144
	v_add_f32_e32 v202, v202, v203
	v_mul_f32_e32 v203, v139, v139
	v_fmac_f32_e32 v203, v138, v138
	v_add_f32_e32 v202, v203, v202
	v_mul_f32_e32 v203, v141, v141
	v_fmac_f32_e32 v203, v140, v140
	v_add_f32_e32 v204, v203, v202
	v_pk_mul_f32 v[144:145], v[72:73], v[144:145]
	v_pk_mul_f32 v[142:143], v[70:71], v[142:143]
	v_pk_mul_f32 v[202:203], v[68:69], v[140:141]
	v_pk_mul_f32 v[140:141], v[66:67], v[138:139]
	v_cvt_pk_bf16_f32 v138, v142, v143
	v_cvt_pk_bf16_f32 v139, v144, v145
	v_cvt_pk_bf16_f32 v140, v140, v141
	v_cvt_pk_bf16_f32 v141, v202, v203
	v_lshl_add_u64 v[142:143], v[230:231], 1, s[62:63]
	v_or_b32_e32 v230, 0x80, v230
	global_store_dwordx4 v[142:143], v[138:141], off
	v_pk_fma_f32 v[136:137], s[58:59], v[136:137], v[200:201]
	v_pk_fma_f32 v[134:135], s[46:47], v[134:135], v[198:199]
	v_lshl_add_u64 v[138:139], v[230:231], 2, s[60:61]
	v_pk_fma_f32 v[132:133], s[58:59], v[132:133], v[196:197]
	v_pk_fma_f32 v[130:131], s[46:47], v[130:131], v[194:195]
	global_store_dwordx4 v[138:139], v[134:137], off nt
	global_store_dwordx4 v[138:139], v[130:133], off offset:16 nt
	v_mul_f32_e32 v138, v135, v135
	v_mul_f32_e32 v139, v137, v137
	v_fmac_f32_e32 v138, v134, v134
	v_fmac_f32_e32 v139, v136, v136
	v_add_f32_e32 v138, v138, v139
	v_mul_f32_e32 v139, v131, v131
	v_fmac_f32_e32 v139, v130, v130
	v_add_f32_e32 v138, v139, v138
	v_mul_f32_e32 v139, v133, v133
	v_fmac_f32_e32 v139, v132, v132
	v_add_f32_e32 v138, v139, v138
	v_add_f32_e32 v140, v204, v138
	v_pk_mul_f32 v[136:137], v[64:65], v[136:137]
	v_pk_mul_f32 v[134:135], v[62:63], v[134:135]
	v_pk_mul_f32 v[138:139], v[60:61], v[132:133]
	v_pk_mul_f32 v[132:133], v[58:59], v[130:131]
	v_cvt_pk_bf16_f32 v130, v134, v135
	v_cvt_pk_bf16_f32 v131, v136, v137
	v_cvt_pk_bf16_f32 v132, v132, v133
	v_cvt_pk_bf16_f32 v133, v138, v139
	v_lshl_add_u64 v[134:135], v[230:231], 1, s[62:63]
	global_store_dwordx4 v[134:135], v[130:133], off
	ds_bpermute_b32 v130, v245, v140
	v_lshl_add_u64 v[138:139], v[220:221], 2, s[56:57]
	s_waitcnt lgkmcnt(0)
	v_add_f32_e32 v130, v140, v130
	ds_bpermute_b32 v131, v244, v130
	s_and_saveexec_b64 s[60:61], s[36:37]
	s_cbranch_execz .LBB0_657
	s_waitcnt lgkmcnt(0)
	v_add_f32_e32 v130, v130, v131
	global_atomic_add_f32 v[138:139], v130, off
